# k23 + K-loop ds_read ring-slot bases folded into the ds_read offset field (3 fewer VALU adds per iteration)
# speedup vs baseline: 1.0075x; 1.0012x over previous
.LBB0_444:
	s_add_u32 s48, s46, 0x20080
	s_addc_u32 s49, s47, 0
	s_add_u32 s25, s50, 0x100
	s_addc_u32 s64, s51, 0
	s_mov_b32 s65, -2
	s_add_u32 s46, s48, 0xfffe0080
	s_addc_u32 s47, s49, -1
	s_add_i32 s84, 0, 0x10000
	s_cmp_eq_u32 s65, 4
	s_cselect_b32 s47, s15, s47
	s_cselect_b32 s46, s14, s46
	v_add_u32_e32 v0, s84, v147
	s_cselect_b32 s51, s17, s64
	s_cselect_b32 s50, s16, s25
	s_add_i32 s86, 0, 0x14000
	ds_read_b128 v[150:153], v0
	ds_read_b128 v[154:157], v0 offset:1024
	ds_read_b128 v[158:161], v0 offset:2048
	ds_read_b128 v[162:165], v0 offset:3072
	ds_read_b128 v[166:169], v0 offset:16384
	ds_read_b128 v[170:173], v0 offset:17408
	ds_read_b128 v[174:177], v0 offset:18432
	ds_read_b128 v[178:181], v0 offset:19456
	ds_read_b128 v[182:185], v148
	ds_read_b128 v[186:189], v148 offset:1024
	ds_read_b128 v[190:193], v148 offset:2048
	ds_read_b128 v[194:197], v148 offset:3072
	ds_read_b128 v[198:201], v148 offset:4096
	ds_read_b128 v[202:205], v148 offset:5120
	ds_read_b128 v[206:209], v148 offset:6144
	ds_read_b128 v[210:213], v148 offset:7168
	s_add_i32 m0, s59, 0xc000
	s_nop 0
	global_load_lds_dwordx4 v132, s[48:49]
	s_add_i32 m0, s59, 0xe000
	s_nop 0
	global_load_lds_dwordx4 v133, s[48:49]
	s_waitcnt vmcnt(8)
	s_waitcnt lgkmcnt(0)
	s_barrier
	s_setprio 1
	s_waitcnt lgkmcnt(0)
	v_mfma_i32_16x16x64_i8 v[126:129], v[150:153], v[182:185], 0
	v_mfma_i32_16x16x64_i8 v[122:125], v[158:161], v[182:185], 0
	v_mfma_i32_16x16x64_i8 v[110:113], v[150:153], v[190:193], 0
	v_mfma_i32_16x16x64_i8 v[106:109], v[158:161], v[190:193], 0
	v_mfma_i32_16x16x64_i8 v[94:97], v[150:153], v[198:201], 0
	v_mfma_i32_16x16x64_i8 v[90:93], v[158:161], v[198:201], 0
	v_mfma_i32_16x16x64_i8 v[78:81], v[150:153], v[206:209], 0
	v_mfma_i32_16x16x64_i8 v[74:77], v[158:161], v[206:209], 0
	v_mfma_i32_16x16x64_i8 v[126:129], v[154:157], v[186:189], v[126:129]
	v_mfma_i32_16x16x64_i8 v[122:125], v[162:165], v[186:189], v[122:125]
	v_mfma_i32_16x16x64_i8 v[110:113], v[154:157], v[194:197], v[110:113]
	v_mfma_i32_16x16x64_i8 v[106:109], v[162:165], v[194:197], v[106:109]
	v_mfma_i32_16x16x64_i8 v[94:97], v[154:157], v[202:205], v[94:97]
	v_mfma_i32_16x16x64_i8 v[90:93], v[162:165], v[202:205], v[90:93]
	v_mfma_i32_16x16x64_i8 v[78:81], v[154:157], v[210:213], v[78:81]
	v_mfma_i32_16x16x64_i8 v[74:77], v[162:165], v[210:213], v[74:77]
	s_setprio 0
	s_setprio 1
	v_mfma_i32_16x16x64_i8 v[118:121], v[166:169], v[182:185], 0
	v_mfma_i32_16x16x64_i8 v[114:117], v[174:177], v[182:185], 0
	v_mfma_i32_16x16x64_i8 v[102:105], v[166:169], v[190:193], 0
	v_mfma_i32_16x16x64_i8 v[98:101], v[174:177], v[190:193], 0
	v_mfma_i32_16x16x64_i8 v[86:89], v[166:169], v[198:201], 0
	v_mfma_i32_16x16x64_i8 v[82:85], v[174:177], v[198:201], 0
	v_mfma_i32_16x16x64_i8 v[70:73], v[166:169], v[206:209], 0
	v_mfma_i32_16x16x64_i8 v[66:69], v[174:177], v[206:209], 0
	v_mfma_i32_16x16x64_i8 v[118:121], v[170:173], v[186:189], v[118:121]
	v_mfma_i32_16x16x64_i8 v[114:117], v[178:181], v[186:189], v[114:117]
	v_mfma_i32_16x16x64_i8 v[102:105], v[170:173], v[194:197], v[102:105]
	v_mfma_i32_16x16x64_i8 v[98:101], v[178:181], v[194:197], v[98:101]
	v_mfma_i32_16x16x64_i8 v[86:89], v[170:173], v[202:205], v[86:89]
	v_mfma_i32_16x16x64_i8 v[82:85], v[178:181], v[202:205], v[82:85]
	v_mfma_i32_16x16x64_i8 v[70:73], v[170:173], v[210:213], v[70:73]
	v_mfma_i32_16x16x64_i8 v[66:69], v[178:181], v[210:213], v[66:69]
	s_setprio 0
	s_barrier
	s_add_i32 s84, s84, s40
	ds_read_b128 v[182:185], v148 offset:16384
	ds_read_b128 v[186:189], v148 offset:17408
	ds_read_b128 v[190:193], v148 offset:18432
	ds_read_b128 v[194:197], v148 offset:19456
	ds_read_b128 v[198:201], v148 offset:20480
	ds_read_b128 v[202:205], v148 offset:21504
	ds_read_b128 v[206:209], v148 offset:22528
	ds_read_b128 v[210:213], v148 offset:23552
	s_mov_b32 m0, s84
	s_nop 0
	global_load_lds_dwordx4 v143, s[50:51]
	s_add_i32 m0, s84, 0x2000
	s_add_u32 s84, s50, 0x20000
	global_load_lds_dwordx4 v144, s[50:51]
	s_addc_u32 s85, s51, 0
	s_add_i32 s86, s86, s40
	s_mov_b32 m0, s86
	s_nop 0
	global_load_lds_dwordx4 v143, s[84:85]
	s_add_i32 m0, s86, 0x2000
	s_nop 0
	global_load_lds_dwordx4 v144, s[84:85]
	s_mov_b32 m0, s59
	s_nop 0
	global_load_lds_dwordx4 v132, s[46:47]
	s_mov_b32 m0, s60
	s_nop 0
	global_load_lds_dwordx4 v133, s[46:47]
	s_waitcnt vmcnt(8)
	s_waitcnt lgkmcnt(0)
	s_barrier
	s_setprio 1
	s_waitcnt lgkmcnt(0)
	v_mfma_i32_16x16x64_i8 v[62:65], v[150:153], v[182:185], 0
	v_mfma_i32_16x16x64_i8 v[58:61], v[158:161], v[182:185], 0
	v_mfma_i32_16x16x64_i8 v[46:49], v[150:153], v[190:193], 0
	v_mfma_i32_16x16x64_i8 v[42:45], v[158:161], v[190:193], 0
	v_mfma_i32_16x16x64_i8 v[30:33], v[150:153], v[198:201], 0
	v_mfma_i32_16x16x64_i8 v[26:29], v[158:161], v[198:201], 0
	v_mfma_i32_16x16x64_i8 v[14:17], v[150:153], v[206:209], 0
	v_mfma_i32_16x16x64_i8 v[10:13], v[158:161], v[206:209], 0
	v_mfma_i32_16x16x64_i8 v[62:65], v[154:157], v[186:189], v[62:65]
	v_mfma_i32_16x16x64_i8 v[58:61], v[162:165], v[186:189], v[58:61]
	v_mfma_i32_16x16x64_i8 v[46:49], v[154:157], v[194:197], v[46:49]
	v_mfma_i32_16x16x64_i8 v[42:45], v[162:165], v[194:197], v[42:45]
	v_mfma_i32_16x16x64_i8 v[30:33], v[154:157], v[202:205], v[30:33]
	v_mfma_i32_16x16x64_i8 v[26:29], v[162:165], v[202:205], v[26:29]
	v_mfma_i32_16x16x64_i8 v[14:17], v[154:157], v[210:213], v[14:17]
	v_mfma_i32_16x16x64_i8 v[10:13], v[162:165], v[210:213], v[10:13]
	s_setprio 0
	s_setprio 1
	v_mfma_i32_16x16x64_i8 v[54:57], v[166:169], v[182:185], 0
	v_mfma_i32_16x16x64_i8 v[50:53], v[174:177], v[182:185], 0
	v_mfma_i32_16x16x64_i8 v[38:41], v[166:169], v[190:193], 0
	v_mfma_i32_16x16x64_i8 v[34:37], v[174:177], v[190:193], 0
	v_mfma_i32_16x16x64_i8 v[22:25], v[166:169], v[198:201], 0
	v_mfma_i32_16x16x64_i8 v[18:21], v[174:177], v[198:201], 0
	v_mfma_i32_16x16x64_i8 v[6:9], v[166:169], v[206:209], 0
	v_mfma_i32_16x16x64_i8 v[2:5], v[174:177], v[206:209], 0
	v_mfma_i32_16x16x64_i8 v[54:57], v[170:173], v[186:189], v[54:57]
	v_mfma_i32_16x16x64_i8 v[50:53], v[178:181], v[186:189], v[50:53]
	v_mfma_i32_16x16x64_i8 v[38:41], v[170:173], v[194:197], v[38:41]
	v_mfma_i32_16x16x64_i8 v[34:37], v[178:181], v[194:197], v[34:37]
	v_mfma_i32_16x16x64_i8 v[22:25], v[170:173], v[202:205], v[22:25]
	v_mfma_i32_16x16x64_i8 v[18:21], v[178:181], v[202:205], v[18:21]
	v_mfma_i32_16x16x64_i8 v[6:9], v[170:173], v[210:213], v[6:9]
	v_mfma_i32_16x16x64_i8 v[2:5], v[178:181], v[210:213], v[2:5]
	s_setprio 0
	s_barrier
	s_add_i32 s86, 0, 0x18000
	s_add_i32 s87, 0, 0x1c000
	ds_read_b128 v[150:153], v0 offset:32768
	ds_read_b128 v[154:157], v0 offset:33792
	ds_read_b128 v[158:161], v0 offset:34816
	ds_read_b128 v[162:165], v0 offset:35840
	ds_read_b128 v[166:169], v0 offset:49152
	ds_read_b128 v[170:173], v0 offset:50176
	ds_read_b128 v[174:177], v0 offset:51200
	ds_read_b128 v[178:181], v0 offset:52224
	s_add_u32 s84, s46, 0x20000
	s_mov_b32 m0, s61
	ds_read_b128 v[182:185], v148 offset:32768
	ds_read_b128 v[186:189], v148 offset:33792
	ds_read_b128 v[190:193], v148 offset:34816
	ds_read_b128 v[194:197], v148 offset:35840
	ds_read_b128 v[198:201], v148 offset:36864
	ds_read_b128 v[202:205], v148 offset:37888
	ds_read_b128 v[206:209], v148 offset:38912
	ds_read_b128 v[210:213], v148 offset:39936
	s_addc_u32 s85, s47, 0
	s_nop 0
	global_load_lds_dwordx4 v132, s[84:85]
	s_mov_b32 m0, s66
	s_nop 0
	global_load_lds_dwordx4 v133, s[84:85]
	s_waitcnt vmcnt(8)
	s_waitcnt lgkmcnt(0)
	s_barrier
	s_setprio 1
	s_waitcnt lgkmcnt(0)
	v_mfma_i32_16x16x64_i8 v[126:129], v[150:153], v[182:185], v[126:129]
	v_mfma_i32_16x16x64_i8 v[122:125], v[158:161], v[182:185], v[122:125]
	v_mfma_i32_16x16x64_i8 v[110:113], v[150:153], v[190:193], v[110:113]
	v_mfma_i32_16x16x64_i8 v[106:109], v[158:161], v[190:193], v[106:109]
	v_mfma_i32_16x16x64_i8 v[94:97], v[150:153], v[198:201], v[94:97]
	v_mfma_i32_16x16x64_i8 v[90:93], v[158:161], v[198:201], v[90:93]
	v_mfma_i32_16x16x64_i8 v[78:81], v[150:153], v[206:209], v[78:81]
	v_mfma_i32_16x16x64_i8 v[74:77], v[158:161], v[206:209], v[74:77]
	v_mfma_i32_16x16x64_i8 v[126:129], v[154:157], v[186:189], v[126:129]
	v_mfma_i32_16x16x64_i8 v[122:125], v[162:165], v[186:189], v[122:125]
	v_mfma_i32_16x16x64_i8 v[110:113], v[154:157], v[194:197], v[110:113]
	v_mfma_i32_16x16x64_i8 v[106:109], v[162:165], v[194:197], v[106:109]
	v_mfma_i32_16x16x64_i8 v[94:97], v[154:157], v[202:205], v[94:97]
	v_mfma_i32_16x16x64_i8 v[90:93], v[162:165], v[202:205], v[90:93]
	v_mfma_i32_16x16x64_i8 v[78:81], v[154:157], v[210:213], v[78:81]
	v_mfma_i32_16x16x64_i8 v[74:77], v[162:165], v[210:213], v[74:77]
	s_setprio 0
	s_setprio 1
	v_mfma_i32_16x16x64_i8 v[118:121], v[166:169], v[182:185], v[118:121]
	v_mfma_i32_16x16x64_i8 v[114:117], v[174:177], v[182:185], v[114:117]
	v_mfma_i32_16x16x64_i8 v[102:105], v[166:169], v[190:193], v[102:105]
	v_mfma_i32_16x16x64_i8 v[98:101], v[174:177], v[190:193], v[98:101]
	v_mfma_i32_16x16x64_i8 v[86:89], v[166:169], v[198:201], v[86:89]
	v_mfma_i32_16x16x64_i8 v[82:85], v[174:177], v[198:201], v[82:85]
	v_mfma_i32_16x16x64_i8 v[70:73], v[166:169], v[206:209], v[70:73]
	v_mfma_i32_16x16x64_i8 v[66:69], v[174:177], v[206:209], v[66:69]
	v_mfma_i32_16x16x64_i8 v[118:121], v[170:173], v[186:189], v[118:121]
	v_mfma_i32_16x16x64_i8 v[114:117], v[178:181], v[186:189], v[114:117]
	v_mfma_i32_16x16x64_i8 v[102:105], v[170:173], v[194:197], v[102:105]
	v_mfma_i32_16x16x64_i8 v[98:101], v[178:181], v[194:197], v[98:101]
	v_mfma_i32_16x16x64_i8 v[86:89], v[170:173], v[202:205], v[86:89]
	v_mfma_i32_16x16x64_i8 v[82:85], v[178:181], v[202:205], v[82:85]
	v_mfma_i32_16x16x64_i8 v[70:73], v[170:173], v[210:213], v[70:73]
	v_mfma_i32_16x16x64_i8 v[66:69], v[178:181], v[210:213], v[66:69]
	s_setprio 0
	s_barrier
	ds_read_b128 v[182:185], v148 offset:49152
	ds_read_b128 v[186:189], v148 offset:50176
	ds_read_b128 v[190:193], v148 offset:51200
	ds_read_b128 v[194:197], v148 offset:52224
	ds_read_b128 v[198:201], v148 offset:53248
	ds_read_b128 v[202:205], v148 offset:54272
	ds_read_b128 v[206:209], v148 offset:55296
	ds_read_b128 v[210:213], v148 offset:56320
	s_add_i32 s84, s86, s40
	s_add_u32 s100, s50, s38
	s_addc_u32 s101, s51, s39
	s_mov_b32 m0, s84
	s_nop 0
	global_load_lds_dwordx4 v143, s[100:101]
	s_add_i32 m0, s84, 0x2000
	s_nop 0
	s_add_u32 s50, s50, 0x20080
	s_addc_u32 s51, s51, 0
	s_add_i32 s84, s87, s40
	global_load_lds_dwordx4 v144, s[100:101]
	s_mov_b32 m0, s84
	s_nop 0
	global_load_lds_dwordx4 v143, s[50:51]
	s_add_i32 m0, s84, 0x2000
	s_nop 0
	global_load_lds_dwordx4 v144, s[50:51]
	s_mov_b32 m0, s75
	s_add_u32 s100, s46, s38
	s_addc_u32 s101, s47, s39
	v_mov_b32_e32 v0, v133
	global_load_lds_dwordx4 v132, s[100:101]
	s_mov_b32 m0, s78
	s_nop 0
	global_load_lds_dwordx4 v133, s[100:101]
	s_waitcnt vmcnt(8)
	s_waitcnt lgkmcnt(0)
	s_barrier
	s_setprio 1
	s_waitcnt lgkmcnt(0)
	v_mfma_i32_16x16x64_i8 v[62:65], v[150:153], v[182:185], v[62:65]
	v_mfma_i32_16x16x64_i8 v[58:61], v[158:161], v[182:185], v[58:61]
	v_mfma_i32_16x16x64_i8 v[46:49], v[150:153], v[190:193], v[46:49]
	v_mfma_i32_16x16x64_i8 v[42:45], v[158:161], v[190:193], v[42:45]
	v_mfma_i32_16x16x64_i8 v[30:33], v[150:153], v[198:201], v[30:33]
	v_mfma_i32_16x16x64_i8 v[26:29], v[158:161], v[198:201], v[26:29]
	v_mfma_i32_16x16x64_i8 v[14:17], v[150:153], v[206:209], v[14:17]
	v_mfma_i32_16x16x64_i8 v[10:13], v[158:161], v[206:209], v[10:13]
	v_mfma_i32_16x16x64_i8 v[62:65], v[154:157], v[186:189], v[62:65]
	v_mfma_i32_16x16x64_i8 v[58:61], v[162:165], v[186:189], v[58:61]
	v_mfma_i32_16x16x64_i8 v[46:49], v[154:157], v[194:197], v[46:49]
	v_mfma_i32_16x16x64_i8 v[42:45], v[162:165], v[194:197], v[42:45]
	v_mfma_i32_16x16x64_i8 v[30:33], v[154:157], v[202:205], v[30:33]
	v_mfma_i32_16x16x64_i8 v[26:29], v[162:165], v[202:205], v[26:29]
	v_mfma_i32_16x16x64_i8 v[14:17], v[154:157], v[210:213], v[14:17]
	v_mfma_i32_16x16x64_i8 v[10:13], v[162:165], v[210:213], v[10:13]
	s_setprio 0
	s_setprio 1
	v_mfma_i32_16x16x64_i8 v[54:57], v[166:169], v[182:185], v[54:57]
	v_mfma_i32_16x16x64_i8 v[50:53], v[174:177], v[182:185], v[50:53]
	v_mfma_i32_16x16x64_i8 v[38:41], v[166:169], v[190:193], v[38:41]
	v_mfma_i32_16x16x64_i8 v[34:37], v[174:177], v[190:193], v[34:37]
	v_mfma_i32_16x16x64_i8 v[22:25], v[166:169], v[198:201], v[22:25]
	v_mfma_i32_16x16x64_i8 v[18:21], v[174:177], v[198:201], v[18:21]
	v_mfma_i32_16x16x64_i8 v[6:9], v[166:169], v[206:209], v[6:9]
	v_mfma_i32_16x16x64_i8 v[2:5], v[174:177], v[206:209], v[2:5]
	v_mfma_i32_16x16x64_i8 v[54:57], v[170:173], v[186:189], v[54:57]
	v_mfma_i32_16x16x64_i8 v[50:53], v[178:181], v[186:189], v[50:53]
	v_mfma_i32_16x16x64_i8 v[38:41], v[170:173], v[194:197], v[38:41]
	v_mfma_i32_16x16x64_i8 v[34:37], v[178:181], v[194:197], v[34:37]
	v_mfma_i32_16x16x64_i8 v[22:25], v[170:173], v[202:205], v[22:25]
	v_mfma_i32_16x16x64_i8 v[18:21], v[178:181], v[202:205], v[18:21]
	v_mfma_i32_16x16x64_i8 v[6:9], v[170:173], v[210:213], v[6:9]
	v_mfma_i32_16x16x64_i8 v[2:5], v[178:181], v[210:213], v[2:5]
	s_setprio 0
	s_barrier
	s_add_i32 s65, s65, 2
	s_add_u32 s48, s48, 0x100
	s_addc_u32 s49, s49, 0
	s_add_u32 s25, s25, 0x100
	s_addc_u32 s64, s64, 0
	s_cmp_gt_u32 s65, 5
	s_cbranch_scc0 .LBB0_445
	s_branch .Lpeel_exit_445
.LBB0_445:
	s_add_u32 s46, s48, 0xfffe0080
	s_addc_u32 s47, s49, -1
	s_add_i32 s84, 0, 0x10000
	s_cmp_eq_u32 s65, 4
	s_cselect_b32 s47, s15, s47
	s_cselect_b32 s46, s14, s46
	v_add_u32_e32 v0, s84, v147
	s_cselect_b32 s51, s17, s64
	s_cselect_b32 s50, s16, s25
	s_add_i32 s86, 0, 0x14000
	ds_read_b128 v[150:153], v0
	ds_read_b128 v[154:157], v0 offset:1024
	ds_read_b128 v[158:161], v0 offset:2048
	ds_read_b128 v[162:165], v0 offset:3072
	ds_read_b128 v[166:169], v0 offset:16384
	ds_read_b128 v[170:173], v0 offset:17408
	ds_read_b128 v[174:177], v0 offset:18432
	ds_read_b128 v[178:181], v0 offset:19456
	ds_read_b128 v[182:185], v148
	ds_read_b128 v[186:189], v148 offset:1024
	ds_read_b128 v[190:193], v148 offset:2048
	ds_read_b128 v[194:197], v148 offset:3072
	ds_read_b128 v[198:201], v148 offset:4096
	ds_read_b128 v[202:205], v148 offset:5120
	ds_read_b128 v[206:209], v148 offset:6144
	ds_read_b128 v[210:213], v148 offset:7168
	s_add_i32 m0, s59, 0xc000
	s_nop 0
	global_load_lds_dwordx4 v132, s[48:49]
	s_add_i32 m0, s59, 0xe000
	s_nop 0
	global_load_lds_dwordx4 v133, s[48:49]
	s_waitcnt vmcnt(8)
	s_waitcnt lgkmcnt(0)
	s_barrier
	s_setprio 1
	s_waitcnt lgkmcnt(0)
	v_mfma_i32_16x16x64_i8 v[126:129], v[150:153], v[182:185], v[126:129]
	v_mfma_i32_16x16x64_i8 v[122:125], v[158:161], v[182:185], v[122:125]
	v_mfma_i32_16x16x64_i8 v[110:113], v[150:153], v[190:193], v[110:113]
	v_mfma_i32_16x16x64_i8 v[106:109], v[158:161], v[190:193], v[106:109]
	v_mfma_i32_16x16x64_i8 v[94:97], v[150:153], v[198:201], v[94:97]
	v_mfma_i32_16x16x64_i8 v[90:93], v[158:161], v[198:201], v[90:93]
	v_mfma_i32_16x16x64_i8 v[78:81], v[150:153], v[206:209], v[78:81]
	v_mfma_i32_16x16x64_i8 v[74:77], v[158:161], v[206:209], v[74:77]
	v_mfma_i32_16x16x64_i8 v[126:129], v[154:157], v[186:189], v[126:129]
	v_mfma_i32_16x16x64_i8 v[122:125], v[162:165], v[186:189], v[122:125]
	v_mfma_i32_16x16x64_i8 v[110:113], v[154:157], v[194:197], v[110:113]
	v_mfma_i32_16x16x64_i8 v[106:109], v[162:165], v[194:197], v[106:109]
	v_mfma_i32_16x16x64_i8 v[94:97], v[154:157], v[202:205], v[94:97]
	v_mfma_i32_16x16x64_i8 v[90:93], v[162:165], v[202:205], v[90:93]
	v_mfma_i32_16x16x64_i8 v[78:81], v[154:157], v[210:213], v[78:81]
	v_mfma_i32_16x16x64_i8 v[74:77], v[162:165], v[210:213], v[74:77]
	s_setprio 0
	s_setprio 1
	v_mfma_i32_16x16x64_i8 v[118:121], v[166:169], v[182:185], v[118:121]
	v_mfma_i32_16x16x64_i8 v[114:117], v[174:177], v[182:185], v[114:117]
	v_mfma_i32_16x16x64_i8 v[102:105], v[166:169], v[190:193], v[102:105]
	v_mfma_i32_16x16x64_i8 v[98:101], v[174:177], v[190:193], v[98:101]
	v_mfma_i32_16x16x64_i8 v[86:89], v[166:169], v[198:201], v[86:89]
	v_mfma_i32_16x16x64_i8 v[82:85], v[174:177], v[198:201], v[82:85]
	v_mfma_i32_16x16x64_i8 v[70:73], v[166:169], v[206:209], v[70:73]
	v_mfma_i32_16x16x64_i8 v[66:69], v[174:177], v[206:209], v[66:69]
	v_mfma_i32_16x16x64_i8 v[118:121], v[170:173], v[186:189], v[118:121]
	v_mfma_i32_16x16x64_i8 v[114:117], v[178:181], v[186:189], v[114:117]
	v_mfma_i32_16x16x64_i8 v[102:105], v[170:173], v[194:197], v[102:105]
	v_mfma_i32_16x16x64_i8 v[98:101], v[178:181], v[194:197], v[98:101]
	v_mfma_i32_16x16x64_i8 v[86:89], v[170:173], v[202:205], v[86:89]
	v_mfma_i32_16x16x64_i8 v[82:85], v[178:181], v[202:205], v[82:85]
	v_mfma_i32_16x16x64_i8 v[70:73], v[170:173], v[210:213], v[70:73]
	v_mfma_i32_16x16x64_i8 v[66:69], v[178:181], v[210:213], v[66:69]
	s_setprio 0
	s_barrier
	s_add_i32 s84, s84, s40
	ds_read_b128 v[182:185], v148 offset:16384
	ds_read_b128 v[186:189], v148 offset:17408
	ds_read_b128 v[190:193], v148 offset:18432
	ds_read_b128 v[194:197], v148 offset:19456
	ds_read_b128 v[198:201], v148 offset:20480
	ds_read_b128 v[202:205], v148 offset:21504
	ds_read_b128 v[206:209], v148 offset:22528
	ds_read_b128 v[210:213], v148 offset:23552
	s_mov_b32 m0, s84
	s_nop 0
	global_load_lds_dwordx4 v143, s[50:51]
	s_add_i32 m0, s84, 0x2000
	s_add_u32 s84, s50, 0x20000
	global_load_lds_dwordx4 v144, s[50:51]
	s_addc_u32 s85, s51, 0
	s_add_i32 s86, s86, s40
	s_mov_b32 m0, s86
	s_nop 0
	global_load_lds_dwordx4 v143, s[84:85]
	s_add_i32 m0, s86, 0x2000
	s_nop 0
	global_load_lds_dwordx4 v144, s[84:85]
	s_mov_b32 m0, s59
	s_nop 0
	global_load_lds_dwordx4 v132, s[46:47]
	s_mov_b32 m0, s60
	s_nop 0
	global_load_lds_dwordx4 v133, s[46:47]
	s_waitcnt vmcnt(8)
	s_waitcnt lgkmcnt(0)
	s_barrier
	s_setprio 1
	s_waitcnt lgkmcnt(0)
	v_mfma_i32_16x16x64_i8 v[62:65], v[150:153], v[182:185], v[62:65]
	v_mfma_i32_16x16x64_i8 v[58:61], v[158:161], v[182:185], v[58:61]
	v_mfma_i32_16x16x64_i8 v[46:49], v[150:153], v[190:193], v[46:49]
	v_mfma_i32_16x16x64_i8 v[42:45], v[158:161], v[190:193], v[42:45]
	v_mfma_i32_16x16x64_i8 v[30:33], v[150:153], v[198:201], v[30:33]
	v_mfma_i32_16x16x64_i8 v[26:29], v[158:161], v[198:201], v[26:29]
	v_mfma_i32_16x16x64_i8 v[14:17], v[150:153], v[206:209], v[14:17]
	v_mfma_i32_16x16x64_i8 v[10:13], v[158:161], v[206:209], v[10:13]
	v_mfma_i32_16x16x64_i8 v[62:65], v[154:157], v[186:189], v[62:65]
	v_mfma_i32_16x16x64_i8 v[58:61], v[162:165], v[186:189], v[58:61]
	v_mfma_i32_16x16x64_i8 v[46:49], v[154:157], v[194:197], v[46:49]
	v_mfma_i32_16x16x64_i8 v[42:45], v[162:165], v[194:197], v[42:45]
	v_mfma_i32_16x16x64_i8 v[30:33], v[154:157], v[202:205], v[30:33]
	v_mfma_i32_16x16x64_i8 v[26:29], v[162:165], v[202:205], v[26:29]
	v_mfma_i32_16x16x64_i8 v[14:17], v[154:157], v[210:213], v[14:17]
	v_mfma_i32_16x16x64_i8 v[10:13], v[162:165], v[210:213], v[10:13]
	s_setprio 0
	s_setprio 1
	v_mfma_i32_16x16x64_i8 v[54:57], v[166:169], v[182:185], v[54:57]
	v_mfma_i32_16x16x64_i8 v[50:53], v[174:177], v[182:185], v[50:53]
	v_mfma_i32_16x16x64_i8 v[38:41], v[166:169], v[190:193], v[38:41]
	v_mfma_i32_16x16x64_i8 v[34:37], v[174:177], v[190:193], v[34:37]
	v_mfma_i32_16x16x64_i8 v[22:25], v[166:169], v[198:201], v[22:25]
	v_mfma_i32_16x16x64_i8 v[18:21], v[174:177], v[198:201], v[18:21]
	v_mfma_i32_16x16x64_i8 v[6:9], v[166:169], v[206:209], v[6:9]
	v_mfma_i32_16x16x64_i8 v[2:5], v[174:177], v[206:209], v[2:5]
	v_mfma_i32_16x16x64_i8 v[54:57], v[170:173], v[186:189], v[54:57]
	v_mfma_i32_16x16x64_i8 v[50:53], v[178:181], v[186:189], v[50:53]
	v_mfma_i32_16x16x64_i8 v[38:41], v[170:173], v[194:197], v[38:41]
	v_mfma_i32_16x16x64_i8 v[34:37], v[178:181], v[194:197], v[34:37]
	v_mfma_i32_16x16x64_i8 v[22:25], v[170:173], v[202:205], v[22:25]
	v_mfma_i32_16x16x64_i8 v[18:21], v[178:181], v[202:205], v[18:21]
	v_mfma_i32_16x16x64_i8 v[6:9], v[170:173], v[210:213], v[6:9]
	v_mfma_i32_16x16x64_i8 v[2:5], v[178:181], v[210:213], v[2:5]
	s_setprio 0
	s_barrier
	s_add_i32 s86, 0, 0x18000
	s_add_i32 s87, 0, 0x1c000
	ds_read_b128 v[150:153], v0 offset:32768
	ds_read_b128 v[154:157], v0 offset:33792
	ds_read_b128 v[158:161], v0 offset:34816
	ds_read_b128 v[162:165], v0 offset:35840
	ds_read_b128 v[166:169], v0 offset:49152
	ds_read_b128 v[170:173], v0 offset:50176
	ds_read_b128 v[174:177], v0 offset:51200
	ds_read_b128 v[178:181], v0 offset:52224
	s_add_u32 s84, s46, 0x20000
	s_mov_b32 m0, s61
	ds_read_b128 v[182:185], v148 offset:32768
	ds_read_b128 v[186:189], v148 offset:33792
	ds_read_b128 v[190:193], v148 offset:34816
	ds_read_b128 v[194:197], v148 offset:35840
	ds_read_b128 v[198:201], v148 offset:36864
	ds_read_b128 v[202:205], v148 offset:37888
	ds_read_b128 v[206:209], v148 offset:38912
	ds_read_b128 v[210:213], v148 offset:39936
	s_addc_u32 s85, s47, 0
	s_nop 0
	global_load_lds_dwordx4 v132, s[84:85]
	s_mov_b32 m0, s66
	s_nop 0
	global_load_lds_dwordx4 v133, s[84:85]
	s_waitcnt vmcnt(8)
	s_waitcnt lgkmcnt(0)
	s_barrier
	s_setprio 1
	s_waitcnt lgkmcnt(0)
	v_mfma_i32_16x16x64_i8 v[126:129], v[150:153], v[182:185], v[126:129]
	v_mfma_i32_16x16x64_i8 v[122:125], v[158:161], v[182:185], v[122:125]
	v_mfma_i32_16x16x64_i8 v[110:113], v[150:153], v[190:193], v[110:113]
	v_mfma_i32_16x16x64_i8 v[106:109], v[158:161], v[190:193], v[106:109]
	v_mfma_i32_16x16x64_i8 v[94:97], v[150:153], v[198:201], v[94:97]
	v_mfma_i32_16x16x64_i8 v[90:93], v[158:161], v[198:201], v[90:93]
	v_mfma_i32_16x16x64_i8 v[78:81], v[150:153], v[206:209], v[78:81]
	v_mfma_i32_16x16x64_i8 v[74:77], v[158:161], v[206:209], v[74:77]
	v_mfma_i32_16x16x64_i8 v[126:129], v[154:157], v[186:189], v[126:129]
	v_mfma_i32_16x16x64_i8 v[122:125], v[162:165], v[186:189], v[122:125]
	v_mfma_i32_16x16x64_i8 v[110:113], v[154:157], v[194:197], v[110:113]
	v_mfma_i32_16x16x64_i8 v[106:109], v[162:165], v[194:197], v[106:109]
	v_mfma_i32_16x16x64_i8 v[94:97], v[154:157], v[202:205], v[94:97]
	v_mfma_i32_16x16x64_i8 v[90:93], v[162:165], v[202:205], v[90:93]
	v_mfma_i32_16x16x64_i8 v[78:81], v[154:157], v[210:213], v[78:81]
	v_mfma_i32_16x16x64_i8 v[74:77], v[162:165], v[210:213], v[74:77]
	s_setprio 0
	s_setprio 1
	v_mfma_i32_16x16x64_i8 v[118:121], v[166:169], v[182:185], v[118:121]
	v_mfma_i32_16x16x64_i8 v[114:117], v[174:177], v[182:185], v[114:117]
	v_mfma_i32_16x16x64_i8 v[102:105], v[166:169], v[190:193], v[102:105]
	v_mfma_i32_16x16x64_i8 v[98:101], v[174:177], v[190:193], v[98:101]
	v_mfma_i32_16x16x64_i8 v[86:89], v[166:169], v[198:201], v[86:89]
	v_mfma_i32_16x16x64_i8 v[82:85], v[174:177], v[198:201], v[82:85]
	v_mfma_i32_16x16x64_i8 v[70:73], v[166:169], v[206:209], v[70:73]
	v_mfma_i32_16x16x64_i8 v[66:69], v[174:177], v[206:209], v[66:69]
	v_mfma_i32_16x16x64_i8 v[118:121], v[170:173], v[186:189], v[118:121]
	v_mfma_i32_16x16x64_i8 v[114:117], v[178:181], v[186:189], v[114:117]
	v_mfma_i32_16x16x64_i8 v[102:105], v[170:173], v[194:197], v[102:105]
	v_mfma_i32_16x16x64_i8 v[98:101], v[178:181], v[194:197], v[98:101]
	v_mfma_i32_16x16x64_i8 v[86:89], v[170:173], v[202:205], v[86:89]
	v_mfma_i32_16x16x64_i8 v[82:85], v[178:181], v[202:205], v[82:85]
	v_mfma_i32_16x16x64_i8 v[70:73], v[170:173], v[210:213], v[70:73]
	v_mfma_i32_16x16x64_i8 v[66:69], v[178:181], v[210:213], v[66:69]
	s_setprio 0
	s_barrier
	ds_read_b128 v[182:185], v148 offset:49152
	ds_read_b128 v[186:189], v148 offset:50176
	ds_read_b128 v[190:193], v148 offset:51200
	ds_read_b128 v[194:197], v148 offset:52224
	ds_read_b128 v[198:201], v148 offset:53248
	ds_read_b128 v[202:205], v148 offset:54272
	ds_read_b128 v[206:209], v148 offset:55296
	ds_read_b128 v[210:213], v148 offset:56320
	s_add_i32 s84, s86, s40
	s_add_u32 s100, s50, s38
	s_addc_u32 s101, s51, s39
	s_mov_b32 m0, s84
	s_nop 0
	global_load_lds_dwordx4 v143, s[100:101]
	s_add_i32 m0, s84, 0x2000
	s_nop 0
	s_add_u32 s50, s50, 0x20080
	s_addc_u32 s51, s51, 0
	s_add_i32 s84, s87, s40
	global_load_lds_dwordx4 v144, s[100:101]
	s_mov_b32 m0, s84
	s_nop 0
	global_load_lds_dwordx4 v143, s[50:51]
	s_add_i32 m0, s84, 0x2000
	s_nop 0
	global_load_lds_dwordx4 v144, s[50:51]
	s_mov_b32 m0, s75
	s_add_u32 s100, s46, s38
	s_addc_u32 s101, s47, s39
	v_mov_b32_e32 v0, v133
	global_load_lds_dwordx4 v132, s[100:101]
	s_mov_b32 m0, s78
	s_nop 0
	global_load_lds_dwordx4 v133, s[100:101]
	s_waitcnt vmcnt(8)
	s_waitcnt lgkmcnt(0)
	s_barrier
	s_setprio 1
	s_waitcnt lgkmcnt(0)
	v_mfma_i32_16x16x64_i8 v[62:65], v[150:153], v[182:185], v[62:65]
	v_mfma_i32_16x16x64_i8 v[58:61], v[158:161], v[182:185], v[58:61]
	v_mfma_i32_16x16x64_i8 v[46:49], v[150:153], v[190:193], v[46:49]
	v_mfma_i32_16x16x64_i8 v[42:45], v[158:161], v[190:193], v[42:45]
	v_mfma_i32_16x16x64_i8 v[30:33], v[150:153], v[198:201], v[30:33]
	v_mfma_i32_16x16x64_i8 v[26:29], v[158:161], v[198:201], v[26:29]
	v_mfma_i32_16x16x64_i8 v[14:17], v[150:153], v[206:209], v[14:17]
	v_mfma_i32_16x16x64_i8 v[10:13], v[158:161], v[206:209], v[10:13]
	v_mfma_i32_16x16x64_i8 v[62:65], v[154:157], v[186:189], v[62:65]
	v_mfma_i32_16x16x64_i8 v[58:61], v[162:165], v[186:189], v[58:61]
	v_mfma_i32_16x16x64_i8 v[46:49], v[154:157], v[194:197], v[46:49]
	v_mfma_i32_16x16x64_i8 v[42:45], v[162:165], v[194:197], v[42:45]
	v_mfma_i32_16x16x64_i8 v[30:33], v[154:157], v[202:205], v[30:33]
	v_mfma_i32_16x16x64_i8 v[26:29], v[162:165], v[202:205], v[26:29]
	v_mfma_i32_16x16x64_i8 v[14:17], v[154:157], v[210:213], v[14:17]
	v_mfma_i32_16x16x64_i8 v[10:13], v[162:165], v[210:213], v[10:13]
	s_setprio 0
	s_setprio 1
	v_mfma_i32_16x16x64_i8 v[54:57], v[166:169], v[182:185], v[54:57]
	v_mfma_i32_16x16x64_i8 v[50:53], v[174:177], v[182:185], v[50:53]
	v_mfma_i32_16x16x64_i8 v[38:41], v[166:169], v[190:193], v[38:41]
	v_mfma_i32_16x16x64_i8 v[34:37], v[174:177], v[190:193], v[34:37]
	v_mfma_i32_16x16x64_i8 v[22:25], v[166:169], v[198:201], v[22:25]
	v_mfma_i32_16x16x64_i8 v[18:21], v[174:177], v[198:201], v[18:21]
	v_mfma_i32_16x16x64_i8 v[6:9], v[166:169], v[206:209], v[6:9]
	v_mfma_i32_16x16x64_i8 v[2:5], v[174:177], v[206:209], v[2:5]
	v_mfma_i32_16x16x64_i8 v[54:57], v[170:173], v[186:189], v[54:57]
	v_mfma_i32_16x16x64_i8 v[50:53], v[178:181], v[186:189], v[50:53]
	v_mfma_i32_16x16x64_i8 v[38:41], v[170:173], v[194:197], v[38:41]
	v_mfma_i32_16x16x64_i8 v[34:37], v[178:181], v[194:197], v[34:37]
	v_mfma_i32_16x16x64_i8 v[22:25], v[170:173], v[202:205], v[22:25]
	v_mfma_i32_16x16x64_i8 v[18:21], v[178:181], v[202:205], v[18:21]
	v_mfma_i32_16x16x64_i8 v[6:9], v[170:173], v[210:213], v[6:9]
	v_mfma_i32_16x16x64_i8 v[2:5], v[178:181], v[210:213], v[2:5]
	s_setprio 0
	s_barrier
	s_add_i32 s65, s65, 2
	s_add_u32 s48, s48, 0x100
	s_addc_u32 s49, s49, 0
	s_add_u32 s25, s25, 0x100
	s_addc_u32 s64, s64, 0
	s_cmp_gt_u32 s65, 5
	s_cbranch_scc0 .LBB0_445

.LBB0_626:
	s_add_u32 s58, s14, s50
	s_addc_u32 s59, s15, s51
	s_add_u32 s46, s58, 0x100
	s_addc_u32 s47, s59, 0
	s_and_b64 s[4:5], s[48:49], exec
	s_cselect_b32 s47, s15, s47
	s_cselect_b32 s46, s14, s46
	s_add_u32 s4, s16, s50
	s_addc_u32 s5, s17, s51
	s_add_u32 s50, s4, 0x100
	s_addc_u32 s51, s5, 0
	s_add_i32 s78, 0, 0x10000
	s_and_b64 s[4:5], s[48:49], exec
	s_cselect_b32 s49, s17, s51
	s_cselect_b32 s48, s16, s50
	s_add_i32 s4, 0, 0x14000
	s_add_u32 s96, s58, 0x80080
	s_addc_u32 s97, s59, 0
	s_add_i32 s82, s78, s42
	s_add_i32 m0, s43, 0xc000
	s_add_i32 s5, s43, 0xe000
	s_add_i32 s76, s82, 0x2000
	v_add_u32_e32 v0, s78, v136
	s_add_u32 s94, s48, 0x40000
	ds_read_b128 v[138:141], v0
	ds_read_b128 v[142:145], v0 offset:1024
	ds_read_b128 v[146:149], v0 offset:2048
	ds_read_b128 v[150:153], v0 offset:3072
	s_addc_u32 s95, s49, 0
	s_add_i32 s77, s4, s42
	ds_read_b128 v[154:157], v0 offset:16384
	ds_read_b128 v[158:161], v0 offset:17408
	ds_read_b128 v[162:165], v0 offset:18432
	ds_read_b128 v[166:169], v0 offset:19456
	s_add_i32 s75, s77, 0x2000
	s_add_i32 s74, 0, 0x18000
	s_add_i32 s71, 0, 0x1c000
	s_add_u32 s58, s46, 0x80000
	s_addc_u32 s59, s47, 0
	s_add_i32 s70, s74, s42
	s_add_i32 s69, s70, 0x2000
	s_add_u32 s50, s48, 0x40080
	s_addc_u32 s51, s49, 0
	s_add_i32 s79, s71, s42
	s_add_i32 s78, s79, 0x2000
	ds_read_b128 v[170:173], v137
	ds_read_b128 v[174:177], v137 offset:1024
	ds_read_b128 v[178:181], v137 offset:2048
	ds_read_b128 v[182:185], v137 offset:3072
	ds_read_b128 v[186:189], v137 offset:4096
	ds_read_b128 v[190:193], v137 offset:5120
	ds_read_b128 v[194:197], v137 offset:6144
	ds_read_b128 v[198:201], v137 offset:7168
	s_nop 0
	global_load_lds_dwordx4 v130, s[96:97]
	s_mov_b32 m0, s5
	s_nop 0
	global_load_lds_dwordx4 v132, s[96:97]
	s_waitcnt vmcnt(8)
	s_waitcnt lgkmcnt(0)
	s_barrier
	s_setprio 1
	s_waitcnt lgkmcnt(0)
	v_mfma_f32_16x16x32_bf16 v[126:129], v[138:141], v[170:173], v[126:129]
	v_mfma_f32_16x16x32_bf16 v[122:125], v[146:149], v[170:173], v[122:125]
	v_mfma_f32_16x16x32_bf16 v[118:121], v[138:141], v[178:181], v[118:121]
	v_mfma_f32_16x16x32_bf16 v[110:113], v[146:149], v[178:181], v[110:113]
	v_mfma_f32_16x16x32_bf16 v[102:105], v[138:141], v[186:189], v[102:105]
	v_mfma_f32_16x16x32_bf16 v[94:97], v[146:149], v[186:189], v[94:97]
	v_mfma_f32_16x16x32_bf16 v[86:89], v[138:141], v[194:197], v[86:89]
	v_mfma_f32_16x16x32_bf16 v[78:81], v[146:149], v[194:197], v[78:81]
	v_mfma_f32_16x16x32_bf16 v[126:129], v[142:145], v[174:177], v[126:129]
	v_mfma_f32_16x16x32_bf16 v[122:125], v[150:153], v[174:177], v[122:125]
	v_mfma_f32_16x16x32_bf16 v[118:121], v[142:145], v[182:185], v[118:121]
	v_mfma_f32_16x16x32_bf16 v[110:113], v[150:153], v[182:185], v[110:113]
	v_mfma_f32_16x16x32_bf16 v[102:105], v[142:145], v[190:193], v[102:105]
	v_mfma_f32_16x16x32_bf16 v[94:97], v[150:153], v[190:193], v[94:97]
	v_mfma_f32_16x16x32_bf16 v[86:89], v[142:145], v[198:201], v[86:89]
	v_mfma_f32_16x16x32_bf16 v[78:81], v[150:153], v[198:201], v[78:81]
	s_setprio 0
	s_setprio 1
	v_mfma_f32_16x16x32_bf16 v[114:117], v[154:157], v[170:173], v[114:117]
	v_mfma_f32_16x16x32_bf16 v[106:109], v[162:165], v[170:173], v[106:109]
	v_mfma_f32_16x16x32_bf16 v[98:101], v[154:157], v[178:181], v[98:101]
	v_mfma_f32_16x16x32_bf16 v[90:93], v[162:165], v[178:181], v[90:93]
	v_mfma_f32_16x16x32_bf16 v[82:85], v[154:157], v[186:189], v[82:85]
	v_mfma_f32_16x16x32_bf16 v[74:77], v[162:165], v[186:189], v[74:77]
	v_mfma_f32_16x16x32_bf16 v[70:73], v[154:157], v[194:197], v[70:73]
	v_mfma_f32_16x16x32_bf16 v[62:65], v[162:165], v[194:197], v[62:65]
	v_mfma_f32_16x16x32_bf16 v[114:117], v[158:161], v[174:177], v[114:117]
	v_mfma_f32_16x16x32_bf16 v[106:109], v[166:169], v[174:177], v[106:109]
	v_mfma_f32_16x16x32_bf16 v[98:101], v[158:161], v[182:185], v[98:101]
	v_mfma_f32_16x16x32_bf16 v[90:93], v[166:169], v[182:185], v[90:93]
	v_mfma_f32_16x16x32_bf16 v[82:85], v[158:161], v[190:193], v[82:85]
	v_mfma_f32_16x16x32_bf16 v[74:77], v[166:169], v[190:193], v[74:77]
	v_mfma_f32_16x16x32_bf16 v[70:73], v[158:161], v[198:201], v[70:73]
	v_mfma_f32_16x16x32_bf16 v[62:65], v[166:169], v[198:201], v[62:65]
	s_setprio 0
	s_barrier
	s_mov_b32 m0, s82
	ds_read_b128 v[170:173], v137 offset:16384
	ds_read_b128 v[174:177], v137 offset:17408
	ds_read_b128 v[178:181], v137 offset:18432
	ds_read_b128 v[182:185], v137 offset:19456
	ds_read_b128 v[186:189], v137 offset:20480
	ds_read_b128 v[190:193], v137 offset:21504
	ds_read_b128 v[194:197], v137 offset:22528
	ds_read_b128 v[198:201], v137 offset:23552
	s_nop 0
	global_load_lds_dwordx4 v131, s[48:49]
	s_mov_b32 m0, s76
	s_nop 0
	global_load_lds_dwordx4 v133, s[48:49]
	s_mov_b32 m0, s77
	s_nop 0
	global_load_lds_dwordx4 v131, s[94:95]
	s_mov_b32 m0, s75
	s_nop 0
	global_load_lds_dwordx4 v133, s[94:95]
	s_mov_b32 m0, s43
	s_nop 0
	global_load_lds_dwordx4 v130, s[46:47]
	s_mov_b32 m0, s60
	s_nop 0
	global_load_lds_dwordx4 v132, s[46:47]
	s_waitcnt vmcnt(8)
	s_waitcnt lgkmcnt(0)
	s_barrier
	s_setprio 1
	s_waitcnt lgkmcnt(0)
	v_mfma_f32_16x16x32_bf16 v[66:69], v[138:141], v[170:173], v[66:69]
	v_mfma_f32_16x16x32_bf16 v[58:61], v[146:149], v[170:173], v[58:61]
	v_mfma_f32_16x16x32_bf16 v[54:57], v[138:141], v[178:181], v[54:57]
	v_mfma_f32_16x16x32_bf16 v[46:49], v[146:149], v[178:181], v[46:49]
	v_mfma_f32_16x16x32_bf16 v[38:41], v[138:141], v[186:189], v[38:41]
	v_mfma_f32_16x16x32_bf16 v[30:33], v[146:149], v[186:189], v[30:33]
	v_mfma_f32_16x16x32_bf16 v[22:25], v[138:141], v[194:197], v[22:25]
	v_mfma_f32_16x16x32_bf16 v[14:17], v[146:149], v[194:197], v[14:17]
	v_mfma_f32_16x16x32_bf16 v[66:69], v[142:145], v[174:177], v[66:69]
	v_mfma_f32_16x16x32_bf16 v[58:61], v[150:153], v[174:177], v[58:61]
	v_mfma_f32_16x16x32_bf16 v[54:57], v[142:145], v[182:185], v[54:57]
	v_mfma_f32_16x16x32_bf16 v[46:49], v[150:153], v[182:185], v[46:49]
	v_mfma_f32_16x16x32_bf16 v[38:41], v[142:145], v[190:193], v[38:41]
	v_mfma_f32_16x16x32_bf16 v[30:33], v[150:153], v[190:193], v[30:33]
	v_mfma_f32_16x16x32_bf16 v[22:25], v[142:145], v[198:201], v[22:25]
	v_mfma_f32_16x16x32_bf16 v[14:17], v[150:153], v[198:201], v[14:17]
	s_setprio 0
	s_setprio 1
	v_mfma_f32_16x16x32_bf16 v[50:53], v[154:157], v[170:173], v[50:53]
	v_mfma_f32_16x16x32_bf16 v[42:45], v[162:165], v[170:173], v[42:45]
	v_mfma_f32_16x16x32_bf16 v[34:37], v[154:157], v[178:181], v[34:37]
	v_mfma_f32_16x16x32_bf16 v[26:29], v[162:165], v[178:181], v[26:29]
	v_mfma_f32_16x16x32_bf16 v[18:21], v[154:157], v[186:189], v[18:21]
	v_mfma_f32_16x16x32_bf16 v[10:13], v[162:165], v[186:189], v[10:13]
	v_mfma_f32_16x16x32_bf16 v[6:9], v[154:157], v[194:197], v[6:9]
	v_mfma_f32_16x16x32_bf16 v[2:5], v[162:165], v[194:197], v[2:5]
	v_mfma_f32_16x16x32_bf16 v[50:53], v[158:161], v[174:177], v[50:53]
	v_mfma_f32_16x16x32_bf16 v[42:45], v[166:169], v[174:177], v[42:45]
	v_mfma_f32_16x16x32_bf16 v[34:37], v[158:161], v[182:185], v[34:37]
	v_mfma_f32_16x16x32_bf16 v[26:29], v[166:169], v[182:185], v[26:29]
	v_mfma_f32_16x16x32_bf16 v[18:21], v[158:161], v[190:193], v[18:21]
	v_mfma_f32_16x16x32_bf16 v[10:13], v[166:169], v[190:193], v[10:13]
	v_mfma_f32_16x16x32_bf16 v[6:9], v[158:161], v[198:201], v[6:9]
	v_mfma_f32_16x16x32_bf16 v[2:5], v[166:169], v[198:201], v[2:5]
	s_setprio 0
	s_barrier
	ds_read_b128 v[138:141], v0 offset:32768
	ds_read_b128 v[142:145], v0 offset:33792
	ds_read_b128 v[146:149], v0 offset:34816
	ds_read_b128 v[150:153], v0 offset:35840
	ds_read_b128 v[154:157], v0 offset:49152
	ds_read_b128 v[158:161], v0 offset:50176
	ds_read_b128 v[162:165], v0 offset:51200
	ds_read_b128 v[166:169], v0 offset:52224
	s_mov_b32 m0, s65
	ds_read_b128 v[170:173], v137 offset:32768
	ds_read_b128 v[174:177], v137 offset:33792
	ds_read_b128 v[178:181], v137 offset:34816
	ds_read_b128 v[182:185], v137 offset:35840
	ds_read_b128 v[186:189], v137 offset:36864
	ds_read_b128 v[190:193], v137 offset:37888
	ds_read_b128 v[194:197], v137 offset:38912
	ds_read_b128 v[198:201], v137 offset:39936
	s_nop 0
	global_load_lds_dwordx4 v130, s[58:59]
	s_mov_b32 m0, s66
	s_nop 0
	global_load_lds_dwordx4 v132, s[58:59]
	s_waitcnt vmcnt(8)
	s_waitcnt lgkmcnt(0)
	s_barrier
	s_setprio 1
	s_waitcnt lgkmcnt(0)
	v_mfma_f32_16x16x32_bf16 v[126:129], v[138:141], v[170:173], v[126:129]
	v_mfma_f32_16x16x32_bf16 v[122:125], v[146:149], v[170:173], v[122:125]
	v_mfma_f32_16x16x32_bf16 v[118:121], v[138:141], v[178:181], v[118:121]
	v_mfma_f32_16x16x32_bf16 v[110:113], v[146:149], v[178:181], v[110:113]
	v_mfma_f32_16x16x32_bf16 v[102:105], v[138:141], v[186:189], v[102:105]
	v_mfma_f32_16x16x32_bf16 v[94:97], v[146:149], v[186:189], v[94:97]
	v_mfma_f32_16x16x32_bf16 v[86:89], v[138:141], v[194:197], v[86:89]
	v_mfma_f32_16x16x32_bf16 v[78:81], v[146:149], v[194:197], v[78:81]
	v_mfma_f32_16x16x32_bf16 v[126:129], v[142:145], v[174:177], v[126:129]
	v_mfma_f32_16x16x32_bf16 v[122:125], v[150:153], v[174:177], v[122:125]
	v_mfma_f32_16x16x32_bf16 v[118:121], v[142:145], v[182:185], v[118:121]
	v_mfma_f32_16x16x32_bf16 v[110:113], v[150:153], v[182:185], v[110:113]
	v_mfma_f32_16x16x32_bf16 v[102:105], v[142:145], v[190:193], v[102:105]
	v_mfma_f32_16x16x32_bf16 v[94:97], v[150:153], v[190:193], v[94:97]
	v_mfma_f32_16x16x32_bf16 v[86:89], v[142:145], v[198:201], v[86:89]
	v_mfma_f32_16x16x32_bf16 v[78:81], v[150:153], v[198:201], v[78:81]
	s_setprio 0
	s_setprio 1
	v_mfma_f32_16x16x32_bf16 v[114:117], v[154:157], v[170:173], v[114:117]
	v_mfma_f32_16x16x32_bf16 v[106:109], v[162:165], v[170:173], v[106:109]
	v_mfma_f32_16x16x32_bf16 v[98:101], v[154:157], v[178:181], v[98:101]
	v_mfma_f32_16x16x32_bf16 v[90:93], v[162:165], v[178:181], v[90:93]
	v_mfma_f32_16x16x32_bf16 v[82:85], v[154:157], v[186:189], v[82:85]
	v_mfma_f32_16x16x32_bf16 v[74:77], v[162:165], v[186:189], v[74:77]
	v_mfma_f32_16x16x32_bf16 v[70:73], v[154:157], v[194:197], v[70:73]
	v_mfma_f32_16x16x32_bf16 v[62:65], v[162:165], v[194:197], v[62:65]
	v_mfma_f32_16x16x32_bf16 v[114:117], v[158:161], v[174:177], v[114:117]
	v_mfma_f32_16x16x32_bf16 v[106:109], v[166:169], v[174:177], v[106:109]
	v_mfma_f32_16x16x32_bf16 v[98:101], v[158:161], v[182:185], v[98:101]
	v_mfma_f32_16x16x32_bf16 v[90:93], v[166:169], v[182:185], v[90:93]
	v_mfma_f32_16x16x32_bf16 v[82:85], v[158:161], v[190:193], v[82:85]
	v_mfma_f32_16x16x32_bf16 v[74:77], v[166:169], v[190:193], v[74:77]
	v_mfma_f32_16x16x32_bf16 v[70:73], v[158:161], v[198:201], v[70:73]
	v_mfma_f32_16x16x32_bf16 v[62:65], v[166:169], v[198:201], v[62:65]
	s_setprio 0
	s_barrier
	ds_read_b128 v[170:173], v137 offset:49152
	ds_read_b128 v[174:177], v137 offset:50176
	ds_read_b128 v[178:181], v137 offset:51200
	ds_read_b128 v[182:185], v137 offset:52224
	ds_read_b128 v[186:189], v137 offset:53248
	ds_read_b128 v[190:193], v137 offset:54272
	ds_read_b128 v[194:197], v137 offset:55296
	ds_read_b128 v[198:201], v137 offset:56320
	s_mov_b32 m0, s70
	s_add_u32 s100, s48, s38
	s_addc_u32 s101, s49, s39
	global_load_lds_dwordx4 v131, s[100:101]
	s_mov_b32 m0, s69
	s_nop 0
	global_load_lds_dwordx4 v133, s[100:101]
	s_mov_b32 m0, s79
	s_nop 0
	global_load_lds_dwordx4 v131, s[50:51]
	s_mov_b32 m0, s78
	s_nop 0
	global_load_lds_dwordx4 v133, s[50:51]
	s_mov_b32 m0, s67
	s_add_u32 s100, s46, s38
	s_addc_u32 s101, s47, s39
	v_mov_b32_e32 v0, v132
	global_load_lds_dwordx4 v130, s[100:101]
	s_mov_b32 m0, s68
	s_nop 0
	global_load_lds_dwordx4 v132, s[100:101]
	s_waitcnt vmcnt(8)
	s_waitcnt lgkmcnt(0)
	s_barrier
	s_setprio 1
	s_waitcnt lgkmcnt(0)
	v_mfma_f32_16x16x32_bf16 v[66:69], v[138:141], v[170:173], v[66:69]
	v_mfma_f32_16x16x32_bf16 v[58:61], v[146:149], v[170:173], v[58:61]
	v_mfma_f32_16x16x32_bf16 v[54:57], v[138:141], v[178:181], v[54:57]
	v_mfma_f32_16x16x32_bf16 v[46:49], v[146:149], v[178:181], v[46:49]
	v_mfma_f32_16x16x32_bf16 v[38:41], v[138:141], v[186:189], v[38:41]
	v_mfma_f32_16x16x32_bf16 v[30:33], v[146:149], v[186:189], v[30:33]
	v_mfma_f32_16x16x32_bf16 v[22:25], v[138:141], v[194:197], v[22:25]
	v_mfma_f32_16x16x32_bf16 v[14:17], v[146:149], v[194:197], v[14:17]
	v_mfma_f32_16x16x32_bf16 v[66:69], v[142:145], v[174:177], v[66:69]
	v_mfma_f32_16x16x32_bf16 v[58:61], v[150:153], v[174:177], v[58:61]
	v_mfma_f32_16x16x32_bf16 v[54:57], v[142:145], v[182:185], v[54:57]
	v_mfma_f32_16x16x32_bf16 v[46:49], v[150:153], v[182:185], v[46:49]
	v_mfma_f32_16x16x32_bf16 v[38:41], v[142:145], v[190:193], v[38:41]
	v_mfma_f32_16x16x32_bf16 v[30:33], v[150:153], v[190:193], v[30:33]
	v_mfma_f32_16x16x32_bf16 v[22:25], v[142:145], v[198:201], v[22:25]
	v_mfma_f32_16x16x32_bf16 v[14:17], v[150:153], v[198:201], v[14:17]
	s_setprio 0
	s_setprio 1
	v_mfma_f32_16x16x32_bf16 v[50:53], v[154:157], v[170:173], v[50:53]
	v_mfma_f32_16x16x32_bf16 v[42:45], v[162:165], v[170:173], v[42:45]
	v_mfma_f32_16x16x32_bf16 v[34:37], v[154:157], v[178:181], v[34:37]
	v_mfma_f32_16x16x32_bf16 v[26:29], v[162:165], v[178:181], v[26:29]
	v_mfma_f32_16x16x32_bf16 v[18:21], v[154:157], v[186:189], v[18:21]
	v_mfma_f32_16x16x32_bf16 v[10:13], v[162:165], v[186:189], v[10:13]
	v_mfma_f32_16x16x32_bf16 v[6:9], v[154:157], v[194:197], v[6:9]
	v_mfma_f32_16x16x32_bf16 v[2:5], v[162:165], v[194:197], v[2:5]
	v_mfma_f32_16x16x32_bf16 v[50:53], v[158:161], v[174:177], v[50:53]
	v_mfma_f32_16x16x32_bf16 v[42:45], v[166:169], v[174:177], v[42:45]
	v_mfma_f32_16x16x32_bf16 v[34:37], v[158:161], v[182:185], v[34:37]
	v_mfma_f32_16x16x32_bf16 v[26:29], v[166:169], v[182:185], v[26:29]
	v_mfma_f32_16x16x32_bf16 v[18:21], v[158:161], v[190:193], v[18:21]
	v_mfma_f32_16x16x32_bf16 v[10:13], v[166:169], v[190:193], v[10:13]
	v_mfma_f32_16x16x32_bf16 v[6:9], v[158:161], v[198:201], v[6:9]
	v_mfma_f32_16x16x32_bf16 v[2:5], v[166:169], v[198:201], v[2:5]
	s_setprio 0
	s_barrier
	s_andn2_b64 vcc, exec, s[22:23]
	s_mov_b64 s[48:49], -1
	s_mov_b64 s[22:23], 0
	s_mov_b64 s[50:51], 0x100
	s_cbranch_vccz .LBB0_626
	s_cmpk_lt_u32 s25, 0x100
	s_cbranch_scc0 .LBB0_629
	s_barrier

.LBB0_634:
	s_add_u32 s50, s2, s48
	s_addc_u32 s51, s3, s49
	s_add_u32 s22, s50, 0x100
	s_addc_u32 s23, s51, 0
	s_and_b64 s[4:5], s[46:47], exec
	s_cselect_b32 s23, s3, s23
	s_cselect_b32 s22, s2, s22
	s_add_u32 s4, s14, s48
	s_addc_u32 s5, s15, s49
	s_add_u32 s48, s4, 0x900
	s_addc_u32 s49, s5, 0
	s_add_i32 s78, 0, 0x10000
	s_and_b64 s[4:5], s[46:47], exec
	s_cselect_b32 s47, s66, s49
	s_cselect_b32 s46, s65, s48
	s_add_i32 s4, 0, 0x14000
	s_add_u32 s94, s50, 0x40080
	s_addc_u32 s95, s51, 0
	s_add_i32 s82, s78, s40
	s_add_i32 m0, s41, 0xc000
	s_add_i32 s5, s41, 0xe000
	s_add_i32 s76, s82, 0x2000
	v_add_u32_e32 v0, s78, v136
	s_add_u32 s58, s46, 0x80000
	ds_read_b128 v[138:141], v0
	ds_read_b128 v[142:145], v0 offset:1024
	ds_read_b128 v[146:149], v0 offset:2048
	ds_read_b128 v[150:153], v0 offset:3072
	s_addc_u32 s59, s47, 0
	s_add_i32 s77, s4, s40
	ds_read_b128 v[154:157], v0 offset:16384
	ds_read_b128 v[158:161], v0 offset:17408
	ds_read_b128 v[162:165], v0 offset:18432
	ds_read_b128 v[166:169], v0 offset:19456
	s_add_i32 s75, s77, 0x2000
	s_add_i32 s74, 0, 0x18000
	s_add_i32 s71, 0, 0x1c000
	s_add_u32 s50, s22, 0x40000
	s_addc_u32 s51, s23, 0
	s_add_i32 s70, s74, s40
	s_add_i32 s69, s70, 0x2000
	s_add_u32 s48, s46, 0x80080
	s_addc_u32 s49, s47, 0
	s_add_i32 s79, s71, s40
	s_add_i32 s78, s79, 0x2000
	ds_read_b128 v[170:173], v137
	ds_read_b128 v[174:177], v137 offset:1024
	ds_read_b128 v[178:181], v137 offset:2048
	ds_read_b128 v[182:185], v137 offset:3072
	ds_read_b128 v[186:189], v137 offset:4096
	ds_read_b128 v[190:193], v137 offset:5120
	ds_read_b128 v[194:197], v137 offset:6144
	ds_read_b128 v[198:201], v137 offset:7168
	s_nop 0
	global_load_lds_dwordx4 v130, s[94:95]
	s_mov_b32 m0, s5
	s_nop 0
	global_load_lds_dwordx4 v132, s[94:95]
	s_waitcnt vmcnt(8)
	s_waitcnt lgkmcnt(0)
	s_barrier
	s_setprio 1
	s_waitcnt lgkmcnt(0)
	v_mfma_f32_16x16x32_bf16 v[126:129], v[138:141], v[170:173], v[126:129]
	v_mfma_f32_16x16x32_bf16 v[122:125], v[146:149], v[170:173], v[122:125]
	v_mfma_f32_16x16x32_bf16 v[118:121], v[138:141], v[178:181], v[118:121]
	v_mfma_f32_16x16x32_bf16 v[110:113], v[146:149], v[178:181], v[110:113]
	v_mfma_f32_16x16x32_bf16 v[102:105], v[138:141], v[186:189], v[102:105]
	v_mfma_f32_16x16x32_bf16 v[94:97], v[146:149], v[186:189], v[94:97]
	v_mfma_f32_16x16x32_bf16 v[86:89], v[138:141], v[194:197], v[86:89]
	v_mfma_f32_16x16x32_bf16 v[78:81], v[146:149], v[194:197], v[78:81]
	v_mfma_f32_16x16x32_bf16 v[126:129], v[142:145], v[174:177], v[126:129]
	v_mfma_f32_16x16x32_bf16 v[122:125], v[150:153], v[174:177], v[122:125]
	v_mfma_f32_16x16x32_bf16 v[118:121], v[142:145], v[182:185], v[118:121]
	v_mfma_f32_16x16x32_bf16 v[110:113], v[150:153], v[182:185], v[110:113]
	v_mfma_f32_16x16x32_bf16 v[102:105], v[142:145], v[190:193], v[102:105]
	v_mfma_f32_16x16x32_bf16 v[94:97], v[150:153], v[190:193], v[94:97]
	v_mfma_f32_16x16x32_bf16 v[86:89], v[142:145], v[198:201], v[86:89]
	v_mfma_f32_16x16x32_bf16 v[78:81], v[150:153], v[198:201], v[78:81]
	s_setprio 0
	s_setprio 1
	v_mfma_f32_16x16x32_bf16 v[114:117], v[154:157], v[170:173], v[114:117]
	v_mfma_f32_16x16x32_bf16 v[106:109], v[162:165], v[170:173], v[106:109]
	v_mfma_f32_16x16x32_bf16 v[98:101], v[154:157], v[178:181], v[98:101]
	v_mfma_f32_16x16x32_bf16 v[90:93], v[162:165], v[178:181], v[90:93]
	v_mfma_f32_16x16x32_bf16 v[82:85], v[154:157], v[186:189], v[82:85]
	v_mfma_f32_16x16x32_bf16 v[74:77], v[162:165], v[186:189], v[74:77]
	v_mfma_f32_16x16x32_bf16 v[70:73], v[154:157], v[194:197], v[70:73]
	v_mfma_f32_16x16x32_bf16 v[62:65], v[162:165], v[194:197], v[62:65]
	v_mfma_f32_16x16x32_bf16 v[114:117], v[158:161], v[174:177], v[114:117]
	v_mfma_f32_16x16x32_bf16 v[106:109], v[166:169], v[174:177], v[106:109]
	v_mfma_f32_16x16x32_bf16 v[98:101], v[158:161], v[182:185], v[98:101]
	v_mfma_f32_16x16x32_bf16 v[90:93], v[166:169], v[182:185], v[90:93]
	v_mfma_f32_16x16x32_bf16 v[82:85], v[158:161], v[190:193], v[82:85]
	v_mfma_f32_16x16x32_bf16 v[74:77], v[166:169], v[190:193], v[74:77]
	v_mfma_f32_16x16x32_bf16 v[70:73], v[158:161], v[198:201], v[70:73]
	v_mfma_f32_16x16x32_bf16 v[62:65], v[166:169], v[198:201], v[62:65]
	s_setprio 0
	s_barrier
	s_mov_b32 m0, s82
	ds_read_b128 v[170:173], v137 offset:16384
	ds_read_b128 v[174:177], v137 offset:17408
	ds_read_b128 v[178:181], v137 offset:18432
	ds_read_b128 v[182:185], v137 offset:19456
	ds_read_b128 v[186:189], v137 offset:20480
	ds_read_b128 v[190:193], v137 offset:21504
	ds_read_b128 v[194:197], v137 offset:22528
	ds_read_b128 v[198:201], v137 offset:23552
	s_nop 0
	global_load_lds_dwordx4 v131, s[46:47]
	s_mov_b32 m0, s76
	s_nop 0
	global_load_lds_dwordx4 v133, s[46:47]
	s_mov_b32 m0, s77
	s_nop 0
	global_load_lds_dwordx4 v131, s[58:59]
	s_mov_b32 m0, s75
	s_nop 0
	global_load_lds_dwordx4 v133, s[58:59]
	s_mov_b32 m0, s41
	s_nop 0
	global_load_lds_dwordx4 v130, s[22:23]
	s_mov_b32 m0, s42
	s_nop 0
	global_load_lds_dwordx4 v132, s[22:23]
	s_waitcnt vmcnt(8)
	s_waitcnt lgkmcnt(0)
	s_barrier
	s_setprio 1
	s_waitcnt lgkmcnt(0)
	v_mfma_f32_16x16x32_bf16 v[66:69], v[138:141], v[170:173], v[66:69]
	v_mfma_f32_16x16x32_bf16 v[58:61], v[146:149], v[170:173], v[58:61]
	v_mfma_f32_16x16x32_bf16 v[54:57], v[138:141], v[178:181], v[54:57]
	v_mfma_f32_16x16x32_bf16 v[46:49], v[146:149], v[178:181], v[46:49]
	v_mfma_f32_16x16x32_bf16 v[38:41], v[138:141], v[186:189], v[38:41]
	v_mfma_f32_16x16x32_bf16 v[30:33], v[146:149], v[186:189], v[30:33]
	v_mfma_f32_16x16x32_bf16 v[22:25], v[138:141], v[194:197], v[22:25]
	v_mfma_f32_16x16x32_bf16 v[14:17], v[146:149], v[194:197], v[14:17]
	v_mfma_f32_16x16x32_bf16 v[66:69], v[142:145], v[174:177], v[66:69]
	v_mfma_f32_16x16x32_bf16 v[58:61], v[150:153], v[174:177], v[58:61]
	v_mfma_f32_16x16x32_bf16 v[54:57], v[142:145], v[182:185], v[54:57]
	v_mfma_f32_16x16x32_bf16 v[46:49], v[150:153], v[182:185], v[46:49]
	v_mfma_f32_16x16x32_bf16 v[38:41], v[142:145], v[190:193], v[38:41]
	v_mfma_f32_16x16x32_bf16 v[30:33], v[150:153], v[190:193], v[30:33]
	v_mfma_f32_16x16x32_bf16 v[22:25], v[142:145], v[198:201], v[22:25]
	v_mfma_f32_16x16x32_bf16 v[14:17], v[150:153], v[198:201], v[14:17]
	s_setprio 0
	s_setprio 1
	v_mfma_f32_16x16x32_bf16 v[50:53], v[154:157], v[170:173], v[50:53]
	v_mfma_f32_16x16x32_bf16 v[42:45], v[162:165], v[170:173], v[42:45]
	v_mfma_f32_16x16x32_bf16 v[34:37], v[154:157], v[178:181], v[34:37]
	v_mfma_f32_16x16x32_bf16 v[26:29], v[162:165], v[178:181], v[26:29]
	v_mfma_f32_16x16x32_bf16 v[18:21], v[154:157], v[186:189], v[18:21]
	v_mfma_f32_16x16x32_bf16 v[10:13], v[162:165], v[186:189], v[10:13]
	v_mfma_f32_16x16x32_bf16 v[6:9], v[154:157], v[194:197], v[6:9]
	v_mfma_f32_16x16x32_bf16 v[2:5], v[162:165], v[194:197], v[2:5]
	v_mfma_f32_16x16x32_bf16 v[50:53], v[158:161], v[174:177], v[50:53]
	v_mfma_f32_16x16x32_bf16 v[42:45], v[166:169], v[174:177], v[42:45]
	v_mfma_f32_16x16x32_bf16 v[34:37], v[158:161], v[182:185], v[34:37]
	v_mfma_f32_16x16x32_bf16 v[26:29], v[166:169], v[182:185], v[26:29]
	v_mfma_f32_16x16x32_bf16 v[18:21], v[158:161], v[190:193], v[18:21]
	v_mfma_f32_16x16x32_bf16 v[10:13], v[166:169], v[190:193], v[10:13]
	v_mfma_f32_16x16x32_bf16 v[6:9], v[158:161], v[198:201], v[6:9]
	v_mfma_f32_16x16x32_bf16 v[2:5], v[166:169], v[198:201], v[2:5]
	s_setprio 0
	s_barrier
	ds_read_b128 v[138:141], v0 offset:32768
	ds_read_b128 v[142:145], v0 offset:33792
	ds_read_b128 v[146:149], v0 offset:34816
	ds_read_b128 v[150:153], v0 offset:35840
	ds_read_b128 v[154:157], v0 offset:49152
	ds_read_b128 v[158:161], v0 offset:50176
	ds_read_b128 v[162:165], v0 offset:51200
	ds_read_b128 v[166:169], v0 offset:52224
	s_mov_b32 m0, s43
	ds_read_b128 v[170:173], v137 offset:32768
	ds_read_b128 v[174:177], v137 offset:33792
	ds_read_b128 v[178:181], v137 offset:34816
	ds_read_b128 v[182:185], v137 offset:35840
	ds_read_b128 v[186:189], v137 offset:36864
	ds_read_b128 v[190:193], v137 offset:37888
	ds_read_b128 v[194:197], v137 offset:38912
	ds_read_b128 v[198:201], v137 offset:39936
	s_nop 0
	global_load_lds_dwordx4 v130, s[50:51]
	s_mov_b32 m0, s64
	s_nop 0
	global_load_lds_dwordx4 v132, s[50:51]
	s_waitcnt vmcnt(8)
	s_waitcnt lgkmcnt(0)
	s_barrier
	s_setprio 1
	s_waitcnt lgkmcnt(0)
	v_mfma_f32_16x16x32_bf16 v[126:129], v[138:141], v[170:173], v[126:129]
	v_mfma_f32_16x16x32_bf16 v[122:125], v[146:149], v[170:173], v[122:125]
	v_mfma_f32_16x16x32_bf16 v[118:121], v[138:141], v[178:181], v[118:121]
	v_mfma_f32_16x16x32_bf16 v[110:113], v[146:149], v[178:181], v[110:113]
	v_mfma_f32_16x16x32_bf16 v[102:105], v[138:141], v[186:189], v[102:105]
	v_mfma_f32_16x16x32_bf16 v[94:97], v[146:149], v[186:189], v[94:97]
	v_mfma_f32_16x16x32_bf16 v[86:89], v[138:141], v[194:197], v[86:89]
	v_mfma_f32_16x16x32_bf16 v[78:81], v[146:149], v[194:197], v[78:81]
	v_mfma_f32_16x16x32_bf16 v[126:129], v[142:145], v[174:177], v[126:129]
	v_mfma_f32_16x16x32_bf16 v[122:125], v[150:153], v[174:177], v[122:125]
	v_mfma_f32_16x16x32_bf16 v[118:121], v[142:145], v[182:185], v[118:121]
	v_mfma_f32_16x16x32_bf16 v[110:113], v[150:153], v[182:185], v[110:113]
	v_mfma_f32_16x16x32_bf16 v[102:105], v[142:145], v[190:193], v[102:105]
	v_mfma_f32_16x16x32_bf16 v[94:97], v[150:153], v[190:193], v[94:97]
	v_mfma_f32_16x16x32_bf16 v[86:89], v[142:145], v[198:201], v[86:89]
	v_mfma_f32_16x16x32_bf16 v[78:81], v[150:153], v[198:201], v[78:81]
	s_setprio 0
	s_setprio 1
	v_mfma_f32_16x16x32_bf16 v[114:117], v[154:157], v[170:173], v[114:117]
	v_mfma_f32_16x16x32_bf16 v[106:109], v[162:165], v[170:173], v[106:109]
	v_mfma_f32_16x16x32_bf16 v[98:101], v[154:157], v[178:181], v[98:101]
	v_mfma_f32_16x16x32_bf16 v[90:93], v[162:165], v[178:181], v[90:93]
	v_mfma_f32_16x16x32_bf16 v[82:85], v[154:157], v[186:189], v[82:85]
	v_mfma_f32_16x16x32_bf16 v[74:77], v[162:165], v[186:189], v[74:77]
	v_mfma_f32_16x16x32_bf16 v[70:73], v[154:157], v[194:197], v[70:73]
	v_mfma_f32_16x16x32_bf16 v[62:65], v[162:165], v[194:197], v[62:65]
	v_mfma_f32_16x16x32_bf16 v[114:117], v[158:161], v[174:177], v[114:117]
	v_mfma_f32_16x16x32_bf16 v[106:109], v[166:169], v[174:177], v[106:109]
	v_mfma_f32_16x16x32_bf16 v[98:101], v[158:161], v[182:185], v[98:101]
	v_mfma_f32_16x16x32_bf16 v[90:93], v[166:169], v[182:185], v[90:93]
	v_mfma_f32_16x16x32_bf16 v[82:85], v[158:161], v[190:193], v[82:85]
	v_mfma_f32_16x16x32_bf16 v[74:77], v[166:169], v[190:193], v[74:77]
	v_mfma_f32_16x16x32_bf16 v[70:73], v[158:161], v[198:201], v[70:73]
	v_mfma_f32_16x16x32_bf16 v[62:65], v[166:169], v[198:201], v[62:65]
	s_setprio 0
	s_barrier
	ds_read_b128 v[170:173], v137 offset:49152
	ds_read_b128 v[174:177], v137 offset:50176
	ds_read_b128 v[178:181], v137 offset:51200
	ds_read_b128 v[182:185], v137 offset:52224
	ds_read_b128 v[186:189], v137 offset:53248
	ds_read_b128 v[190:193], v137 offset:54272
	ds_read_b128 v[194:197], v137 offset:55296
	ds_read_b128 v[198:201], v137 offset:56320
	s_mov_b32 m0, s70
	s_add_u32 s100, s46, s38
	s_addc_u32 s101, s47, s39
	global_load_lds_dwordx4 v131, s[100:101]
	s_mov_b32 m0, s69
	s_nop 0
	global_load_lds_dwordx4 v133, s[100:101]
	s_mov_b32 m0, s79
	s_nop 0
	global_load_lds_dwordx4 v131, s[48:49]
	s_mov_b32 m0, s78
	s_nop 0
	global_load_lds_dwordx4 v133, s[48:49]
	s_mov_b32 m0, s67
	s_add_u32 s100, s22, s38
	s_addc_u32 s101, s23, s39
	v_mov_b32_e32 v0, v132
	global_load_lds_dwordx4 v130, s[100:101]
	s_mov_b32 m0, s68
	s_nop 0
	global_load_lds_dwordx4 v132, s[100:101]
	s_waitcnt vmcnt(8)
	s_waitcnt lgkmcnt(0)
	s_barrier
	s_setprio 1
	s_waitcnt lgkmcnt(0)
	v_mfma_f32_16x16x32_bf16 v[66:69], v[138:141], v[170:173], v[66:69]
	v_mfma_f32_16x16x32_bf16 v[58:61], v[146:149], v[170:173], v[58:61]
	v_mfma_f32_16x16x32_bf16 v[54:57], v[138:141], v[178:181], v[54:57]
	v_mfma_f32_16x16x32_bf16 v[46:49], v[146:149], v[178:181], v[46:49]
	v_mfma_f32_16x16x32_bf16 v[38:41], v[138:141], v[186:189], v[38:41]
	v_mfma_f32_16x16x32_bf16 v[30:33], v[146:149], v[186:189], v[30:33]
	v_mfma_f32_16x16x32_bf16 v[22:25], v[138:141], v[194:197], v[22:25]
	v_mfma_f32_16x16x32_bf16 v[14:17], v[146:149], v[194:197], v[14:17]
	v_mfma_f32_16x16x32_bf16 v[66:69], v[142:145], v[174:177], v[66:69]
	v_mfma_f32_16x16x32_bf16 v[58:61], v[150:153], v[174:177], v[58:61]
	v_mfma_f32_16x16x32_bf16 v[54:57], v[142:145], v[182:185], v[54:57]
	v_mfma_f32_16x16x32_bf16 v[46:49], v[150:153], v[182:185], v[46:49]
	v_mfma_f32_16x16x32_bf16 v[38:41], v[142:145], v[190:193], v[38:41]
	v_mfma_f32_16x16x32_bf16 v[30:33], v[150:153], v[190:193], v[30:33]
	v_mfma_f32_16x16x32_bf16 v[22:25], v[142:145], v[198:201], v[22:25]
	v_mfma_f32_16x16x32_bf16 v[14:17], v[150:153], v[198:201], v[14:17]
	s_setprio 0
	s_setprio 1
	v_mfma_f32_16x16x32_bf16 v[50:53], v[154:157], v[170:173], v[50:53]
	v_mfma_f32_16x16x32_bf16 v[42:45], v[162:165], v[170:173], v[42:45]
	v_mfma_f32_16x16x32_bf16 v[34:37], v[154:157], v[178:181], v[34:37]
	v_mfma_f32_16x16x32_bf16 v[26:29], v[162:165], v[178:181], v[26:29]
	v_mfma_f32_16x16x32_bf16 v[18:21], v[154:157], v[186:189], v[18:21]
	v_mfma_f32_16x16x32_bf16 v[10:13], v[162:165], v[186:189], v[10:13]
	v_mfma_f32_16x16x32_bf16 v[6:9], v[154:157], v[194:197], v[6:9]
	v_mfma_f32_16x16x32_bf16 v[2:5], v[162:165], v[194:197], v[2:5]
	v_mfma_f32_16x16x32_bf16 v[50:53], v[158:161], v[174:177], v[50:53]
	v_mfma_f32_16x16x32_bf16 v[42:45], v[166:169], v[174:177], v[42:45]
	v_mfma_f32_16x16x32_bf16 v[34:37], v[158:161], v[182:185], v[34:37]
	v_mfma_f32_16x16x32_bf16 v[26:29], v[166:169], v[182:185], v[26:29]
	v_mfma_f32_16x16x32_bf16 v[18:21], v[158:161], v[190:193], v[18:21]
	v_mfma_f32_16x16x32_bf16 v[10:13], v[166:169], v[190:193], v[10:13]
	v_mfma_f32_16x16x32_bf16 v[6:9], v[158:161], v[198:201], v[6:9]
	v_mfma_f32_16x16x32_bf16 v[2:5], v[166:169], v[198:201], v[2:5]
	s_setprio 0
	s_barrier
	s_andn2_b64 vcc, exec, s[16:17]
	s_mov_b64 s[46:47], -1
	s_mov_b64 s[16:17], 0
	s_mov_b64 s[48:49], 0x100
	s_cbranch_vccz .LBB0_634
	s_cmpk_lt_u32 s25, 0x100
	s_cbranch_scc0 .LBB0_637
	s_barrier

.LBB0_667:
	s_add_u32 s4, s70, s50
	s_addc_u32 s5, s71, s51
	s_add_u32 s46, s4, 0x9400100
	s_addc_u32 s47, s5, 0
	s_add_u32 s58, s74, s50
	s_addc_u32 s59, s75, s51
	s_add_i32 s77, 0, 0x10000
	s_cmpk_eq_i32 s50, 0x300
	s_cselect_b32 s47, s23, s47
	s_cselect_b32 s46, s22, s46
	v_add_u32_e32 v0, s77, v144
	s_cselect_b32 s59, s49, s59
	s_cselect_b32 s58, s48, s58
	s_add_i32 s78, 0, 0x14000
	ds_read_b128 v[146:149], v0
	ds_read_b128 v[150:153], v0 offset:1024
	ds_read_b128 v[154:157], v0 offset:2048
	ds_read_b128 v[158:161], v0 offset:3072
	ds_read_b128 v[162:165], v0 offset:16384
	ds_read_b128 v[166:169], v0 offset:17408
	ds_read_b128 v[170:173], v0 offset:18432
	ds_read_b128 v[174:177], v0 offset:19456
	ds_read_b128 v[178:181], v145
	ds_read_b128 v[182:185], v145 offset:1024
	ds_read_b128 v[186:189], v145 offset:2048
	ds_read_b128 v[190:193], v145 offset:3072
	ds_read_b128 v[194:197], v145 offset:4096
	ds_read_b128 v[198:201], v145 offset:5120
	ds_read_b128 v[202:205], v145 offset:6144
	ds_read_b128 v[206:209], v145 offset:7168
	s_add_i32 m0, s61, 0xc000
	s_add_u32 s100, s4, s54
	s_addc_u32 s101, s5, s55
	global_load_lds_dwordx4 v130, s[100:101]
	s_add_i32 m0, s61, 0xe000
	s_nop 0
	global_load_lds_dwordx4 v141, s[100:101]
	s_waitcnt vmcnt(8)
	s_waitcnt lgkmcnt(0)
	s_barrier
	s_setprio 1
	s_waitcnt lgkmcnt(0)
	v_mfma_i32_16x16x64_i8 v[126:129], v[146:149], v[178:181], v[126:129]
	v_mfma_i32_16x16x64_i8 v[122:125], v[154:157], v[178:181], v[122:125]
	v_mfma_i32_16x16x64_i8 v[110:113], v[146:149], v[186:189], v[110:113]
	v_mfma_i32_16x16x64_i8 v[106:109], v[154:157], v[186:189], v[106:109]
	v_mfma_i32_16x16x64_i8 v[94:97], v[146:149], v[194:197], v[94:97]
	v_mfma_i32_16x16x64_i8 v[90:93], v[154:157], v[194:197], v[90:93]
	v_mfma_i32_16x16x64_i8 v[78:81], v[146:149], v[202:205], v[78:81]
	v_mfma_i32_16x16x64_i8 v[74:77], v[154:157], v[202:205], v[74:77]
	v_mfma_i32_16x16x64_i8 v[126:129], v[150:153], v[182:185], v[126:129]
	v_mfma_i32_16x16x64_i8 v[122:125], v[158:161], v[182:185], v[122:125]
	v_mfma_i32_16x16x64_i8 v[110:113], v[150:153], v[190:193], v[110:113]
	v_mfma_i32_16x16x64_i8 v[106:109], v[158:161], v[190:193], v[106:109]
	v_mfma_i32_16x16x64_i8 v[94:97], v[150:153], v[198:201], v[94:97]
	v_mfma_i32_16x16x64_i8 v[90:93], v[158:161], v[198:201], v[90:93]
	v_mfma_i32_16x16x64_i8 v[78:81], v[150:153], v[206:209], v[78:81]
	v_mfma_i32_16x16x64_i8 v[74:77], v[158:161], v[206:209], v[74:77]
	s_setprio 0
	s_setprio 1
	v_mfma_i32_16x16x64_i8 v[118:121], v[162:165], v[178:181], v[118:121]
	v_mfma_i32_16x16x64_i8 v[114:117], v[170:173], v[178:181], v[114:117]
	v_mfma_i32_16x16x64_i8 v[102:105], v[162:165], v[186:189], v[102:105]
	v_mfma_i32_16x16x64_i8 v[98:101], v[170:173], v[186:189], v[98:101]
	v_mfma_i32_16x16x64_i8 v[86:89], v[162:165], v[194:197], v[86:89]
	v_mfma_i32_16x16x64_i8 v[82:85], v[170:173], v[194:197], v[82:85]
	v_mfma_i32_16x16x64_i8 v[70:73], v[162:165], v[202:205], v[70:73]
	v_mfma_i32_16x16x64_i8 v[66:69], v[170:173], v[202:205], v[66:69]
	v_mfma_i32_16x16x64_i8 v[118:121], v[166:169], v[182:185], v[118:121]
	v_mfma_i32_16x16x64_i8 v[114:117], v[174:177], v[182:185], v[114:117]
	v_mfma_i32_16x16x64_i8 v[102:105], v[166:169], v[190:193], v[102:105]
	v_mfma_i32_16x16x64_i8 v[98:101], v[174:177], v[190:193], v[98:101]
	v_mfma_i32_16x16x64_i8 v[86:89], v[166:169], v[198:201], v[86:89]
	v_mfma_i32_16x16x64_i8 v[82:85], v[174:177], v[198:201], v[82:85]
	v_mfma_i32_16x16x64_i8 v[70:73], v[166:169], v[206:209], v[70:73]
	v_mfma_i32_16x16x64_i8 v[66:69], v[174:177], v[206:209], v[66:69]
	s_setprio 0
	s_barrier
	s_add_i32 s4, s77, s60
	ds_read_b128 v[178:181], v145 offset:16384
	ds_read_b128 v[182:185], v145 offset:17408
	ds_read_b128 v[186:189], v145 offset:18432
	ds_read_b128 v[190:193], v145 offset:19456
	ds_read_b128 v[194:197], v145 offset:20480
	ds_read_b128 v[198:201], v145 offset:21504
	ds_read_b128 v[202:205], v145 offset:22528
	ds_read_b128 v[206:209], v145 offset:23552
	s_mov_b32 m0, s4
	s_nop 0
	global_load_lds_dwordx4 v131, s[58:59]
	s_add_i32 m0, s4, 0x2000
	s_add_u32 s4, s58, 0x20000
	global_load_lds_dwordx4 v142, s[58:59]
	s_addc_u32 s5, s59, 0
	s_add_i32 s77, s78, s60
	s_mov_b32 m0, s77
	s_nop 0
	global_load_lds_dwordx4 v131, s[4:5]
	s_add_i32 m0, s77, 0x2000
	s_nop 0
	global_load_lds_dwordx4 v142, s[4:5]
	s_mov_b32 m0, s61
	s_nop 0
	global_load_lds_dwordx4 v130, s[46:47]
	s_mov_b32 m0, s65
	s_nop 0
	global_load_lds_dwordx4 v141, s[46:47]
	s_waitcnt vmcnt(8)
	s_waitcnt lgkmcnt(0)
	s_barrier
	s_setprio 1
	s_waitcnt lgkmcnt(0)
	v_mfma_i32_16x16x64_i8 v[62:65], v[146:149], v[178:181], v[62:65]
	v_mfma_i32_16x16x64_i8 v[58:61], v[154:157], v[178:181], v[58:61]
	v_mfma_i32_16x16x64_i8 v[46:49], v[146:149], v[186:189], v[46:49]
	v_mfma_i32_16x16x64_i8 v[42:45], v[154:157], v[186:189], v[42:45]
	v_mfma_i32_16x16x64_i8 v[30:33], v[146:149], v[194:197], v[30:33]
	v_mfma_i32_16x16x64_i8 v[26:29], v[154:157], v[194:197], v[26:29]
	v_mfma_i32_16x16x64_i8 v[14:17], v[146:149], v[202:205], v[14:17]
	v_mfma_i32_16x16x64_i8 v[10:13], v[154:157], v[202:205], v[10:13]
	v_mfma_i32_16x16x64_i8 v[62:65], v[150:153], v[182:185], v[62:65]
	v_mfma_i32_16x16x64_i8 v[58:61], v[158:161], v[182:185], v[58:61]
	v_mfma_i32_16x16x64_i8 v[46:49], v[150:153], v[190:193], v[46:49]
	v_mfma_i32_16x16x64_i8 v[42:45], v[158:161], v[190:193], v[42:45]
	v_mfma_i32_16x16x64_i8 v[30:33], v[150:153], v[198:201], v[30:33]
	v_mfma_i32_16x16x64_i8 v[26:29], v[158:161], v[198:201], v[26:29]
	v_mfma_i32_16x16x64_i8 v[14:17], v[150:153], v[206:209], v[14:17]
	v_mfma_i32_16x16x64_i8 v[10:13], v[158:161], v[206:209], v[10:13]
	s_setprio 0
	s_setprio 1
	v_mfma_i32_16x16x64_i8 v[54:57], v[162:165], v[178:181], v[54:57]
	v_mfma_i32_16x16x64_i8 v[50:53], v[170:173], v[178:181], v[50:53]
	v_mfma_i32_16x16x64_i8 v[38:41], v[162:165], v[186:189], v[38:41]
	v_mfma_i32_16x16x64_i8 v[34:37], v[170:173], v[186:189], v[34:37]
	v_mfma_i32_16x16x64_i8 v[22:25], v[162:165], v[194:197], v[22:25]
	v_mfma_i32_16x16x64_i8 v[18:21], v[170:173], v[194:197], v[18:21]
	v_mfma_i32_16x16x64_i8 v[6:9], v[162:165], v[202:205], v[6:9]
	v_mfma_i32_16x16x64_i8 v[2:5], v[170:173], v[202:205], v[2:5]
	v_mfma_i32_16x16x64_i8 v[54:57], v[166:169], v[182:185], v[54:57]
	v_mfma_i32_16x16x64_i8 v[50:53], v[174:177], v[182:185], v[50:53]
	v_mfma_i32_16x16x64_i8 v[38:41], v[166:169], v[190:193], v[38:41]
	v_mfma_i32_16x16x64_i8 v[34:37], v[174:177], v[190:193], v[34:37]
	v_mfma_i32_16x16x64_i8 v[22:25], v[166:169], v[198:201], v[22:25]
	v_mfma_i32_16x16x64_i8 v[18:21], v[174:177], v[198:201], v[18:21]
	v_mfma_i32_16x16x64_i8 v[6:9], v[166:169], v[206:209], v[6:9]
	v_mfma_i32_16x16x64_i8 v[2:5], v[174:177], v[206:209], v[2:5]
	s_setprio 0
	s_barrier
	s_add_i32 s77, 0, 0x18000
	s_add_i32 s78, 0, 0x1c000
	ds_read_b128 v[146:149], v0 offset:32768
	ds_read_b128 v[150:153], v0 offset:33792
	ds_read_b128 v[154:157], v0 offset:34816
	ds_read_b128 v[158:161], v0 offset:35840
	ds_read_b128 v[162:165], v0 offset:49152
	ds_read_b128 v[166:169], v0 offset:50176
	ds_read_b128 v[170:173], v0 offset:51200
	ds_read_b128 v[174:177], v0 offset:52224
	s_add_u32 s4, s46, 0x20000
	s_mov_b32 m0, s66
	ds_read_b128 v[178:181], v145 offset:32768
	ds_read_b128 v[182:185], v145 offset:33792
	ds_read_b128 v[186:189], v145 offset:34816
	ds_read_b128 v[190:193], v145 offset:35840
	ds_read_b128 v[194:197], v145 offset:36864
	ds_read_b128 v[198:201], v145 offset:37888
	ds_read_b128 v[202:205], v145 offset:38912
	ds_read_b128 v[206:209], v145 offset:39936
	s_addc_u32 s5, s47, 0
	s_nop 0
	global_load_lds_dwordx4 v130, s[4:5]
	s_mov_b32 m0, s67
	s_nop 0
	global_load_lds_dwordx4 v141, s[4:5]
	s_waitcnt vmcnt(8)
	s_waitcnt lgkmcnt(0)
	s_barrier
	s_setprio 1
	s_waitcnt lgkmcnt(0)
	v_mfma_i32_16x16x64_i8 v[126:129], v[146:149], v[178:181], v[126:129]
	v_mfma_i32_16x16x64_i8 v[122:125], v[154:157], v[178:181], v[122:125]
	v_mfma_i32_16x16x64_i8 v[110:113], v[146:149], v[186:189], v[110:113]
	v_mfma_i32_16x16x64_i8 v[106:109], v[154:157], v[186:189], v[106:109]
	v_mfma_i32_16x16x64_i8 v[94:97], v[146:149], v[194:197], v[94:97]
	v_mfma_i32_16x16x64_i8 v[90:93], v[154:157], v[194:197], v[90:93]
	v_mfma_i32_16x16x64_i8 v[78:81], v[146:149], v[202:205], v[78:81]
	v_mfma_i32_16x16x64_i8 v[74:77], v[154:157], v[202:205], v[74:77]
	v_mfma_i32_16x16x64_i8 v[126:129], v[150:153], v[182:185], v[126:129]
	v_mfma_i32_16x16x64_i8 v[122:125], v[158:161], v[182:185], v[122:125]
	v_mfma_i32_16x16x64_i8 v[110:113], v[150:153], v[190:193], v[110:113]
	v_mfma_i32_16x16x64_i8 v[106:109], v[158:161], v[190:193], v[106:109]
	v_mfma_i32_16x16x64_i8 v[94:97], v[150:153], v[198:201], v[94:97]
	v_mfma_i32_16x16x64_i8 v[90:93], v[158:161], v[198:201], v[90:93]
	v_mfma_i32_16x16x64_i8 v[78:81], v[150:153], v[206:209], v[78:81]
	v_mfma_i32_16x16x64_i8 v[74:77], v[158:161], v[206:209], v[74:77]
	s_setprio 0
	s_setprio 1
	v_mfma_i32_16x16x64_i8 v[118:121], v[162:165], v[178:181], v[118:121]
	v_mfma_i32_16x16x64_i8 v[114:117], v[170:173], v[178:181], v[114:117]
	v_mfma_i32_16x16x64_i8 v[102:105], v[162:165], v[186:189], v[102:105]
	v_mfma_i32_16x16x64_i8 v[98:101], v[170:173], v[186:189], v[98:101]
	v_mfma_i32_16x16x64_i8 v[86:89], v[162:165], v[194:197], v[86:89]
	v_mfma_i32_16x16x64_i8 v[82:85], v[170:173], v[194:197], v[82:85]
	v_mfma_i32_16x16x64_i8 v[70:73], v[162:165], v[202:205], v[70:73]
	v_mfma_i32_16x16x64_i8 v[66:69], v[170:173], v[202:205], v[66:69]
	v_mfma_i32_16x16x64_i8 v[118:121], v[166:169], v[182:185], v[118:121]
	v_mfma_i32_16x16x64_i8 v[114:117], v[174:177], v[182:185], v[114:117]
	v_mfma_i32_16x16x64_i8 v[102:105], v[166:169], v[190:193], v[102:105]
	v_mfma_i32_16x16x64_i8 v[98:101], v[174:177], v[190:193], v[98:101]
	v_mfma_i32_16x16x64_i8 v[86:89], v[166:169], v[198:201], v[86:89]
	v_mfma_i32_16x16x64_i8 v[82:85], v[174:177], v[198:201], v[82:85]
	v_mfma_i32_16x16x64_i8 v[70:73], v[166:169], v[206:209], v[70:73]
	v_mfma_i32_16x16x64_i8 v[66:69], v[174:177], v[206:209], v[66:69]
	s_setprio 0
	s_barrier
	ds_read_b128 v[178:181], v145 offset:49152
	ds_read_b128 v[182:185], v145 offset:50176
	ds_read_b128 v[186:189], v145 offset:51200
	ds_read_b128 v[190:193], v145 offset:52224
	ds_read_b128 v[194:197], v145 offset:53248
	ds_read_b128 v[198:201], v145 offset:54272
	ds_read_b128 v[202:205], v145 offset:55296
	ds_read_b128 v[206:209], v145 offset:56320
	s_add_i32 s4, s77, s60
	s_add_u32 s100, s58, s38
	s_addc_u32 s101, s59, s39
	s_mov_b32 m0, s4
	s_nop 0
	global_load_lds_dwordx4 v131, s[100:101]
	s_add_i32 m0, s4, 0x2000
	s_add_u32 s4, s58, 0x20080
	s_addc_u32 s5, s59, 0
	s_add_i32 s58, s78, s60
	global_load_lds_dwordx4 v142, s[100:101]
	s_mov_b32 m0, s58
	s_nop 0
	global_load_lds_dwordx4 v131, s[4:5]
	s_add_i32 m0, s58, 0x2000
	s_nop 0
	global_load_lds_dwordx4 v142, s[4:5]
	s_mov_b32 m0, s68
	s_add_u32 s100, s46, s38
	s_addc_u32 s101, s47, s39
	v_mov_b32_e32 v0, v141
	global_load_lds_dwordx4 v130, s[100:101]
	s_mov_b32 m0, s69
	s_nop 0
	global_load_lds_dwordx4 v141, s[100:101]
	s_waitcnt vmcnt(8)
	s_waitcnt lgkmcnt(0)
	s_barrier
	s_setprio 1
	s_waitcnt lgkmcnt(0)
	v_mfma_i32_16x16x64_i8 v[62:65], v[146:149], v[178:181], v[62:65]
	v_mfma_i32_16x16x64_i8 v[58:61], v[154:157], v[178:181], v[58:61]
	v_mfma_i32_16x16x64_i8 v[46:49], v[146:149], v[186:189], v[46:49]
	v_mfma_i32_16x16x64_i8 v[42:45], v[154:157], v[186:189], v[42:45]
	v_mfma_i32_16x16x64_i8 v[30:33], v[146:149], v[194:197], v[30:33]
	v_mfma_i32_16x16x64_i8 v[26:29], v[154:157], v[194:197], v[26:29]
	v_mfma_i32_16x16x64_i8 v[14:17], v[146:149], v[202:205], v[14:17]
	v_mfma_i32_16x16x64_i8 v[10:13], v[154:157], v[202:205], v[10:13]
	v_mfma_i32_16x16x64_i8 v[62:65], v[150:153], v[182:185], v[62:65]
	v_mfma_i32_16x16x64_i8 v[58:61], v[158:161], v[182:185], v[58:61]
	v_mfma_i32_16x16x64_i8 v[46:49], v[150:153], v[190:193], v[46:49]
	v_mfma_i32_16x16x64_i8 v[42:45], v[158:161], v[190:193], v[42:45]
	v_mfma_i32_16x16x64_i8 v[30:33], v[150:153], v[198:201], v[30:33]
	v_mfma_i32_16x16x64_i8 v[26:29], v[158:161], v[198:201], v[26:29]
	v_mfma_i32_16x16x64_i8 v[14:17], v[150:153], v[206:209], v[14:17]
	v_mfma_i32_16x16x64_i8 v[10:13], v[158:161], v[206:209], v[10:13]
	s_setprio 0
	s_setprio 1
	v_mfma_i32_16x16x64_i8 v[54:57], v[162:165], v[178:181], v[54:57]
	v_mfma_i32_16x16x64_i8 v[50:53], v[170:173], v[178:181], v[50:53]
	v_mfma_i32_16x16x64_i8 v[38:41], v[162:165], v[186:189], v[38:41]
	v_mfma_i32_16x16x64_i8 v[34:37], v[170:173], v[186:189], v[34:37]
	v_mfma_i32_16x16x64_i8 v[22:25], v[162:165], v[194:197], v[22:25]
	v_mfma_i32_16x16x64_i8 v[18:21], v[170:173], v[194:197], v[18:21]
	v_mfma_i32_16x16x64_i8 v[6:9], v[162:165], v[202:205], v[6:9]
	v_mfma_i32_16x16x64_i8 v[2:5], v[170:173], v[202:205], v[2:5]
	v_mfma_i32_16x16x64_i8 v[54:57], v[166:169], v[182:185], v[54:57]
	v_mfma_i32_16x16x64_i8 v[50:53], v[174:177], v[182:185], v[50:53]
	v_mfma_i32_16x16x64_i8 v[38:41], v[166:169], v[190:193], v[38:41]
	v_mfma_i32_16x16x64_i8 v[34:37], v[174:177], v[190:193], v[34:37]
	v_mfma_i32_16x16x64_i8 v[22:25], v[166:169], v[198:201], v[22:25]
	v_mfma_i32_16x16x64_i8 v[18:21], v[174:177], v[198:201], v[18:21]
	v_mfma_i32_16x16x64_i8 v[6:9], v[166:169], v[206:209], v[6:9]
	v_mfma_i32_16x16x64_i8 v[2:5], v[174:177], v[206:209], v[2:5]
	s_setprio 0
	s_barrier
	s_add_i32 s76, s76, 2
	s_add_u32 s50, s50, 0x100
	s_addc_u32 s51, s51, 0
	s_cmp_gt_u32 s76, 5
	s_cbranch_scc0 .LBB0_667
	s_cmpk_lt_u32 s17, 0x100
	s_cbranch_scc0 .LBB0_661
	s_barrier
	s_branch .LBB0_661

.LBB0_821:
	s_add_u32 s4, s79, s50
	s_addc_u32 s5, s82, s51
	s_add_u32 s46, s4, 0x9800100
	s_addc_u32 s47, s5, 0
	s_add_u32 s58, s64, s50
	s_addc_u32 s59, s83, s51
	s_add_i32 s85, 0, 0x10000
	s_cmpk_eq_i32 s50, 0x1500
	s_cselect_b32 s47, s49, s47
	s_cselect_b32 s46, s48, s46
	v_add_u32_e32 v0, s85, v134
	s_cselect_b32 s59, s71, s59
	s_cselect_b32 s58, s70, s58
	s_add_i32 s86, 0, 0x14000
	ds_read_b128 v[136:139], v0
	ds_read_b128 v[140:143], v0 offset:1024
	ds_read_b128 v[144:147], v0 offset:2048
	ds_read_b128 v[148:151], v0 offset:3072
	ds_read_b128 v[152:155], v0 offset:16384
	ds_read_b128 v[156:159], v0 offset:17408
	ds_read_b128 v[160:163], v0 offset:18432
	ds_read_b128 v[164:167], v0 offset:19456
	ds_read_b128 v[168:171], v135
	ds_read_b128 v[172:175], v135 offset:1024
	ds_read_b128 v[176:179], v135 offset:2048
	ds_read_b128 v[180:183], v135 offset:3072
	ds_read_b128 v[184:187], v135 offset:4096
	ds_read_b128 v[188:191], v135 offset:5120
	ds_read_b128 v[192:195], v135 offset:6144
	ds_read_b128 v[198:201], v135 offset:7168
	s_add_i32 m0, s60, 0xc000
	s_add_u32 s100, s4, s88
	s_addc_u32 s101, s5, s89
	global_load_lds_dwordx4 v130, s[100:101]
	s_add_i32 m0, s60, 0xe000
	s_nop 0
	global_load_lds_dwordx4 v131, s[100:101]
	s_waitcnt vmcnt(8)
	s_waitcnt lgkmcnt(0)
	s_barrier
	s_setprio 1
	s_waitcnt lgkmcnt(0)
	v_mfma_f32_16x16x32_bf16 v[126:129], v[136:139], v[168:171], v[126:129]
	v_mfma_f32_16x16x32_bf16 v[122:125], v[144:147], v[168:171], v[122:125]
	v_mfma_f32_16x16x32_bf16 v[110:113], v[136:139], v[176:179], v[110:113]
	v_mfma_f32_16x16x32_bf16 v[106:109], v[144:147], v[176:179], v[106:109]
	v_mfma_f32_16x16x32_bf16 v[94:97], v[136:139], v[184:187], v[94:97]
	v_mfma_f32_16x16x32_bf16 v[90:93], v[144:147], v[184:187], v[90:93]
	v_mfma_f32_16x16x32_bf16 v[78:81], v[136:139], v[192:195], v[78:81]
	v_mfma_f32_16x16x32_bf16 v[74:77], v[144:147], v[192:195], v[74:77]
	v_mfma_f32_16x16x32_bf16 v[126:129], v[140:143], v[172:175], v[126:129]
	v_mfma_f32_16x16x32_bf16 v[122:125], v[148:151], v[172:175], v[122:125]
	v_mfma_f32_16x16x32_bf16 v[110:113], v[140:143], v[180:183], v[110:113]
	v_mfma_f32_16x16x32_bf16 v[106:109], v[148:151], v[180:183], v[106:109]
	v_mfma_f32_16x16x32_bf16 v[94:97], v[140:143], v[188:191], v[94:97]
	v_mfma_f32_16x16x32_bf16 v[90:93], v[148:151], v[188:191], v[90:93]
	v_mfma_f32_16x16x32_bf16 v[78:81], v[140:143], v[198:201], v[78:81]
	v_mfma_f32_16x16x32_bf16 v[74:77], v[148:151], v[198:201], v[74:77]
	s_setprio 0
	s_setprio 1
	v_mfma_f32_16x16x32_bf16 v[118:121], v[152:155], v[168:171], v[118:121]
	v_mfma_f32_16x16x32_bf16 v[114:117], v[160:163], v[168:171], v[114:117]
	v_mfma_f32_16x16x32_bf16 v[102:105], v[152:155], v[176:179], v[102:105]
	v_mfma_f32_16x16x32_bf16 v[98:101], v[160:163], v[176:179], v[98:101]
	v_mfma_f32_16x16x32_bf16 v[86:89], v[152:155], v[184:187], v[86:89]
	v_mfma_f32_16x16x32_bf16 v[82:85], v[160:163], v[184:187], v[82:85]
	v_mfma_f32_16x16x32_bf16 v[70:73], v[152:155], v[192:195], v[70:73]
	v_mfma_f32_16x16x32_bf16 v[66:69], v[160:163], v[192:195], v[66:69]
	v_mfma_f32_16x16x32_bf16 v[118:121], v[156:159], v[172:175], v[118:121]
	v_mfma_f32_16x16x32_bf16 v[114:117], v[164:167], v[172:175], v[114:117]
	v_mfma_f32_16x16x32_bf16 v[102:105], v[156:159], v[180:183], v[102:105]
	v_mfma_f32_16x16x32_bf16 v[98:101], v[164:167], v[180:183], v[98:101]
	v_mfma_f32_16x16x32_bf16 v[86:89], v[156:159], v[188:191], v[86:89]
	v_mfma_f32_16x16x32_bf16 v[82:85], v[164:167], v[188:191], v[82:85]
	v_mfma_f32_16x16x32_bf16 v[70:73], v[156:159], v[198:201], v[70:73]
	v_mfma_f32_16x16x32_bf16 v[66:69], v[164:167], v[198:201], v[66:69]
	s_setprio 0
	s_barrier
	s_add_i32 s4, s85, s26
	ds_read_b128 v[168:171], v135 offset:16384
	ds_read_b128 v[172:175], v135 offset:17408
	ds_read_b128 v[176:179], v135 offset:18432
	ds_read_b128 v[180:183], v135 offset:19456
	ds_read_b128 v[184:187], v135 offset:20480
	ds_read_b128 v[188:191], v135 offset:21504
	ds_read_b128 v[192:195], v135 offset:22528
	ds_read_b128 v[198:201], v135 offset:23552
	s_mov_b32 m0, s4
	s_nop 0
	global_load_lds_dwordx4 v132, s[58:59]
	s_add_i32 m0, s4, 0x2000
	s_add_u32 s4, s58, 0xb0000
	global_load_lds_dwordx4 v133, s[58:59]
	s_addc_u32 s5, s59, 0
	s_add_i32 s85, s86, s26
	s_mov_b32 m0, s85
	s_nop 0
	global_load_lds_dwordx4 v132, s[4:5]
	s_add_i32 m0, s85, 0x2000
	s_nop 0
	global_load_lds_dwordx4 v133, s[4:5]
	s_mov_b32 m0, s60
	s_nop 0
	global_load_lds_dwordx4 v130, s[46:47]
	s_mov_b32 m0, s65
	s_nop 0
	global_load_lds_dwordx4 v131, s[46:47]
	s_waitcnt vmcnt(8)
	s_waitcnt lgkmcnt(0)
	s_barrier
	s_setprio 1
	s_waitcnt lgkmcnt(0)
	v_mfma_f32_16x16x32_bf16 v[62:65], v[136:139], v[168:171], v[62:65]
	v_mfma_f32_16x16x32_bf16 v[58:61], v[144:147], v[168:171], v[58:61]
	v_mfma_f32_16x16x32_bf16 v[46:49], v[136:139], v[176:179], v[46:49]
	v_mfma_f32_16x16x32_bf16 v[42:45], v[144:147], v[176:179], v[42:45]
	v_mfma_f32_16x16x32_bf16 v[30:33], v[136:139], v[184:187], v[30:33]
	v_mfma_f32_16x16x32_bf16 v[26:29], v[144:147], v[184:187], v[26:29]
	v_mfma_f32_16x16x32_bf16 v[14:17], v[136:139], v[192:195], v[14:17]
	v_mfma_f32_16x16x32_bf16 v[10:13], v[144:147], v[192:195], v[10:13]
	v_mfma_f32_16x16x32_bf16 v[62:65], v[140:143], v[172:175], v[62:65]
	v_mfma_f32_16x16x32_bf16 v[58:61], v[148:151], v[172:175], v[58:61]
	v_mfma_f32_16x16x32_bf16 v[46:49], v[140:143], v[180:183], v[46:49]
	v_mfma_f32_16x16x32_bf16 v[42:45], v[148:151], v[180:183], v[42:45]
	v_mfma_f32_16x16x32_bf16 v[30:33], v[140:143], v[188:191], v[30:33]
	v_mfma_f32_16x16x32_bf16 v[26:29], v[148:151], v[188:191], v[26:29]
	v_mfma_f32_16x16x32_bf16 v[14:17], v[140:143], v[198:201], v[14:17]
	v_mfma_f32_16x16x32_bf16 v[10:13], v[148:151], v[198:201], v[10:13]
	s_setprio 0
	s_setprio 1
	v_mfma_f32_16x16x32_bf16 v[54:57], v[152:155], v[168:171], v[54:57]
	v_mfma_f32_16x16x32_bf16 v[50:53], v[160:163], v[168:171], v[50:53]
	v_mfma_f32_16x16x32_bf16 v[38:41], v[152:155], v[176:179], v[38:41]
	v_mfma_f32_16x16x32_bf16 v[34:37], v[160:163], v[176:179], v[34:37]
	v_mfma_f32_16x16x32_bf16 v[22:25], v[152:155], v[184:187], v[22:25]
	v_mfma_f32_16x16x32_bf16 v[18:21], v[160:163], v[184:187], v[18:21]
	v_mfma_f32_16x16x32_bf16 v[6:9], v[152:155], v[192:195], v[6:9]
	v_mfma_f32_16x16x32_bf16 v[2:5], v[160:163], v[192:195], v[2:5]
	v_mfma_f32_16x16x32_bf16 v[54:57], v[156:159], v[172:175], v[54:57]
	v_mfma_f32_16x16x32_bf16 v[50:53], v[164:167], v[172:175], v[50:53]
	v_mfma_f32_16x16x32_bf16 v[38:41], v[156:159], v[180:183], v[38:41]
	v_mfma_f32_16x16x32_bf16 v[34:37], v[164:167], v[180:183], v[34:37]
	v_mfma_f32_16x16x32_bf16 v[22:25], v[156:159], v[188:191], v[22:25]
	v_mfma_f32_16x16x32_bf16 v[18:21], v[164:167], v[188:191], v[18:21]
	v_mfma_f32_16x16x32_bf16 v[6:9], v[156:159], v[198:201], v[6:9]
	v_mfma_f32_16x16x32_bf16 v[2:5], v[164:167], v[198:201], v[2:5]
	s_setprio 0
	s_barrier
	s_add_i32 s85, 0, 0x18000
	s_add_i32 s86, 0, 0x1c000
	ds_read_b128 v[136:139], v0 offset:32768
	ds_read_b128 v[140:143], v0 offset:33792
	ds_read_b128 v[144:147], v0 offset:34816
	ds_read_b128 v[148:151], v0 offset:35840
	ds_read_b128 v[152:155], v0 offset:49152
	ds_read_b128 v[156:159], v0 offset:50176
	ds_read_b128 v[160:163], v0 offset:51200
	ds_read_b128 v[164:167], v0 offset:52224
	s_add_u32 s4, s46, 0xb0000
	s_mov_b32 m0, s68
	ds_read_b128 v[168:171], v135 offset:32768
	ds_read_b128 v[172:175], v135 offset:33792
	ds_read_b128 v[176:179], v135 offset:34816
	ds_read_b128 v[180:183], v135 offset:35840
	ds_read_b128 v[184:187], v135 offset:36864
	ds_read_b128 v[188:191], v135 offset:37888
	ds_read_b128 v[192:195], v135 offset:38912
	ds_read_b128 v[198:201], v135 offset:39936
	s_addc_u32 s5, s47, 0
	s_nop 0
	global_load_lds_dwordx4 v130, s[4:5]
	s_mov_b32 m0, s69
	s_nop 0
	global_load_lds_dwordx4 v131, s[4:5]
	s_waitcnt vmcnt(8)
	s_waitcnt lgkmcnt(0)
	s_barrier
	s_setprio 1
	s_waitcnt lgkmcnt(0)
	v_mfma_f32_16x16x32_bf16 v[126:129], v[136:139], v[168:171], v[126:129]
	v_mfma_f32_16x16x32_bf16 v[122:125], v[144:147], v[168:171], v[122:125]
	v_mfma_f32_16x16x32_bf16 v[110:113], v[136:139], v[176:179], v[110:113]
	v_mfma_f32_16x16x32_bf16 v[106:109], v[144:147], v[176:179], v[106:109]
	v_mfma_f32_16x16x32_bf16 v[94:97], v[136:139], v[184:187], v[94:97]
	v_mfma_f32_16x16x32_bf16 v[90:93], v[144:147], v[184:187], v[90:93]
	v_mfma_f32_16x16x32_bf16 v[78:81], v[136:139], v[192:195], v[78:81]
	v_mfma_f32_16x16x32_bf16 v[74:77], v[144:147], v[192:195], v[74:77]
	v_mfma_f32_16x16x32_bf16 v[126:129], v[140:143], v[172:175], v[126:129]
	v_mfma_f32_16x16x32_bf16 v[122:125], v[148:151], v[172:175], v[122:125]
	v_mfma_f32_16x16x32_bf16 v[110:113], v[140:143], v[180:183], v[110:113]
	v_mfma_f32_16x16x32_bf16 v[106:109], v[148:151], v[180:183], v[106:109]
	v_mfma_f32_16x16x32_bf16 v[94:97], v[140:143], v[188:191], v[94:97]
	v_mfma_f32_16x16x32_bf16 v[90:93], v[148:151], v[188:191], v[90:93]
	v_mfma_f32_16x16x32_bf16 v[78:81], v[140:143], v[198:201], v[78:81]
	v_mfma_f32_16x16x32_bf16 v[74:77], v[148:151], v[198:201], v[74:77]
	s_setprio 0
	s_setprio 1
	v_mfma_f32_16x16x32_bf16 v[118:121], v[152:155], v[168:171], v[118:121]
	v_mfma_f32_16x16x32_bf16 v[114:117], v[160:163], v[168:171], v[114:117]
	v_mfma_f32_16x16x32_bf16 v[102:105], v[152:155], v[176:179], v[102:105]
	v_mfma_f32_16x16x32_bf16 v[98:101], v[160:163], v[176:179], v[98:101]
	v_mfma_f32_16x16x32_bf16 v[86:89], v[152:155], v[184:187], v[86:89]
	v_mfma_f32_16x16x32_bf16 v[82:85], v[160:163], v[184:187], v[82:85]
	v_mfma_f32_16x16x32_bf16 v[70:73], v[152:155], v[192:195], v[70:73]
	v_mfma_f32_16x16x32_bf16 v[66:69], v[160:163], v[192:195], v[66:69]
	v_mfma_f32_16x16x32_bf16 v[118:121], v[156:159], v[172:175], v[118:121]
	v_mfma_f32_16x16x32_bf16 v[114:117], v[164:167], v[172:175], v[114:117]
	v_mfma_f32_16x16x32_bf16 v[102:105], v[156:159], v[180:183], v[102:105]
	v_mfma_f32_16x16x32_bf16 v[98:101], v[164:167], v[180:183], v[98:101]
	v_mfma_f32_16x16x32_bf16 v[86:89], v[156:159], v[188:191], v[86:89]
	v_mfma_f32_16x16x32_bf16 v[82:85], v[164:167], v[188:191], v[82:85]
	v_mfma_f32_16x16x32_bf16 v[70:73], v[156:159], v[198:201], v[70:73]
	v_mfma_f32_16x16x32_bf16 v[66:69], v[164:167], v[198:201], v[66:69]
	s_setprio 0
	s_barrier
	ds_read_b128 v[168:171], v135 offset:49152
	ds_read_b128 v[172:175], v135 offset:50176
	ds_read_b128 v[176:179], v135 offset:51200
	ds_read_b128 v[180:183], v135 offset:52224
	ds_read_b128 v[184:187], v135 offset:53248
	ds_read_b128 v[188:191], v135 offset:54272
	ds_read_b128 v[192:195], v135 offset:55296
	ds_read_b128 v[198:201], v135 offset:56320
	s_add_i32 s4, s85, s26
	s_add_u32 s100, s58, s38
	s_addc_u32 s101, s59, s39
	s_mov_b32 m0, s4
	s_nop 0
	global_load_lds_dwordx4 v132, s[100:101]
	s_add_i32 m0, s4, 0x2000
	s_add_u32 s4, s58, 0xb0080
	s_addc_u32 s5, s59, 0
	s_add_i32 s58, s86, s26
	global_load_lds_dwordx4 v133, s[100:101]
	s_mov_b32 m0, s58
	s_nop 0
	global_load_lds_dwordx4 v132, s[4:5]
	s_add_i32 m0, s58, 0x2000
	s_nop 0
	global_load_lds_dwordx4 v133, s[4:5]
	s_mov_b32 m0, s75
	s_add_u32 s100, s46, s38
	s_addc_u32 s101, s47, s39
	v_mov_b32_e32 v0, v131
	global_load_lds_dwordx4 v130, s[100:101]
	s_mov_b32 m0, s78
	s_nop 0
	global_load_lds_dwordx4 v131, s[100:101]
	s_waitcnt vmcnt(8)
	s_waitcnt lgkmcnt(0)
	s_barrier
	s_setprio 1
	s_waitcnt lgkmcnt(0)
	v_mfma_f32_16x16x32_bf16 v[62:65], v[136:139], v[168:171], v[62:65]
	v_mfma_f32_16x16x32_bf16 v[58:61], v[144:147], v[168:171], v[58:61]
	v_mfma_f32_16x16x32_bf16 v[46:49], v[136:139], v[176:179], v[46:49]
	v_mfma_f32_16x16x32_bf16 v[42:45], v[144:147], v[176:179], v[42:45]
	v_mfma_f32_16x16x32_bf16 v[30:33], v[136:139], v[184:187], v[30:33]
	v_mfma_f32_16x16x32_bf16 v[26:29], v[144:147], v[184:187], v[26:29]
	v_mfma_f32_16x16x32_bf16 v[14:17], v[136:139], v[192:195], v[14:17]
	v_mfma_f32_16x16x32_bf16 v[10:13], v[144:147], v[192:195], v[10:13]
	v_mfma_f32_16x16x32_bf16 v[62:65], v[140:143], v[172:175], v[62:65]
	v_mfma_f32_16x16x32_bf16 v[58:61], v[148:151], v[172:175], v[58:61]
	v_mfma_f32_16x16x32_bf16 v[46:49], v[140:143], v[180:183], v[46:49]
	v_mfma_f32_16x16x32_bf16 v[42:45], v[148:151], v[180:183], v[42:45]
	v_mfma_f32_16x16x32_bf16 v[30:33], v[140:143], v[188:191], v[30:33]
	v_mfma_f32_16x16x32_bf16 v[26:29], v[148:151], v[188:191], v[26:29]
	v_mfma_f32_16x16x32_bf16 v[14:17], v[140:143], v[198:201], v[14:17]
	v_mfma_f32_16x16x32_bf16 v[10:13], v[148:151], v[198:201], v[10:13]
	s_setprio 0
	s_setprio 1
	v_mfma_f32_16x16x32_bf16 v[54:57], v[152:155], v[168:171], v[54:57]
	v_mfma_f32_16x16x32_bf16 v[50:53], v[160:163], v[168:171], v[50:53]
	v_mfma_f32_16x16x32_bf16 v[38:41], v[152:155], v[176:179], v[38:41]
	v_mfma_f32_16x16x32_bf16 v[34:37], v[160:163], v[176:179], v[34:37]
	v_mfma_f32_16x16x32_bf16 v[22:25], v[152:155], v[184:187], v[22:25]
	v_mfma_f32_16x16x32_bf16 v[18:21], v[160:163], v[184:187], v[18:21]
	v_mfma_f32_16x16x32_bf16 v[6:9], v[152:155], v[192:195], v[6:9]
	v_mfma_f32_16x16x32_bf16 v[2:5], v[160:163], v[192:195], v[2:5]
	v_mfma_f32_16x16x32_bf16 v[54:57], v[156:159], v[172:175], v[54:57]
	v_mfma_f32_16x16x32_bf16 v[50:53], v[164:167], v[172:175], v[50:53]
	v_mfma_f32_16x16x32_bf16 v[38:41], v[156:159], v[180:183], v[38:41]
	v_mfma_f32_16x16x32_bf16 v[34:37], v[164:167], v[180:183], v[34:37]
	v_mfma_f32_16x16x32_bf16 v[22:25], v[156:159], v[188:191], v[22:25]
	v_mfma_f32_16x16x32_bf16 v[18:21], v[164:167], v[188:191], v[18:21]
	v_mfma_f32_16x16x32_bf16 v[6:9], v[156:159], v[198:201], v[6:9]
	v_mfma_f32_16x16x32_bf16 v[2:5], v[164:167], v[198:201], v[2:5]
	s_setprio 0
	s_barrier
	s_add_i32 s84, s84, 2
	s_add_u32 s50, s50, 0x100
	s_addc_u32 s51, s51, 0
	s_cmp_gt_u32 s84, 41
	s_cbranch_scc0 .LBB0_821
	s_cmpk_lt_u32 s24, 0x100
	s_cbranch_scc0 .LBB0_824
	s_barrier

.LBB0_869:
	s_add_u32 s4, s10, s2
	s_addc_u32 s5, s11, s3
	s_add_u32 s22, s4, 0x100
	s_addc_u32 s23, s5, 0
	s_add_u32 s46, s58, s2
	s_addc_u32 s47, s59, s3
	s_add_i32 s69, 0, 0x10000
	s_cmp_eq_u32 s68, 40
	s_cselect_b32 s23, s11, s23
	s_cselect_b32 s22, s10, s22
	v_add_u32_e32 v0, s69, v126
	s_cselect_b32 s47, s17, s47
	s_cselect_b32 s46, s16, s46
	s_add_i32 s70, 0, 0x14000
	ds_read_b128 v[128:131], v0
	ds_read_b128 v[142:145], v0 offset:1024
	ds_read_b128 v[146:149], v0 offset:2048
	ds_read_b128 v[150:153], v0 offset:3072
	ds_read_b128 v[154:157], v0 offset:16384
	ds_read_b128 v[160:163], v0 offset:17408
	ds_read_b128 v[164:167], v0 offset:18432
	ds_read_b128 v[168:171], v0 offset:19456
	ds_read_b128 v[172:175], v127
	ds_read_b128 v[176:179], v127 offset:1024
	ds_read_b128 v[180:183], v127 offset:2048
	ds_read_b128 v[184:187], v127 offset:3072
	ds_read_b128 v[188:191], v127 offset:4096
	ds_read_b128 v[192:195], v127 offset:5120
	ds_read_b128 v[196:199], v127 offset:6144
	ds_read_b128 v[200:203], v127 offset:7168
	s_add_i32 m0, s41, 0xc000
	s_add_u32 s100, s4, s62
	s_addc_u32 s101, s5, s63
	global_load_lds_dwordx4 v122, s[100:101]
	s_add_i32 m0, s41, 0xe000
	s_nop 0
	global_load_lds_dwordx4 v123, s[100:101]
	s_waitcnt vmcnt(8)
	s_waitcnt lgkmcnt(0)
	s_barrier
	s_setprio 1
	s_waitcnt lgkmcnt(0)
	v_mfma_f32_16x16x32_bf16 v[138:141], v[128:131], v[172:175], v[138:141]
	v_mfma_f32_16x16x32_bf16 v[132:135], v[146:149], v[172:175], v[134:137]
	v_mfma_f32_16x16x32_bf16 v[110:113], v[128:131], v[180:183], v[110:113]
	v_mfma_f32_16x16x32_bf16 v[106:109], v[146:149], v[180:183], v[106:109]
	v_mfma_f32_16x16x32_bf16 v[94:97], v[128:131], v[188:191], v[94:97]
	v_mfma_f32_16x16x32_bf16 v[90:93], v[146:149], v[188:191], v[90:93]
	v_mfma_f32_16x16x32_bf16 v[78:81], v[128:131], v[196:199], v[78:81]
	v_mfma_f32_16x16x32_bf16 v[74:77], v[146:149], v[196:199], v[74:77]
	v_mfma_f32_16x16x32_bf16 v[138:141], v[142:145], v[176:179], v[138:141]
	v_mfma_f32_16x16x32_bf16 v[132:135], v[150:153], v[176:179], v[132:135]
	v_mfma_f32_16x16x32_bf16 v[110:113], v[142:145], v[184:187], v[110:113]
	v_mfma_f32_16x16x32_bf16 v[106:109], v[150:153], v[184:187], v[106:109]
	v_mfma_f32_16x16x32_bf16 v[94:97], v[142:145], v[192:195], v[94:97]
	v_mfma_f32_16x16x32_bf16 v[90:93], v[150:153], v[192:195], v[90:93]
	v_mfma_f32_16x16x32_bf16 v[78:81], v[142:145], v[200:203], v[78:81]
	v_mfma_f32_16x16x32_bf16 v[74:77], v[150:153], v[200:203], v[74:77]
	s_setprio 0
	s_setprio 1
	v_mfma_f32_16x16x32_bf16 v[118:121], v[154:157], v[172:175], v[118:121]
	v_mfma_f32_16x16x32_bf16 v[114:117], v[164:167], v[172:175], v[114:117]
	v_mfma_f32_16x16x32_bf16 v[102:105], v[154:157], v[180:183], v[102:105]
	v_mfma_f32_16x16x32_bf16 v[98:101], v[164:167], v[180:183], v[98:101]
	v_mfma_f32_16x16x32_bf16 v[86:89], v[154:157], v[188:191], v[86:89]
	v_mfma_f32_16x16x32_bf16 v[82:85], v[164:167], v[188:191], v[82:85]
	v_mfma_f32_16x16x32_bf16 v[70:73], v[154:157], v[196:199], v[70:73]
	v_mfma_f32_16x16x32_bf16 v[66:69], v[164:167], v[196:199], v[66:69]
	v_mfma_f32_16x16x32_bf16 v[118:121], v[160:163], v[176:179], v[118:121]
	v_mfma_f32_16x16x32_bf16 v[114:117], v[168:171], v[176:179], v[114:117]
	v_mfma_f32_16x16x32_bf16 v[102:105], v[160:163], v[184:187], v[102:105]
	v_mfma_f32_16x16x32_bf16 v[98:101], v[168:171], v[184:187], v[98:101]
	v_mfma_f32_16x16x32_bf16 v[86:89], v[160:163], v[192:195], v[86:89]
	v_mfma_f32_16x16x32_bf16 v[82:85], v[168:171], v[192:195], v[82:85]
	v_mfma_f32_16x16x32_bf16 v[70:73], v[160:163], v[200:203], v[70:73]
	v_mfma_f32_16x16x32_bf16 v[66:69], v[168:171], v[200:203], v[66:69]
	s_setprio 0
	s_barrier
	s_add_i32 s4, s69, s26
	ds_read_b128 v[172:175], v127 offset:16384
	ds_read_b128 v[176:179], v127 offset:17408
	ds_read_b128 v[180:183], v127 offset:18432
	ds_read_b128 v[184:187], v127 offset:19456
	ds_read_b128 v[188:191], v127 offset:20480
	ds_read_b128 v[192:195], v127 offset:21504
	ds_read_b128 v[196:199], v127 offset:22528
	ds_read_b128 v[200:203], v127 offset:23552
	s_mov_b32 m0, s4
	s_nop 0
	global_load_lds_dwordx4 v124, s[46:47]
	s_add_i32 m0, s4, 0x2000
	s_add_u32 s4, s46, 0xb0000
	global_load_lds_dwordx4 v125, s[46:47]
	s_addc_u32 s5, s47, 0
	s_add_i32 s69, s70, s26
	s_mov_b32 m0, s69
	s_nop 0
	global_load_lds_dwordx4 v124, s[4:5]
	s_add_i32 m0, s69, 0x2000
	s_nop 0
	global_load_lds_dwordx4 v125, s[4:5]
	s_mov_b32 m0, s41
	s_nop 0
	global_load_lds_dwordx4 v122, s[22:23]
	s_mov_b32 m0, s48
	s_nop 0
	global_load_lds_dwordx4 v123, s[22:23]
	s_waitcnt vmcnt(8)
	s_waitcnt lgkmcnt(0)
	s_barrier
	s_setprio 1
	s_waitcnt lgkmcnt(0)
	v_mfma_f32_16x16x32_bf16 v[62:65], v[128:131], v[172:175], v[62:65]
	v_mfma_f32_16x16x32_bf16 v[58:61], v[146:149], v[172:175], v[58:61]
	v_mfma_f32_16x16x32_bf16 v[46:49], v[128:131], v[180:183], v[46:49]
	v_mfma_f32_16x16x32_bf16 v[42:45], v[146:149], v[180:183], v[42:45]
	v_mfma_f32_16x16x32_bf16 v[30:33], v[128:131], v[188:191], v[30:33]
	v_mfma_f32_16x16x32_bf16 v[26:29], v[146:149], v[188:191], v[26:29]
	v_mfma_f32_16x16x32_bf16 v[14:17], v[128:131], v[196:199], v[14:17]
	v_mfma_f32_16x16x32_bf16 v[10:13], v[146:149], v[196:199], v[10:13]
	v_mfma_f32_16x16x32_bf16 v[62:65], v[142:145], v[176:179], v[62:65]
	v_mfma_f32_16x16x32_bf16 v[58:61], v[150:153], v[176:179], v[58:61]
	v_mfma_f32_16x16x32_bf16 v[46:49], v[142:145], v[184:187], v[46:49]
	v_mfma_f32_16x16x32_bf16 v[42:45], v[150:153], v[184:187], v[42:45]
	v_mfma_f32_16x16x32_bf16 v[30:33], v[142:145], v[192:195], v[30:33]
	v_mfma_f32_16x16x32_bf16 v[26:29], v[150:153], v[192:195], v[26:29]
	v_mfma_f32_16x16x32_bf16 v[14:17], v[142:145], v[200:203], v[14:17]
	v_mfma_f32_16x16x32_bf16 v[10:13], v[150:153], v[200:203], v[10:13]
	s_setprio 0
	s_setprio 1
	v_mfma_f32_16x16x32_bf16 v[54:57], v[154:157], v[172:175], v[54:57]
	v_mfma_f32_16x16x32_bf16 v[50:53], v[164:167], v[172:175], v[50:53]
	v_mfma_f32_16x16x32_bf16 v[38:41], v[154:157], v[180:183], v[38:41]
	v_mfma_f32_16x16x32_bf16 v[34:37], v[164:167], v[180:183], v[34:37]
	v_mfma_f32_16x16x32_bf16 v[22:25], v[154:157], v[188:191], v[22:25]
	v_mfma_f32_16x16x32_bf16 v[18:21], v[164:167], v[188:191], v[18:21]
	v_mfma_f32_16x16x32_bf16 v[6:9], v[154:157], v[196:199], v[6:9]
	v_mfma_f32_16x16x32_bf16 v[2:5], v[164:167], v[196:199], v[2:5]
	v_mfma_f32_16x16x32_bf16 v[54:57], v[160:163], v[176:179], v[54:57]
	v_mfma_f32_16x16x32_bf16 v[50:53], v[168:171], v[176:179], v[50:53]
	v_mfma_f32_16x16x32_bf16 v[38:41], v[160:163], v[184:187], v[38:41]
	v_mfma_f32_16x16x32_bf16 v[34:37], v[168:171], v[184:187], v[34:37]
	v_mfma_f32_16x16x32_bf16 v[22:25], v[160:163], v[192:195], v[22:25]
	v_mfma_f32_16x16x32_bf16 v[18:21], v[168:171], v[192:195], v[18:21]
	v_mfma_f32_16x16x32_bf16 v[6:9], v[160:163], v[200:203], v[6:9]
	v_mfma_f32_16x16x32_bf16 v[2:5], v[168:171], v[200:203], v[2:5]
	s_setprio 0
	s_barrier
	s_add_i32 s69, 0, 0x18000
	s_add_i32 s70, 0, 0x1c000
	ds_read_b128 v[128:131], v0 offset:32768
	ds_read_b128 v[142:145], v0 offset:33792
	ds_read_b128 v[146:149], v0 offset:34816
	ds_read_b128 v[150:153], v0 offset:35840
	ds_read_b128 v[154:157], v0 offset:49152
	ds_read_b128 v[160:163], v0 offset:50176
	ds_read_b128 v[164:167], v0 offset:51200
	ds_read_b128 v[168:171], v0 offset:52224
	s_add_u32 s4, s22, 0xb0000
	s_mov_b32 m0, s49
	ds_read_b128 v[172:175], v127 offset:32768
	ds_read_b128 v[176:179], v127 offset:33792
	ds_read_b128 v[180:183], v127 offset:34816
	ds_read_b128 v[184:187], v127 offset:35840
	ds_read_b128 v[188:191], v127 offset:36864
	ds_read_b128 v[192:195], v127 offset:37888
	ds_read_b128 v[196:199], v127 offset:38912
	ds_read_b128 v[200:203], v127 offset:39936
	s_addc_u32 s5, s23, 0
	s_nop 0
	global_load_lds_dwordx4 v122, s[4:5]
	s_mov_b32 m0, s50
	s_nop 0
	global_load_lds_dwordx4 v123, s[4:5]
	s_waitcnt vmcnt(8)
	s_waitcnt lgkmcnt(0)
	s_barrier
	s_setprio 1
	s_waitcnt lgkmcnt(0)
	v_mfma_f32_16x16x32_bf16 v[136:139], v[128:131], v[172:175], v[138:141]
	v_mfma_f32_16x16x32_bf16 v[132:135], v[146:149], v[172:175], v[132:135]
	v_mfma_f32_16x16x32_bf16 v[110:113], v[128:131], v[180:183], v[110:113]
	v_mfma_f32_16x16x32_bf16 v[106:109], v[146:149], v[180:183], v[106:109]
	v_mfma_f32_16x16x32_bf16 v[94:97], v[128:131], v[188:191], v[94:97]
	v_mfma_f32_16x16x32_bf16 v[90:93], v[146:149], v[188:191], v[90:93]
	v_mfma_f32_16x16x32_bf16 v[78:81], v[128:131], v[196:199], v[78:81]
	v_mfma_f32_16x16x32_bf16 v[74:77], v[146:149], v[196:199], v[74:77]
	v_mfma_f32_16x16x32_bf16 v[138:141], v[142:145], v[176:179], v[136:139]
	v_mfma_f32_16x16x32_bf16 v[134:137], v[150:153], v[176:179], v[132:135]
	v_mfma_f32_16x16x32_bf16 v[110:113], v[142:145], v[184:187], v[110:113]
	v_mfma_f32_16x16x32_bf16 v[106:109], v[150:153], v[184:187], v[106:109]
	v_mfma_f32_16x16x32_bf16 v[94:97], v[142:145], v[192:195], v[94:97]
	v_mfma_f32_16x16x32_bf16 v[90:93], v[150:153], v[192:195], v[90:93]
	v_mfma_f32_16x16x32_bf16 v[78:81], v[142:145], v[200:203], v[78:81]
	v_mfma_f32_16x16x32_bf16 v[74:77], v[150:153], v[200:203], v[74:77]
	s_setprio 0
	s_setprio 1
	v_mfma_f32_16x16x32_bf16 v[118:121], v[154:157], v[172:175], v[118:121]
	v_mfma_f32_16x16x32_bf16 v[114:117], v[164:167], v[172:175], v[114:117]
	v_mfma_f32_16x16x32_bf16 v[102:105], v[154:157], v[180:183], v[102:105]
	v_mfma_f32_16x16x32_bf16 v[98:101], v[164:167], v[180:183], v[98:101]
	v_mfma_f32_16x16x32_bf16 v[86:89], v[154:157], v[188:191], v[86:89]
	v_mfma_f32_16x16x32_bf16 v[82:85], v[164:167], v[188:191], v[82:85]
	v_mfma_f32_16x16x32_bf16 v[70:73], v[154:157], v[196:199], v[70:73]
	v_mfma_f32_16x16x32_bf16 v[66:69], v[164:167], v[196:199], v[66:69]
	v_mfma_f32_16x16x32_bf16 v[118:121], v[160:163], v[176:179], v[118:121]
	v_mfma_f32_16x16x32_bf16 v[114:117], v[168:171], v[176:179], v[114:117]
	v_mfma_f32_16x16x32_bf16 v[102:105], v[160:163], v[184:187], v[102:105]
	v_mfma_f32_16x16x32_bf16 v[98:101], v[168:171], v[184:187], v[98:101]
	v_mfma_f32_16x16x32_bf16 v[86:89], v[160:163], v[192:195], v[86:89]
	v_mfma_f32_16x16x32_bf16 v[82:85], v[168:171], v[192:195], v[82:85]
	v_mfma_f32_16x16x32_bf16 v[70:73], v[160:163], v[200:203], v[70:73]
	v_mfma_f32_16x16x32_bf16 v[66:69], v[168:171], v[200:203], v[66:69]
	s_setprio 0
	s_barrier
	ds_read_b128 v[172:175], v127 offset:49152
	ds_read_b128 v[176:179], v127 offset:50176
	ds_read_b128 v[180:183], v127 offset:51200
	ds_read_b128 v[184:187], v127 offset:52224
	ds_read_b128 v[188:191], v127 offset:53248
	ds_read_b128 v[192:195], v127 offset:54272
	ds_read_b128 v[196:199], v127 offset:55296
	ds_read_b128 v[200:203], v127 offset:56320
	s_add_i32 s4, s69, s26
	s_add_u32 s100, s46, s38
	s_addc_u32 s101, s47, s39
	s_mov_b32 m0, s4
	s_nop 0
	global_load_lds_dwordx4 v124, s[100:101]
	s_add_i32 m0, s4, 0x2000
	s_add_u32 s4, s46, 0xb0080
	s_addc_u32 s5, s47, 0
	s_add_i32 s46, s70, s26
	global_load_lds_dwordx4 v125, s[100:101]
	s_mov_b32 m0, s46
	s_nop 0
	global_load_lds_dwordx4 v124, s[4:5]
	s_add_i32 m0, s46, 0x2000
	s_nop 0
	global_load_lds_dwordx4 v125, s[4:5]
	s_mov_b32 m0, s64
	s_add_u32 s100, s22, s38
	s_addc_u32 s101, s23, s39
	v_mov_b32_e32 v0, v123
	global_load_lds_dwordx4 v122, s[100:101]
	s_mov_b32 m0, s65
	s_nop 0
	global_load_lds_dwordx4 v123, s[100:101]
	s_waitcnt vmcnt(8)
	s_waitcnt lgkmcnt(0)
	s_barrier
	s_setprio 1
	s_waitcnt lgkmcnt(0)
	v_mfma_f32_16x16x32_bf16 v[62:65], v[128:131], v[172:175], v[62:65]
	v_mfma_f32_16x16x32_bf16 v[58:61], v[146:149], v[172:175], v[58:61]
	v_mfma_f32_16x16x32_bf16 v[46:49], v[128:131], v[180:183], v[46:49]
	v_mfma_f32_16x16x32_bf16 v[42:45], v[146:149], v[180:183], v[42:45]
	v_mfma_f32_16x16x32_bf16 v[30:33], v[128:131], v[188:191], v[30:33]
	v_mfma_f32_16x16x32_bf16 v[26:29], v[146:149], v[188:191], v[26:29]
	v_mfma_f32_16x16x32_bf16 v[14:17], v[128:131], v[196:199], v[14:17]
	v_mfma_f32_16x16x32_bf16 v[10:13], v[146:149], v[196:199], v[10:13]
	v_mfma_f32_16x16x32_bf16 v[62:65], v[142:145], v[176:179], v[62:65]
	v_mfma_f32_16x16x32_bf16 v[58:61], v[150:153], v[176:179], v[58:61]
	v_mfma_f32_16x16x32_bf16 v[46:49], v[142:145], v[184:187], v[46:49]
	v_mfma_f32_16x16x32_bf16 v[42:45], v[150:153], v[184:187], v[42:45]
	v_mfma_f32_16x16x32_bf16 v[30:33], v[142:145], v[192:195], v[30:33]
	v_mfma_f32_16x16x32_bf16 v[26:29], v[150:153], v[192:195], v[26:29]
	v_mfma_f32_16x16x32_bf16 v[14:17], v[142:145], v[200:203], v[14:17]
	v_mfma_f32_16x16x32_bf16 v[10:13], v[150:153], v[200:203], v[10:13]
	s_setprio 0
	s_setprio 1
	v_mfma_f32_16x16x32_bf16 v[54:57], v[154:157], v[172:175], v[54:57]
	v_mfma_f32_16x16x32_bf16 v[50:53], v[164:167], v[172:175], v[50:53]
	v_mfma_f32_16x16x32_bf16 v[38:41], v[154:157], v[180:183], v[38:41]
	v_mfma_f32_16x16x32_bf16 v[34:37], v[164:167], v[180:183], v[34:37]
	v_mfma_f32_16x16x32_bf16 v[22:25], v[154:157], v[188:191], v[22:25]
	v_mfma_f32_16x16x32_bf16 v[18:21], v[164:167], v[188:191], v[18:21]
	v_mfma_f32_16x16x32_bf16 v[6:9], v[154:157], v[196:199], v[6:9]
	v_mfma_f32_16x16x32_bf16 v[2:5], v[164:167], v[196:199], v[2:5]
	v_mfma_f32_16x16x32_bf16 v[54:57], v[160:163], v[176:179], v[54:57]
	v_mfma_f32_16x16x32_bf16 v[50:53], v[168:171], v[176:179], v[50:53]
	v_mfma_f32_16x16x32_bf16 v[38:41], v[160:163], v[184:187], v[38:41]
	v_mfma_f32_16x16x32_bf16 v[34:37], v[168:171], v[184:187], v[34:37]
	v_mfma_f32_16x16x32_bf16 v[22:25], v[160:163], v[192:195], v[22:25]
	v_mfma_f32_16x16x32_bf16 v[18:21], v[168:171], v[192:195], v[18:21]
	v_mfma_f32_16x16x32_bf16 v[6:9], v[160:163], v[200:203], v[6:9]
	v_mfma_f32_16x16x32_bf16 v[2:5], v[168:171], v[200:203], v[2:5]
	s_setprio 0
	s_barrier
	s_add_i32 s68, s68, 2
	s_add_u32 s2, s2, 0x100
	s_addc_u32 s3, s3, 0
	s_cmp_gt_u32 s68, 41
	s_cbranch_scc0 .LBB0_869
	s_cmpk_lt_u32 s25, 0x100
	s_cbranch_scc0 .LBB0_872
	s_barrier

.LBB0_953:
	s_add_u32 s58, s4, s2
	s_addc_u32 s59, s5, s3
	s_add_u32 s14, s58, 0x100
	s_addc_u32 s15, s59, 0
	s_add_u32 s16, s43, s2
	s_addc_u32 s17, s46, s3
	s_add_i32 s51, 0, 0x10000
	s_cmp_eq_u32 s50, 40
	s_cselect_b32 s15, s5, s15
	s_cselect_b32 s14, s4, s14
	v_add_u32_e32 v0, s51, v135
	s_cselect_b32 s17, s7, s17
	s_cselect_b32 s16, s6, s16
	s_add_i32 s60, 0, 0x14000
	ds_read_b128 v[138:141], v0
	ds_read_b128 v[142:145], v0 offset:1024
	ds_read_b128 v[146:149], v0 offset:2048
	ds_read_b128 v[150:153], v0 offset:3072
	ds_read_b128 v[154:157], v0 offset:16384
	ds_read_b128 v[158:161], v0 offset:17408
	ds_read_b128 v[162:165], v0 offset:18432
	ds_read_b128 v[166:169], v0 offset:19456
	ds_read_b128 v[170:173], v136
	ds_read_b128 v[174:177], v136 offset:1024
	ds_read_b128 v[178:181], v136 offset:2048
	ds_read_b128 v[182:185], v136 offset:3072
	ds_read_b128 v[186:189], v136 offset:4096
	ds_read_b128 v[190:193], v136 offset:5120
	ds_read_b128 v[194:197], v136 offset:6144
	ds_read_b128 v[198:201], v136 offset:7168
	s_add_i32 m0, s37, 0xc000
	s_add_u32 s100, s58, s62
	s_addc_u32 s101, s59, s63
	global_load_lds_dwordx4 v130, s[100:101]
	s_add_i32 m0, s37, 0xe000
	s_nop 0
	global_load_lds_dwordx4 v131, s[100:101]
	s_waitcnt vmcnt(8)
	s_waitcnt lgkmcnt(0)
	s_barrier
	s_setprio 1
	s_waitcnt lgkmcnt(0)
	v_mfma_f32_16x16x32_bf16 v[126:129], v[138:141], v[170:173], v[126:129]
	v_mfma_f32_16x16x32_bf16 v[122:125], v[146:149], v[170:173], v[122:125]
	v_mfma_f32_16x16x32_bf16 v[110:113], v[138:141], v[178:181], v[110:113]
	v_mfma_f32_16x16x32_bf16 v[106:109], v[146:149], v[178:181], v[106:109]
	v_mfma_f32_16x16x32_bf16 v[94:97], v[138:141], v[186:189], v[94:97]
	v_mfma_f32_16x16x32_bf16 v[90:93], v[146:149], v[186:189], v[90:93]
	v_mfma_f32_16x16x32_bf16 v[78:81], v[138:141], v[194:197], v[78:81]
	v_mfma_f32_16x16x32_bf16 v[74:77], v[146:149], v[194:197], v[74:77]
	v_mfma_f32_16x16x32_bf16 v[126:129], v[142:145], v[174:177], v[126:129]
	v_mfma_f32_16x16x32_bf16 v[122:125], v[150:153], v[174:177], v[122:125]
	v_mfma_f32_16x16x32_bf16 v[110:113], v[142:145], v[182:185], v[110:113]
	v_mfma_f32_16x16x32_bf16 v[106:109], v[150:153], v[182:185], v[106:109]
	v_mfma_f32_16x16x32_bf16 v[94:97], v[142:145], v[190:193], v[94:97]
	v_mfma_f32_16x16x32_bf16 v[90:93], v[150:153], v[190:193], v[90:93]
	v_mfma_f32_16x16x32_bf16 v[78:81], v[142:145], v[198:201], v[78:81]
	v_mfma_f32_16x16x32_bf16 v[74:77], v[150:153], v[198:201], v[74:77]
	s_setprio 0
	s_setprio 1
	v_mfma_f32_16x16x32_bf16 v[118:121], v[154:157], v[170:173], v[118:121]
	v_mfma_f32_16x16x32_bf16 v[114:117], v[162:165], v[170:173], v[114:117]
	v_mfma_f32_16x16x32_bf16 v[102:105], v[154:157], v[178:181], v[102:105]
	v_mfma_f32_16x16x32_bf16 v[98:101], v[162:165], v[178:181], v[98:101]
	v_mfma_f32_16x16x32_bf16 v[86:89], v[154:157], v[186:189], v[86:89]
	v_mfma_f32_16x16x32_bf16 v[82:85], v[162:165], v[186:189], v[82:85]
	v_mfma_f32_16x16x32_bf16 v[70:73], v[154:157], v[194:197], v[70:73]
	v_mfma_f32_16x16x32_bf16 v[66:69], v[162:165], v[194:197], v[66:69]
	v_mfma_f32_16x16x32_bf16 v[118:121], v[158:161], v[174:177], v[118:121]
	v_mfma_f32_16x16x32_bf16 v[114:117], v[166:169], v[174:177], v[114:117]
	v_mfma_f32_16x16x32_bf16 v[102:105], v[158:161], v[182:185], v[102:105]
	v_mfma_f32_16x16x32_bf16 v[98:101], v[166:169], v[182:185], v[98:101]
	v_mfma_f32_16x16x32_bf16 v[86:89], v[158:161], v[190:193], v[86:89]
	v_mfma_f32_16x16x32_bf16 v[82:85], v[166:169], v[190:193], v[82:85]
	v_mfma_f32_16x16x32_bf16 v[70:73], v[158:161], v[198:201], v[70:73]
	v_mfma_f32_16x16x32_bf16 v[66:69], v[166:169], v[198:201], v[66:69]
	s_setprio 0
	s_barrier
	s_add_i32 s51, s51, s26
	ds_read_b128 v[170:173], v136 offset:16384
	ds_read_b128 v[174:177], v136 offset:17408
	ds_read_b128 v[178:181], v136 offset:18432
	ds_read_b128 v[182:185], v136 offset:19456
	ds_read_b128 v[186:189], v136 offset:20480
	ds_read_b128 v[190:193], v136 offset:21504
	ds_read_b128 v[194:197], v136 offset:22528
	ds_read_b128 v[198:201], v136 offset:23552
	s_mov_b32 m0, s51
	s_nop 0
	global_load_lds_dwordx4 v133, s[16:17]
	s_add_i32 m0, s51, 0x2000
	s_add_u32 s58, s16, 0xb0000
	global_load_lds_dwordx4 v134, s[16:17]
	s_addc_u32 s59, s17, 0
	s_add_i32 s51, s60, s26
	s_mov_b32 m0, s51
	s_nop 0
	global_load_lds_dwordx4 v133, s[58:59]
	s_add_i32 m0, s51, 0x2000
	s_nop 0
	global_load_lds_dwordx4 v134, s[58:59]
	s_mov_b32 m0, s37
	s_nop 0
	global_load_lds_dwordx4 v130, s[14:15]
	s_mov_b32 m0, s40
	s_nop 0
	global_load_lds_dwordx4 v131, s[14:15]
	s_waitcnt vmcnt(8)
	s_waitcnt lgkmcnt(0)
	s_barrier
	s_setprio 1
	s_waitcnt lgkmcnt(0)
	v_mfma_f32_16x16x32_bf16 v[62:65], v[138:141], v[170:173], v[62:65]
	v_mfma_f32_16x16x32_bf16 v[58:61], v[146:149], v[170:173], v[58:61]
	v_mfma_f32_16x16x32_bf16 v[46:49], v[138:141], v[178:181], v[46:49]
	v_mfma_f32_16x16x32_bf16 v[42:45], v[146:149], v[178:181], v[42:45]
	v_mfma_f32_16x16x32_bf16 v[30:33], v[138:141], v[186:189], v[30:33]
	v_mfma_f32_16x16x32_bf16 v[26:29], v[146:149], v[186:189], v[26:29]
	v_mfma_f32_16x16x32_bf16 v[14:17], v[138:141], v[194:197], v[14:17]
	v_mfma_f32_16x16x32_bf16 v[10:13], v[146:149], v[194:197], v[10:13]
	v_mfma_f32_16x16x32_bf16 v[62:65], v[142:145], v[174:177], v[62:65]
	v_mfma_f32_16x16x32_bf16 v[58:61], v[150:153], v[174:177], v[58:61]
	v_mfma_f32_16x16x32_bf16 v[46:49], v[142:145], v[182:185], v[46:49]
	v_mfma_f32_16x16x32_bf16 v[42:45], v[150:153], v[182:185], v[42:45]
	v_mfma_f32_16x16x32_bf16 v[30:33], v[142:145], v[190:193], v[30:33]
	v_mfma_f32_16x16x32_bf16 v[26:29], v[150:153], v[190:193], v[26:29]
	v_mfma_f32_16x16x32_bf16 v[14:17], v[142:145], v[198:201], v[14:17]
	v_mfma_f32_16x16x32_bf16 v[10:13], v[150:153], v[198:201], v[10:13]
	s_setprio 0
	s_setprio 1
	v_mfma_f32_16x16x32_bf16 v[54:57], v[154:157], v[170:173], v[54:57]
	v_mfma_f32_16x16x32_bf16 v[50:53], v[162:165], v[170:173], v[50:53]
	v_mfma_f32_16x16x32_bf16 v[38:41], v[154:157], v[178:181], v[38:41]
	v_mfma_f32_16x16x32_bf16 v[34:37], v[162:165], v[178:181], v[34:37]
	v_mfma_f32_16x16x32_bf16 v[22:25], v[154:157], v[186:189], v[22:25]
	v_mfma_f32_16x16x32_bf16 v[18:21], v[162:165], v[186:189], v[18:21]
	v_mfma_f32_16x16x32_bf16 v[6:9], v[154:157], v[194:197], v[6:9]
	v_mfma_f32_16x16x32_bf16 v[2:5], v[162:165], v[194:197], v[2:5]
	v_mfma_f32_16x16x32_bf16 v[54:57], v[158:161], v[174:177], v[54:57]
	v_mfma_f32_16x16x32_bf16 v[50:53], v[166:169], v[174:177], v[50:53]
	v_mfma_f32_16x16x32_bf16 v[38:41], v[158:161], v[182:185], v[38:41]
	v_mfma_f32_16x16x32_bf16 v[34:37], v[166:169], v[182:185], v[34:37]
	v_mfma_f32_16x16x32_bf16 v[22:25], v[158:161], v[190:193], v[22:25]
	v_mfma_f32_16x16x32_bf16 v[18:21], v[166:169], v[190:193], v[18:21]
	v_mfma_f32_16x16x32_bf16 v[6:9], v[158:161], v[198:201], v[6:9]
	v_mfma_f32_16x16x32_bf16 v[2:5], v[166:169], v[198:201], v[2:5]
	s_setprio 0
	s_barrier
	s_add_i32 s51, 0, 0x18000
	s_add_i32 s60, 0, 0x1c000
	ds_read_b128 v[138:141], v0 offset:32768
	ds_read_b128 v[142:145], v0 offset:33792
	ds_read_b128 v[146:149], v0 offset:34816
	ds_read_b128 v[150:153], v0 offset:35840
	ds_read_b128 v[154:157], v0 offset:49152
	ds_read_b128 v[158:161], v0 offset:50176
	ds_read_b128 v[162:165], v0 offset:51200
	ds_read_b128 v[166:169], v0 offset:52224
	s_add_u32 s58, s14, 0xb0000
	s_mov_b32 m0, s41
	ds_read_b128 v[170:173], v136 offset:32768
	ds_read_b128 v[174:177], v136 offset:33792
	ds_read_b128 v[178:181], v136 offset:34816
	ds_read_b128 v[182:185], v136 offset:35840
	ds_read_b128 v[186:189], v136 offset:36864
	ds_read_b128 v[190:193], v136 offset:37888
	ds_read_b128 v[194:197], v136 offset:38912
	ds_read_b128 v[198:201], v136 offset:39936
	s_addc_u32 s59, s15, 0
	s_nop 0
	global_load_lds_dwordx4 v130, s[58:59]
	s_mov_b32 m0, s42
	s_nop 0
	global_load_lds_dwordx4 v131, s[58:59]
	s_waitcnt vmcnt(8)
	s_waitcnt lgkmcnt(0)
	s_barrier
	s_setprio 1
	s_waitcnt lgkmcnt(0)
	v_mfma_f32_16x16x32_bf16 v[126:129], v[138:141], v[170:173], v[126:129]
	v_mfma_f32_16x16x32_bf16 v[122:125], v[146:149], v[170:173], v[122:125]
	v_mfma_f32_16x16x32_bf16 v[110:113], v[138:141], v[178:181], v[110:113]
	v_mfma_f32_16x16x32_bf16 v[106:109], v[146:149], v[178:181], v[106:109]
	v_mfma_f32_16x16x32_bf16 v[94:97], v[138:141], v[186:189], v[94:97]
	v_mfma_f32_16x16x32_bf16 v[90:93], v[146:149], v[186:189], v[90:93]
	v_mfma_f32_16x16x32_bf16 v[78:81], v[138:141], v[194:197], v[78:81]
	v_mfma_f32_16x16x32_bf16 v[74:77], v[146:149], v[194:197], v[74:77]
	v_mfma_f32_16x16x32_bf16 v[126:129], v[142:145], v[174:177], v[126:129]
	v_mfma_f32_16x16x32_bf16 v[122:125], v[150:153], v[174:177], v[122:125]
	v_mfma_f32_16x16x32_bf16 v[110:113], v[142:145], v[182:185], v[110:113]
	v_mfma_f32_16x16x32_bf16 v[106:109], v[150:153], v[182:185], v[106:109]
	v_mfma_f32_16x16x32_bf16 v[94:97], v[142:145], v[190:193], v[94:97]
	v_mfma_f32_16x16x32_bf16 v[90:93], v[150:153], v[190:193], v[90:93]
	v_mfma_f32_16x16x32_bf16 v[78:81], v[142:145], v[198:201], v[78:81]
	v_mfma_f32_16x16x32_bf16 v[74:77], v[150:153], v[198:201], v[74:77]
	s_setprio 0
	s_setprio 1
	v_mfma_f32_16x16x32_bf16 v[118:121], v[154:157], v[170:173], v[118:121]
	v_mfma_f32_16x16x32_bf16 v[114:117], v[162:165], v[170:173], v[114:117]
	v_mfma_f32_16x16x32_bf16 v[102:105], v[154:157], v[178:181], v[102:105]
	v_mfma_f32_16x16x32_bf16 v[98:101], v[162:165], v[178:181], v[98:101]
	v_mfma_f32_16x16x32_bf16 v[86:89], v[154:157], v[186:189], v[86:89]
	v_mfma_f32_16x16x32_bf16 v[82:85], v[162:165], v[186:189], v[82:85]
	v_mfma_f32_16x16x32_bf16 v[70:73], v[154:157], v[194:197], v[70:73]
	v_mfma_f32_16x16x32_bf16 v[66:69], v[162:165], v[194:197], v[66:69]
	v_mfma_f32_16x16x32_bf16 v[118:121], v[158:161], v[174:177], v[118:121]
	v_mfma_f32_16x16x32_bf16 v[114:117], v[166:169], v[174:177], v[114:117]
	v_mfma_f32_16x16x32_bf16 v[102:105], v[158:161], v[182:185], v[102:105]
	v_mfma_f32_16x16x32_bf16 v[98:101], v[166:169], v[182:185], v[98:101]
	v_mfma_f32_16x16x32_bf16 v[86:89], v[158:161], v[190:193], v[86:89]
	v_mfma_f32_16x16x32_bf16 v[82:85], v[166:169], v[190:193], v[82:85]
	v_mfma_f32_16x16x32_bf16 v[70:73], v[158:161], v[198:201], v[70:73]
	v_mfma_f32_16x16x32_bf16 v[66:69], v[166:169], v[198:201], v[66:69]
	s_setprio 0
	s_barrier
	ds_read_b128 v[170:173], v136 offset:49152
	ds_read_b128 v[174:177], v136 offset:50176
	ds_read_b128 v[178:181], v136 offset:51200
	ds_read_b128 v[182:185], v136 offset:52224
	ds_read_b128 v[186:189], v136 offset:53248
	ds_read_b128 v[190:193], v136 offset:54272
	ds_read_b128 v[194:197], v136 offset:55296
	ds_read_b128 v[198:201], v136 offset:56320
	s_add_i32 s51, s51, s26
	s_add_u32 s100, s16, s38
	s_addc_u32 s101, s17, s39
	s_mov_b32 m0, s51
	s_nop 0
	global_load_lds_dwordx4 v133, s[100:101]
	s_add_i32 m0, s51, 0x2000
	s_nop 0
	s_add_u32 s16, s16, 0xb0080
	s_addc_u32 s17, s17, 0
	s_add_i32 s51, s60, s26
	global_load_lds_dwordx4 v134, s[100:101]
	s_mov_b32 m0, s51
	s_nop 0
	global_load_lds_dwordx4 v133, s[16:17]
	s_add_i32 m0, s51, 0x2000
	s_nop 0
	global_load_lds_dwordx4 v134, s[16:17]
	s_mov_b32 m0, s48
	s_add_u32 s100, s14, s38
	s_addc_u32 s101, s15, s39
	v_mov_b32_e32 v0, v131
	global_load_lds_dwordx4 v130, s[100:101]
	s_mov_b32 m0, s49
	s_nop 0
	global_load_lds_dwordx4 v131, s[100:101]
	s_waitcnt vmcnt(8)
	s_waitcnt lgkmcnt(0)
	s_barrier
	s_setprio 1
	s_waitcnt lgkmcnt(0)
	v_mfma_f32_16x16x32_bf16 v[62:65], v[138:141], v[170:173], v[62:65]
	v_mfma_f32_16x16x32_bf16 v[58:61], v[146:149], v[170:173], v[58:61]
	v_mfma_f32_16x16x32_bf16 v[46:49], v[138:141], v[178:181], v[46:49]
	v_mfma_f32_16x16x32_bf16 v[42:45], v[146:149], v[178:181], v[42:45]
	v_mfma_f32_16x16x32_bf16 v[30:33], v[138:141], v[186:189], v[30:33]
	v_mfma_f32_16x16x32_bf16 v[26:29], v[146:149], v[186:189], v[26:29]
	v_mfma_f32_16x16x32_bf16 v[14:17], v[138:141], v[194:197], v[14:17]
	v_mfma_f32_16x16x32_bf16 v[10:13], v[146:149], v[194:197], v[10:13]
	v_mfma_f32_16x16x32_bf16 v[62:65], v[142:145], v[174:177], v[62:65]
	v_mfma_f32_16x16x32_bf16 v[58:61], v[150:153], v[174:177], v[58:61]
	v_mfma_f32_16x16x32_bf16 v[46:49], v[142:145], v[182:185], v[46:49]
	v_mfma_f32_16x16x32_bf16 v[42:45], v[150:153], v[182:185], v[42:45]
	v_mfma_f32_16x16x32_bf16 v[30:33], v[142:145], v[190:193], v[30:33]
	v_mfma_f32_16x16x32_bf16 v[26:29], v[150:153], v[190:193], v[26:29]
	v_mfma_f32_16x16x32_bf16 v[14:17], v[142:145], v[198:201], v[14:17]
	v_mfma_f32_16x16x32_bf16 v[10:13], v[150:153], v[198:201], v[10:13]
	s_setprio 0
	s_setprio 1
	v_mfma_f32_16x16x32_bf16 v[54:57], v[154:157], v[170:173], v[54:57]
	v_mfma_f32_16x16x32_bf16 v[50:53], v[162:165], v[170:173], v[50:53]
	v_mfma_f32_16x16x32_bf16 v[38:41], v[154:157], v[178:181], v[38:41]
	v_mfma_f32_16x16x32_bf16 v[34:37], v[162:165], v[178:181], v[34:37]
	v_mfma_f32_16x16x32_bf16 v[22:25], v[154:157], v[186:189], v[22:25]
	v_mfma_f32_16x16x32_bf16 v[18:21], v[162:165], v[186:189], v[18:21]
	v_mfma_f32_16x16x32_bf16 v[6:9], v[154:157], v[194:197], v[6:9]
	v_mfma_f32_16x16x32_bf16 v[2:5], v[162:165], v[194:197], v[2:5]
	v_mfma_f32_16x16x32_bf16 v[54:57], v[158:161], v[174:177], v[54:57]
	v_mfma_f32_16x16x32_bf16 v[50:53], v[166:169], v[174:177], v[50:53]
	v_mfma_f32_16x16x32_bf16 v[38:41], v[158:161], v[182:185], v[38:41]
	v_mfma_f32_16x16x32_bf16 v[34:37], v[166:169], v[182:185], v[34:37]
	v_mfma_f32_16x16x32_bf16 v[22:25], v[158:161], v[190:193], v[22:25]
	v_mfma_f32_16x16x32_bf16 v[18:21], v[166:169], v[190:193], v[18:21]
	v_mfma_f32_16x16x32_bf16 v[6:9], v[158:161], v[198:201], v[6:9]
	v_mfma_f32_16x16x32_bf16 v[2:5], v[166:169], v[198:201], v[2:5]
	s_setprio 0
	s_barrier
	s_add_i32 s50, s50, 2
	s_add_u32 s2, s2, 0x100
	s_addc_u32 s3, s3, 0
	s_cmp_gt_u32 s50, 41
	s_cbranch_scc0 .LBB0_953
	s_cmpk_lt_u32 s25, 0x100
	s_cbranch_scc0 .LBB0_956
	s_barrier

.LBB0_1087:
	s_add_u32 s2, s6, 0x40080
	s_addc_u32 s3, s7, 0
	s_add_u32 s8, s8, 0x100
	s_addc_u32 s9, s9, 0
	s_mov_b32 s22, -2
	s_add_u32 s4, s2, 0xfffc0080
	s_addc_u32 s5, s3, -1
	s_add_i32 s23, 0, 0x10000
	s_cmp_eq_u32 s22, 12
	s_cselect_b32 s5, s49, s5
	s_cselect_b32 s4, s48, s4
	s_waitcnt vmcnt(0)
	v_add_u32_e32 v0, s23, v145
	s_cselect_b32 s7, s97, s9
	s_cselect_b32 s6, s96, s8
	s_add_i32 s25, 0, 0x14000
	ds_read_b128 v[146:149], v0
	ds_read_b128 v[152:155], v0 offset:1024
	ds_read_b128 v[156:159], v0 offset:2048
	ds_read_b128 v[160:163], v0 offset:3072
	ds_read_b128 v[164:167], v0 offset:16384
	ds_read_b128 v[168:171], v0 offset:17408
	ds_read_b128 v[172:175], v0 offset:18432
	ds_read_b128 v[176:179], v0 offset:19456
	ds_read_b128 v[180:183], v150
	ds_read_b128 v[184:187], v150 offset:1024
	ds_read_b128 v[188:191], v150 offset:2048
	ds_read_b128 v[192:195], v150 offset:3072
	ds_read_b128 v[196:199], v150 offset:4096
	ds_read_b128 v[200:203], v150 offset:5120
	ds_read_b128 v[204:207], v150 offset:6144
	ds_read_b128 v[208:211], v150 offset:7168
	s_add_i32 m0, s60, 0xc000
	s_nop 0
	global_load_lds_dwordx4 v131, s[2:3]
	s_add_i32 m0, s60, 0xe000
	s_nop 0
	global_load_lds_dwordx4 v133, s[2:3]
	s_waitcnt vmcnt(8)
	s_waitcnt lgkmcnt(0)
	s_barrier
	s_setprio 1
	s_waitcnt lgkmcnt(0)
	v_mfma_f32_16x16x32_bf16 v[126:129], v[146:149], v[180:183], 0
	v_mfma_f32_16x16x32_bf16 v[122:125], v[156:159], v[180:183], 0
	v_mfma_f32_16x16x32_bf16 v[110:113], v[146:149], v[188:191], 0
	v_mfma_f32_16x16x32_bf16 v[106:109], v[156:159], v[188:191], 0
	v_mfma_f32_16x16x32_bf16 v[94:97], v[146:149], v[196:199], 0
	v_mfma_f32_16x16x32_bf16 v[90:93], v[156:159], v[196:199], 0
	v_mfma_f32_16x16x32_bf16 v[78:81], v[146:149], v[204:207], 0
	v_mfma_f32_16x16x32_bf16 v[74:77], v[156:159], v[204:207], 0
	v_mfma_f32_16x16x32_bf16 v[126:129], v[152:155], v[184:187], v[126:129]
	v_mfma_f32_16x16x32_bf16 v[122:125], v[160:163], v[184:187], v[122:125]
	v_mfma_f32_16x16x32_bf16 v[110:113], v[152:155], v[192:195], v[110:113]
	v_mfma_f32_16x16x32_bf16 v[106:109], v[160:163], v[192:195], v[106:109]
	v_mfma_f32_16x16x32_bf16 v[94:97], v[152:155], v[200:203], v[94:97]
	v_mfma_f32_16x16x32_bf16 v[90:93], v[160:163], v[200:203], v[90:93]
	v_mfma_f32_16x16x32_bf16 v[78:81], v[152:155], v[208:211], v[78:81]
	v_mfma_f32_16x16x32_bf16 v[74:77], v[160:163], v[208:211], v[74:77]
	s_setprio 0
	s_setprio 1
	v_mfma_f32_16x16x32_bf16 v[118:121], v[164:167], v[180:183], 0
	v_mfma_f32_16x16x32_bf16 v[114:117], v[172:175], v[180:183], 0
	v_mfma_f32_16x16x32_bf16 v[102:105], v[164:167], v[188:191], 0
	v_mfma_f32_16x16x32_bf16 v[98:101], v[172:175], v[188:191], 0
	v_mfma_f32_16x16x32_bf16 v[86:89], v[164:167], v[196:199], 0
	v_mfma_f32_16x16x32_bf16 v[82:85], v[172:175], v[196:199], 0
	v_mfma_f32_16x16x32_bf16 v[70:73], v[164:167], v[204:207], 0
	v_mfma_f32_16x16x32_bf16 v[66:69], v[172:175], v[204:207], 0
	v_mfma_f32_16x16x32_bf16 v[118:121], v[168:171], v[184:187], v[118:121]
	v_mfma_f32_16x16x32_bf16 v[114:117], v[176:179], v[184:187], v[114:117]
	v_mfma_f32_16x16x32_bf16 v[102:105], v[168:171], v[192:195], v[102:105]
	v_mfma_f32_16x16x32_bf16 v[98:101], v[176:179], v[192:195], v[98:101]
	v_mfma_f32_16x16x32_bf16 v[86:89], v[168:171], v[200:203], v[86:89]
	v_mfma_f32_16x16x32_bf16 v[82:85], v[176:179], v[200:203], v[82:85]
	v_mfma_f32_16x16x32_bf16 v[70:73], v[168:171], v[208:211], v[70:73]
	v_mfma_f32_16x16x32_bf16 v[66:69], v[176:179], v[208:211], v[66:69]
	s_setprio 0
	s_barrier
	s_add_i32 s23, s23, s42
	ds_read_b128 v[180:183], v150 offset:16384
	ds_read_b128 v[184:187], v150 offset:17408
	ds_read_b128 v[188:191], v150 offset:18432
	ds_read_b128 v[192:195], v150 offset:19456
	ds_read_b128 v[196:199], v150 offset:20480
	ds_read_b128 v[200:203], v150 offset:21504
	ds_read_b128 v[204:207], v150 offset:22528
	ds_read_b128 v[208:211], v150 offset:23552
	s_mov_b32 m0, s23
	s_nop 0
	global_load_lds_dwordx4 v137, s[6:7]
	s_add_i32 m0, s23, 0x2000
	s_add_u32 s46, s6, 0x40000
	global_load_lds_dwordx4 v139, s[6:7]
	s_addc_u32 s47, s7, 0
	s_add_i32 s23, s25, s42
	s_mov_b32 m0, s23
	s_nop 0
	global_load_lds_dwordx4 v137, s[46:47]
	s_add_i32 m0, s23, 0x2000
	s_nop 0
	global_load_lds_dwordx4 v139, s[46:47]
	s_mov_b32 m0, s60
	s_nop 0
	global_load_lds_dwordx4 v131, s[4:5]
	s_mov_b32 m0, s61
	s_nop 0
	global_load_lds_dwordx4 v133, s[4:5]
	s_waitcnt vmcnt(8)
	s_waitcnt lgkmcnt(0)
	s_barrier
	s_setprio 1
	s_waitcnt lgkmcnt(0)
	v_mfma_f32_16x16x32_bf16 v[62:65], v[146:149], v[180:183], 0
	v_mfma_f32_16x16x32_bf16 v[58:61], v[156:159], v[180:183], 0
	v_mfma_f32_16x16x32_bf16 v[46:49], v[146:149], v[188:191], 0
	v_mfma_f32_16x16x32_bf16 v[42:45], v[156:159], v[188:191], 0
	v_mfma_f32_16x16x32_bf16 v[30:33], v[146:149], v[196:199], 0
	v_mfma_f32_16x16x32_bf16 v[26:29], v[156:159], v[196:199], 0
	v_mfma_f32_16x16x32_bf16 v[14:17], v[146:149], v[204:207], 0
	v_mfma_f32_16x16x32_bf16 v[10:13], v[156:159], v[204:207], 0
	v_mfma_f32_16x16x32_bf16 v[62:65], v[152:155], v[184:187], v[62:65]
	v_mfma_f32_16x16x32_bf16 v[58:61], v[160:163], v[184:187], v[58:61]
	v_mfma_f32_16x16x32_bf16 v[46:49], v[152:155], v[192:195], v[46:49]
	v_mfma_f32_16x16x32_bf16 v[42:45], v[160:163], v[192:195], v[42:45]
	v_mfma_f32_16x16x32_bf16 v[30:33], v[152:155], v[200:203], v[30:33]
	v_mfma_f32_16x16x32_bf16 v[26:29], v[160:163], v[200:203], v[26:29]
	v_mfma_f32_16x16x32_bf16 v[14:17], v[152:155], v[208:211], v[14:17]
	v_mfma_f32_16x16x32_bf16 v[10:13], v[160:163], v[208:211], v[10:13]
	s_setprio 0
	s_setprio 1
	v_mfma_f32_16x16x32_bf16 v[54:57], v[164:167], v[180:183], 0
	v_mfma_f32_16x16x32_bf16 v[50:53], v[172:175], v[180:183], 0
	v_mfma_f32_16x16x32_bf16 v[38:41], v[164:167], v[188:191], 0
	v_mfma_f32_16x16x32_bf16 v[34:37], v[172:175], v[188:191], 0
	v_mfma_f32_16x16x32_bf16 v[22:25], v[164:167], v[196:199], 0
	v_mfma_f32_16x16x32_bf16 v[18:21], v[172:175], v[196:199], 0
	v_mfma_f32_16x16x32_bf16 v[6:9], v[164:167], v[204:207], 0
	v_mfma_f32_16x16x32_bf16 v[2:5], v[172:175], v[204:207], 0
	v_mfma_f32_16x16x32_bf16 v[54:57], v[168:171], v[184:187], v[54:57]
	v_mfma_f32_16x16x32_bf16 v[50:53], v[176:179], v[184:187], v[50:53]
	v_mfma_f32_16x16x32_bf16 v[38:41], v[168:171], v[192:195], v[38:41]
	v_mfma_f32_16x16x32_bf16 v[34:37], v[176:179], v[192:195], v[34:37]
	v_mfma_f32_16x16x32_bf16 v[22:25], v[168:171], v[200:203], v[22:25]
	v_mfma_f32_16x16x32_bf16 v[18:21], v[176:179], v[200:203], v[18:21]
	v_mfma_f32_16x16x32_bf16 v[6:9], v[168:171], v[208:211], v[6:9]
	v_mfma_f32_16x16x32_bf16 v[2:5], v[176:179], v[208:211], v[2:5]
	s_setprio 0
	s_barrier
	s_add_i32 s23, 0, 0x18000
	s_add_i32 s25, 0, 0x1c000
	ds_read_b128 v[146:149], v0 offset:32768
	ds_read_b128 v[152:155], v0 offset:33792
	ds_read_b128 v[156:159], v0 offset:34816
	ds_read_b128 v[160:163], v0 offset:35840
	ds_read_b128 v[164:167], v0 offset:49152
	ds_read_b128 v[168:171], v0 offset:50176
	ds_read_b128 v[172:175], v0 offset:51200
	ds_read_b128 v[176:179], v0 offset:52224
	s_add_u32 s46, s4, 0x40000
	s_mov_b32 m0, s66
	ds_read_b128 v[180:183], v150 offset:32768
	ds_read_b128 v[184:187], v150 offset:33792
	ds_read_b128 v[188:191], v150 offset:34816
	ds_read_b128 v[192:195], v150 offset:35840
	ds_read_b128 v[196:199], v150 offset:36864
	ds_read_b128 v[200:203], v150 offset:37888
	ds_read_b128 v[204:207], v150 offset:38912
	ds_read_b128 v[208:211], v150 offset:39936
	s_addc_u32 s47, s5, 0
	s_nop 0
	global_load_lds_dwordx4 v131, s[46:47]
	s_mov_b32 m0, s67
	s_nop 0
	global_load_lds_dwordx4 v133, s[46:47]
	s_waitcnt vmcnt(8)
	s_waitcnt lgkmcnt(0)
	s_barrier
	s_setprio 1
	s_waitcnt lgkmcnt(0)
	v_mfma_f32_16x16x32_bf16 v[126:129], v[146:149], v[180:183], v[126:129]
	v_mfma_f32_16x16x32_bf16 v[122:125], v[156:159], v[180:183], v[122:125]
	v_mfma_f32_16x16x32_bf16 v[110:113], v[146:149], v[188:191], v[110:113]
	v_mfma_f32_16x16x32_bf16 v[106:109], v[156:159], v[188:191], v[106:109]
	v_mfma_f32_16x16x32_bf16 v[94:97], v[146:149], v[196:199], v[94:97]
	v_mfma_f32_16x16x32_bf16 v[90:93], v[156:159], v[196:199], v[90:93]
	v_mfma_f32_16x16x32_bf16 v[78:81], v[146:149], v[204:207], v[78:81]
	v_mfma_f32_16x16x32_bf16 v[74:77], v[156:159], v[204:207], v[74:77]
	v_mfma_f32_16x16x32_bf16 v[126:129], v[152:155], v[184:187], v[126:129]
	v_mfma_f32_16x16x32_bf16 v[122:125], v[160:163], v[184:187], v[122:125]
	v_mfma_f32_16x16x32_bf16 v[110:113], v[152:155], v[192:195], v[110:113]
	v_mfma_f32_16x16x32_bf16 v[106:109], v[160:163], v[192:195], v[106:109]
	v_mfma_f32_16x16x32_bf16 v[94:97], v[152:155], v[200:203], v[94:97]
	v_mfma_f32_16x16x32_bf16 v[90:93], v[160:163], v[200:203], v[90:93]
	v_mfma_f32_16x16x32_bf16 v[78:81], v[152:155], v[208:211], v[78:81]
	v_mfma_f32_16x16x32_bf16 v[74:77], v[160:163], v[208:211], v[74:77]
	s_setprio 0
	s_setprio 1
	v_mfma_f32_16x16x32_bf16 v[118:121], v[164:167], v[180:183], v[118:121]
	v_mfma_f32_16x16x32_bf16 v[114:117], v[172:175], v[180:183], v[114:117]
	v_mfma_f32_16x16x32_bf16 v[102:105], v[164:167], v[188:191], v[102:105]
	v_mfma_f32_16x16x32_bf16 v[98:101], v[172:175], v[188:191], v[98:101]
	v_mfma_f32_16x16x32_bf16 v[86:89], v[164:167], v[196:199], v[86:89]
	v_mfma_f32_16x16x32_bf16 v[82:85], v[172:175], v[196:199], v[82:85]
	v_mfma_f32_16x16x32_bf16 v[70:73], v[164:167], v[204:207], v[70:73]
	v_mfma_f32_16x16x32_bf16 v[66:69], v[172:175], v[204:207], v[66:69]
	v_mfma_f32_16x16x32_bf16 v[118:121], v[168:171], v[184:187], v[118:121]
	v_mfma_f32_16x16x32_bf16 v[114:117], v[176:179], v[184:187], v[114:117]
	v_mfma_f32_16x16x32_bf16 v[102:105], v[168:171], v[192:195], v[102:105]
	v_mfma_f32_16x16x32_bf16 v[98:101], v[176:179], v[192:195], v[98:101]
	v_mfma_f32_16x16x32_bf16 v[86:89], v[168:171], v[200:203], v[86:89]
	v_mfma_f32_16x16x32_bf16 v[82:85], v[176:179], v[200:203], v[82:85]
	v_mfma_f32_16x16x32_bf16 v[70:73], v[168:171], v[208:211], v[70:73]
	v_mfma_f32_16x16x32_bf16 v[66:69], v[176:179], v[208:211], v[66:69]
	s_setprio 0
	s_barrier
	ds_read_b128 v[180:183], v150 offset:49152
	ds_read_b128 v[184:187], v150 offset:50176
	ds_read_b128 v[188:191], v150 offset:51200
	ds_read_b128 v[192:195], v150 offset:52224
	ds_read_b128 v[196:199], v150 offset:53248
	ds_read_b128 v[200:203], v150 offset:54272
	ds_read_b128 v[204:207], v150 offset:55296
	ds_read_b128 v[208:211], v150 offset:56320
	s_add_i32 s23, s23, s42
	s_add_u32 s100, s6, s38
	s_addc_u32 s101, s7, s39
	s_mov_b32 m0, s23
	s_nop 0
	global_load_lds_dwordx4 v137, s[100:101]
	s_add_i32 m0, s23, 0x2000
	s_nop 0
	s_add_u32 s6, s6, 0x40080
	s_addc_u32 s7, s7, 0
	s_add_i32 s23, s25, s42
	global_load_lds_dwordx4 v139, s[100:101]
	s_mov_b32 m0, s23
	s_nop 0
	global_load_lds_dwordx4 v137, s[6:7]
	s_add_i32 m0, s23, 0x2000
	s_nop 0
	global_load_lds_dwordx4 v139, s[6:7]
	s_mov_b32 m0, s70
	s_add_u32 s100, s4, s38
	s_addc_u32 s101, s5, s39
	v_mov_b32_e32 v0, v133
	global_load_lds_dwordx4 v131, s[100:101]
	s_mov_b32 m0, s71
	s_nop 0
	global_load_lds_dwordx4 v133, s[100:101]
	s_waitcnt vmcnt(8)
	s_waitcnt lgkmcnt(0)
	s_barrier
	s_setprio 1
	s_waitcnt lgkmcnt(0)
	v_mfma_f32_16x16x32_bf16 v[62:65], v[146:149], v[180:183], v[62:65]
	v_mfma_f32_16x16x32_bf16 v[58:61], v[156:159], v[180:183], v[58:61]
	v_mfma_f32_16x16x32_bf16 v[46:49], v[146:149], v[188:191], v[46:49]
	v_mfma_f32_16x16x32_bf16 v[42:45], v[156:159], v[188:191], v[42:45]
	v_mfma_f32_16x16x32_bf16 v[30:33], v[146:149], v[196:199], v[30:33]
	v_mfma_f32_16x16x32_bf16 v[26:29], v[156:159], v[196:199], v[26:29]
	v_mfma_f32_16x16x32_bf16 v[14:17], v[146:149], v[204:207], v[14:17]
	v_mfma_f32_16x16x32_bf16 v[10:13], v[156:159], v[204:207], v[10:13]
	v_mfma_f32_16x16x32_bf16 v[62:65], v[152:155], v[184:187], v[62:65]
	v_mfma_f32_16x16x32_bf16 v[58:61], v[160:163], v[184:187], v[58:61]
	v_mfma_f32_16x16x32_bf16 v[46:49], v[152:155], v[192:195], v[46:49]
	v_mfma_f32_16x16x32_bf16 v[42:45], v[160:163], v[192:195], v[42:45]
	v_mfma_f32_16x16x32_bf16 v[30:33], v[152:155], v[200:203], v[30:33]
	v_mfma_f32_16x16x32_bf16 v[26:29], v[160:163], v[200:203], v[26:29]
	v_mfma_f32_16x16x32_bf16 v[14:17], v[152:155], v[208:211], v[14:17]
	v_mfma_f32_16x16x32_bf16 v[10:13], v[160:163], v[208:211], v[10:13]
	s_setprio 0
	s_setprio 1
	v_mfma_f32_16x16x32_bf16 v[54:57], v[164:167], v[180:183], v[54:57]
	v_mfma_f32_16x16x32_bf16 v[50:53], v[172:175], v[180:183], v[50:53]
	v_mfma_f32_16x16x32_bf16 v[38:41], v[164:167], v[188:191], v[38:41]
	v_mfma_f32_16x16x32_bf16 v[34:37], v[172:175], v[188:191], v[34:37]
	v_mfma_f32_16x16x32_bf16 v[22:25], v[164:167], v[196:199], v[22:25]
	v_mfma_f32_16x16x32_bf16 v[18:21], v[172:175], v[196:199], v[18:21]
	v_mfma_f32_16x16x32_bf16 v[6:9], v[164:167], v[204:207], v[6:9]
	v_mfma_f32_16x16x32_bf16 v[2:5], v[172:175], v[204:207], v[2:5]
	v_mfma_f32_16x16x32_bf16 v[54:57], v[168:171], v[184:187], v[54:57]
	v_mfma_f32_16x16x32_bf16 v[50:53], v[176:179], v[184:187], v[50:53]
	v_mfma_f32_16x16x32_bf16 v[38:41], v[168:171], v[192:195], v[38:41]
	v_mfma_f32_16x16x32_bf16 v[34:37], v[176:179], v[192:195], v[34:37]
	v_mfma_f32_16x16x32_bf16 v[22:25], v[168:171], v[200:203], v[22:25]
	v_mfma_f32_16x16x32_bf16 v[18:21], v[176:179], v[200:203], v[18:21]
	v_mfma_f32_16x16x32_bf16 v[6:9], v[168:171], v[208:211], v[6:9]
	v_mfma_f32_16x16x32_bf16 v[2:5], v[176:179], v[208:211], v[2:5]
	s_setprio 0
	s_barrier
	s_add_i32 s22, s22, 2
	s_add_u32 s2, s2, 0x100
	s_addc_u32 s3, s3, 0
	s_add_u32 s8, s8, 0x100
	s_addc_u32 s9, s9, 0
	s_cmp_gt_u32 s22, 13
	s_cbranch_scc0 .LBB0_1088
	s_branch .Lpeel_exit_1088
.LBB0_1088:
	s_add_u32 s4, s2, 0xfffc0080
	s_addc_u32 s5, s3, -1
	s_add_i32 s23, 0, 0x10000
	s_cmp_eq_u32 s22, 12
	s_cselect_b32 s5, s49, s5
	s_cselect_b32 s4, s48, s4
	v_add_u32_e32 v0, s23, v145
	s_cselect_b32 s7, s97, s9
	s_cselect_b32 s6, s96, s8
	s_add_i32 s25, 0, 0x14000
	ds_read_b128 v[146:149], v0
	ds_read_b128 v[152:155], v0 offset:1024
	ds_read_b128 v[156:159], v0 offset:2048
	ds_read_b128 v[160:163], v0 offset:3072
	ds_read_b128 v[164:167], v0 offset:16384
	ds_read_b128 v[168:171], v0 offset:17408
	ds_read_b128 v[172:175], v0 offset:18432
	ds_read_b128 v[176:179], v0 offset:19456
	ds_read_b128 v[180:183], v150
	ds_read_b128 v[184:187], v150 offset:1024
	ds_read_b128 v[188:191], v150 offset:2048
	ds_read_b128 v[192:195], v150 offset:3072
	ds_read_b128 v[196:199], v150 offset:4096
	ds_read_b128 v[200:203], v150 offset:5120
	ds_read_b128 v[204:207], v150 offset:6144
	ds_read_b128 v[208:211], v150 offset:7168
	s_add_i32 m0, s60, 0xc000
	s_nop 0
	global_load_lds_dwordx4 v131, s[2:3]
	s_add_i32 m0, s60, 0xe000
	s_nop 0
	global_load_lds_dwordx4 v133, s[2:3]
	s_waitcnt vmcnt(8)
	s_waitcnt lgkmcnt(0)
	s_barrier
	s_setprio 1
	s_waitcnt lgkmcnt(0)
	v_mfma_f32_16x16x32_bf16 v[126:129], v[146:149], v[180:183], v[126:129]
	v_mfma_f32_16x16x32_bf16 v[122:125], v[156:159], v[180:183], v[122:125]
	v_mfma_f32_16x16x32_bf16 v[110:113], v[146:149], v[188:191], v[110:113]
	v_mfma_f32_16x16x32_bf16 v[106:109], v[156:159], v[188:191], v[106:109]
	v_mfma_f32_16x16x32_bf16 v[94:97], v[146:149], v[196:199], v[94:97]
	v_mfma_f32_16x16x32_bf16 v[90:93], v[156:159], v[196:199], v[90:93]
	v_mfma_f32_16x16x32_bf16 v[78:81], v[146:149], v[204:207], v[78:81]
	v_mfma_f32_16x16x32_bf16 v[74:77], v[156:159], v[204:207], v[74:77]
	v_mfma_f32_16x16x32_bf16 v[126:129], v[152:155], v[184:187], v[126:129]
	v_mfma_f32_16x16x32_bf16 v[122:125], v[160:163], v[184:187], v[122:125]
	v_mfma_f32_16x16x32_bf16 v[110:113], v[152:155], v[192:195], v[110:113]
	v_mfma_f32_16x16x32_bf16 v[106:109], v[160:163], v[192:195], v[106:109]
	v_mfma_f32_16x16x32_bf16 v[94:97], v[152:155], v[200:203], v[94:97]
	v_mfma_f32_16x16x32_bf16 v[90:93], v[160:163], v[200:203], v[90:93]
	v_mfma_f32_16x16x32_bf16 v[78:81], v[152:155], v[208:211], v[78:81]
	v_mfma_f32_16x16x32_bf16 v[74:77], v[160:163], v[208:211], v[74:77]
	s_setprio 0
	s_setprio 1
	v_mfma_f32_16x16x32_bf16 v[118:121], v[164:167], v[180:183], v[118:121]
	v_mfma_f32_16x16x32_bf16 v[114:117], v[172:175], v[180:183], v[114:117]
	v_mfma_f32_16x16x32_bf16 v[102:105], v[164:167], v[188:191], v[102:105]
	v_mfma_f32_16x16x32_bf16 v[98:101], v[172:175], v[188:191], v[98:101]
	v_mfma_f32_16x16x32_bf16 v[86:89], v[164:167], v[196:199], v[86:89]
	v_mfma_f32_16x16x32_bf16 v[82:85], v[172:175], v[196:199], v[82:85]
	v_mfma_f32_16x16x32_bf16 v[70:73], v[164:167], v[204:207], v[70:73]
	v_mfma_f32_16x16x32_bf16 v[66:69], v[172:175], v[204:207], v[66:69]
	v_mfma_f32_16x16x32_bf16 v[118:121], v[168:171], v[184:187], v[118:121]
	v_mfma_f32_16x16x32_bf16 v[114:117], v[176:179], v[184:187], v[114:117]
	v_mfma_f32_16x16x32_bf16 v[102:105], v[168:171], v[192:195], v[102:105]
	v_mfma_f32_16x16x32_bf16 v[98:101], v[176:179], v[192:195], v[98:101]
	v_mfma_f32_16x16x32_bf16 v[86:89], v[168:171], v[200:203], v[86:89]
	v_mfma_f32_16x16x32_bf16 v[82:85], v[176:179], v[200:203], v[82:85]
	v_mfma_f32_16x16x32_bf16 v[70:73], v[168:171], v[208:211], v[70:73]
	v_mfma_f32_16x16x32_bf16 v[66:69], v[176:179], v[208:211], v[66:69]
	s_setprio 0
	s_barrier
	s_add_i32 s23, s23, s42
	ds_read_b128 v[180:183], v150 offset:16384
	ds_read_b128 v[184:187], v150 offset:17408
	ds_read_b128 v[188:191], v150 offset:18432
	ds_read_b128 v[192:195], v150 offset:19456
	ds_read_b128 v[196:199], v150 offset:20480
	ds_read_b128 v[200:203], v150 offset:21504
	ds_read_b128 v[204:207], v150 offset:22528
	ds_read_b128 v[208:211], v150 offset:23552
	s_mov_b32 m0, s23
	s_nop 0
	global_load_lds_dwordx4 v137, s[6:7]
	s_add_i32 m0, s23, 0x2000
	s_add_u32 s46, s6, 0x40000
	global_load_lds_dwordx4 v139, s[6:7]
	s_addc_u32 s47, s7, 0
	s_add_i32 s23, s25, s42
	s_mov_b32 m0, s23
	s_nop 0
	global_load_lds_dwordx4 v137, s[46:47]
	s_add_i32 m0, s23, 0x2000
	s_nop 0
	global_load_lds_dwordx4 v139, s[46:47]
	s_mov_b32 m0, s60
	s_nop 0
	global_load_lds_dwordx4 v131, s[4:5]
	s_mov_b32 m0, s61
	s_nop 0
	global_load_lds_dwordx4 v133, s[4:5]
	s_waitcnt vmcnt(8)
	s_waitcnt lgkmcnt(0)
	s_barrier
	s_setprio 1
	s_waitcnt lgkmcnt(0)
	v_mfma_f32_16x16x32_bf16 v[62:65], v[146:149], v[180:183], v[62:65]
	v_mfma_f32_16x16x32_bf16 v[58:61], v[156:159], v[180:183], v[58:61]
	v_mfma_f32_16x16x32_bf16 v[46:49], v[146:149], v[188:191], v[46:49]
	v_mfma_f32_16x16x32_bf16 v[42:45], v[156:159], v[188:191], v[42:45]
	v_mfma_f32_16x16x32_bf16 v[30:33], v[146:149], v[196:199], v[30:33]
	v_mfma_f32_16x16x32_bf16 v[26:29], v[156:159], v[196:199], v[26:29]
	v_mfma_f32_16x16x32_bf16 v[14:17], v[146:149], v[204:207], v[14:17]
	v_mfma_f32_16x16x32_bf16 v[10:13], v[156:159], v[204:207], v[10:13]
	v_mfma_f32_16x16x32_bf16 v[62:65], v[152:155], v[184:187], v[62:65]
	v_mfma_f32_16x16x32_bf16 v[58:61], v[160:163], v[184:187], v[58:61]
	v_mfma_f32_16x16x32_bf16 v[46:49], v[152:155], v[192:195], v[46:49]
	v_mfma_f32_16x16x32_bf16 v[42:45], v[160:163], v[192:195], v[42:45]
	v_mfma_f32_16x16x32_bf16 v[30:33], v[152:155], v[200:203], v[30:33]
	v_mfma_f32_16x16x32_bf16 v[26:29], v[160:163], v[200:203], v[26:29]
	v_mfma_f32_16x16x32_bf16 v[14:17], v[152:155], v[208:211], v[14:17]
	v_mfma_f32_16x16x32_bf16 v[10:13], v[160:163], v[208:211], v[10:13]
	s_setprio 0
	s_setprio 1
	v_mfma_f32_16x16x32_bf16 v[54:57], v[164:167], v[180:183], v[54:57]
	v_mfma_f32_16x16x32_bf16 v[50:53], v[172:175], v[180:183], v[50:53]
	v_mfma_f32_16x16x32_bf16 v[38:41], v[164:167], v[188:191], v[38:41]
	v_mfma_f32_16x16x32_bf16 v[34:37], v[172:175], v[188:191], v[34:37]
	v_mfma_f32_16x16x32_bf16 v[22:25], v[164:167], v[196:199], v[22:25]
	v_mfma_f32_16x16x32_bf16 v[18:21], v[172:175], v[196:199], v[18:21]
	v_mfma_f32_16x16x32_bf16 v[6:9], v[164:167], v[204:207], v[6:9]
	v_mfma_f32_16x16x32_bf16 v[2:5], v[172:175], v[204:207], v[2:5]
	v_mfma_f32_16x16x32_bf16 v[54:57], v[168:171], v[184:187], v[54:57]
	v_mfma_f32_16x16x32_bf16 v[50:53], v[176:179], v[184:187], v[50:53]
	v_mfma_f32_16x16x32_bf16 v[38:41], v[168:171], v[192:195], v[38:41]
	v_mfma_f32_16x16x32_bf16 v[34:37], v[176:179], v[192:195], v[34:37]
	v_mfma_f32_16x16x32_bf16 v[22:25], v[168:171], v[200:203], v[22:25]
	v_mfma_f32_16x16x32_bf16 v[18:21], v[176:179], v[200:203], v[18:21]
	v_mfma_f32_16x16x32_bf16 v[6:9], v[168:171], v[208:211], v[6:9]
	v_mfma_f32_16x16x32_bf16 v[2:5], v[176:179], v[208:211], v[2:5]
	s_setprio 0
	s_barrier
	s_add_i32 s23, 0, 0x18000
	s_add_i32 s25, 0, 0x1c000
	ds_read_b128 v[146:149], v0 offset:32768
	ds_read_b128 v[152:155], v0 offset:33792
	ds_read_b128 v[156:159], v0 offset:34816
	ds_read_b128 v[160:163], v0 offset:35840
	ds_read_b128 v[164:167], v0 offset:49152
	ds_read_b128 v[168:171], v0 offset:50176
	ds_read_b128 v[172:175], v0 offset:51200
	ds_read_b128 v[176:179], v0 offset:52224
	s_add_u32 s46, s4, 0x40000
	s_mov_b32 m0, s66
	ds_read_b128 v[180:183], v150 offset:32768
	ds_read_b128 v[184:187], v150 offset:33792
	ds_read_b128 v[188:191], v150 offset:34816
	ds_read_b128 v[192:195], v150 offset:35840
	ds_read_b128 v[196:199], v150 offset:36864
	ds_read_b128 v[200:203], v150 offset:37888
	ds_read_b128 v[204:207], v150 offset:38912
	ds_read_b128 v[208:211], v150 offset:39936
	s_addc_u32 s47, s5, 0
	s_nop 0
	global_load_lds_dwordx4 v131, s[46:47]
	s_mov_b32 m0, s67
	s_nop 0
	global_load_lds_dwordx4 v133, s[46:47]
	s_waitcnt vmcnt(8)
	s_waitcnt lgkmcnt(0)
	s_barrier
	s_setprio 1
	s_waitcnt lgkmcnt(0)
	v_mfma_f32_16x16x32_bf16 v[126:129], v[146:149], v[180:183], v[126:129]
	v_mfma_f32_16x16x32_bf16 v[122:125], v[156:159], v[180:183], v[122:125]
	v_mfma_f32_16x16x32_bf16 v[110:113], v[146:149], v[188:191], v[110:113]
	v_mfma_f32_16x16x32_bf16 v[106:109], v[156:159], v[188:191], v[106:109]
	v_mfma_f32_16x16x32_bf16 v[94:97], v[146:149], v[196:199], v[94:97]
	v_mfma_f32_16x16x32_bf16 v[90:93], v[156:159], v[196:199], v[90:93]
	v_mfma_f32_16x16x32_bf16 v[78:81], v[146:149], v[204:207], v[78:81]
	v_mfma_f32_16x16x32_bf16 v[74:77], v[156:159], v[204:207], v[74:77]
	v_mfma_f32_16x16x32_bf16 v[126:129], v[152:155], v[184:187], v[126:129]
	v_mfma_f32_16x16x32_bf16 v[122:125], v[160:163], v[184:187], v[122:125]
	v_mfma_f32_16x16x32_bf16 v[110:113], v[152:155], v[192:195], v[110:113]
	v_mfma_f32_16x16x32_bf16 v[106:109], v[160:163], v[192:195], v[106:109]
	v_mfma_f32_16x16x32_bf16 v[94:97], v[152:155], v[200:203], v[94:97]
	v_mfma_f32_16x16x32_bf16 v[90:93], v[160:163], v[200:203], v[90:93]
	v_mfma_f32_16x16x32_bf16 v[78:81], v[152:155], v[208:211], v[78:81]
	v_mfma_f32_16x16x32_bf16 v[74:77], v[160:163], v[208:211], v[74:77]
	s_setprio 0
	s_setprio 1
	v_mfma_f32_16x16x32_bf16 v[118:121], v[164:167], v[180:183], v[118:121]
	v_mfma_f32_16x16x32_bf16 v[114:117], v[172:175], v[180:183], v[114:117]
	v_mfma_f32_16x16x32_bf16 v[102:105], v[164:167], v[188:191], v[102:105]
	v_mfma_f32_16x16x32_bf16 v[98:101], v[172:175], v[188:191], v[98:101]
	v_mfma_f32_16x16x32_bf16 v[86:89], v[164:167], v[196:199], v[86:89]
	v_mfma_f32_16x16x32_bf16 v[82:85], v[172:175], v[196:199], v[82:85]
	v_mfma_f32_16x16x32_bf16 v[70:73], v[164:167], v[204:207], v[70:73]
	v_mfma_f32_16x16x32_bf16 v[66:69], v[172:175], v[204:207], v[66:69]
	v_mfma_f32_16x16x32_bf16 v[118:121], v[168:171], v[184:187], v[118:121]
	v_mfma_f32_16x16x32_bf16 v[114:117], v[176:179], v[184:187], v[114:117]
	v_mfma_f32_16x16x32_bf16 v[102:105], v[168:171], v[192:195], v[102:105]
	v_mfma_f32_16x16x32_bf16 v[98:101], v[176:179], v[192:195], v[98:101]
	v_mfma_f32_16x16x32_bf16 v[86:89], v[168:171], v[200:203], v[86:89]
	v_mfma_f32_16x16x32_bf16 v[82:85], v[176:179], v[200:203], v[82:85]
	v_mfma_f32_16x16x32_bf16 v[70:73], v[168:171], v[208:211], v[70:73]
	v_mfma_f32_16x16x32_bf16 v[66:69], v[176:179], v[208:211], v[66:69]
	s_setprio 0
	s_barrier
	ds_read_b128 v[180:183], v150 offset:49152
	ds_read_b128 v[184:187], v150 offset:50176
	ds_read_b128 v[188:191], v150 offset:51200
	ds_read_b128 v[192:195], v150 offset:52224
	ds_read_b128 v[196:199], v150 offset:53248
	ds_read_b128 v[200:203], v150 offset:54272
	ds_read_b128 v[204:207], v150 offset:55296
	ds_read_b128 v[208:211], v150 offset:56320
	s_add_i32 s23, s23, s42
	s_add_u32 s100, s6, s38
	s_addc_u32 s101, s7, s39
	s_mov_b32 m0, s23
	s_nop 0
	global_load_lds_dwordx4 v137, s[100:101]
	s_add_i32 m0, s23, 0x2000
	s_nop 0
	s_add_u32 s6, s6, 0x40080
	s_addc_u32 s7, s7, 0
	s_add_i32 s23, s25, s42
	global_load_lds_dwordx4 v139, s[100:101]
	s_mov_b32 m0, s23
	s_nop 0
	global_load_lds_dwordx4 v137, s[6:7]
	s_add_i32 m0, s23, 0x2000
	s_nop 0
	global_load_lds_dwordx4 v139, s[6:7]
	s_mov_b32 m0, s70
	s_add_u32 s100, s4, s38
	s_addc_u32 s101, s5, s39
	v_mov_b32_e32 v0, v133
	global_load_lds_dwordx4 v131, s[100:101]
	s_mov_b32 m0, s71
	s_nop 0
	global_load_lds_dwordx4 v133, s[100:101]
	s_waitcnt vmcnt(8)
	s_waitcnt lgkmcnt(0)
	s_barrier
	s_setprio 1
	s_waitcnt lgkmcnt(0)
	v_mfma_f32_16x16x32_bf16 v[62:65], v[146:149], v[180:183], v[62:65]
	v_mfma_f32_16x16x32_bf16 v[58:61], v[156:159], v[180:183], v[58:61]
	v_mfma_f32_16x16x32_bf16 v[46:49], v[146:149], v[188:191], v[46:49]
	v_mfma_f32_16x16x32_bf16 v[42:45], v[156:159], v[188:191], v[42:45]
	v_mfma_f32_16x16x32_bf16 v[30:33], v[146:149], v[196:199], v[30:33]
	v_mfma_f32_16x16x32_bf16 v[26:29], v[156:159], v[196:199], v[26:29]
	v_mfma_f32_16x16x32_bf16 v[14:17], v[146:149], v[204:207], v[14:17]
	v_mfma_f32_16x16x32_bf16 v[10:13], v[156:159], v[204:207], v[10:13]
	v_mfma_f32_16x16x32_bf16 v[62:65], v[152:155], v[184:187], v[62:65]
	v_mfma_f32_16x16x32_bf16 v[58:61], v[160:163], v[184:187], v[58:61]
	v_mfma_f32_16x16x32_bf16 v[46:49], v[152:155], v[192:195], v[46:49]
	v_mfma_f32_16x16x32_bf16 v[42:45], v[160:163], v[192:195], v[42:45]
	v_mfma_f32_16x16x32_bf16 v[30:33], v[152:155], v[200:203], v[30:33]
	v_mfma_f32_16x16x32_bf16 v[26:29], v[160:163], v[200:203], v[26:29]
	v_mfma_f32_16x16x32_bf16 v[14:17], v[152:155], v[208:211], v[14:17]
	v_mfma_f32_16x16x32_bf16 v[10:13], v[160:163], v[208:211], v[10:13]
	s_setprio 0
	s_setprio 1
	v_mfma_f32_16x16x32_bf16 v[54:57], v[164:167], v[180:183], v[54:57]
	v_mfma_f32_16x16x32_bf16 v[50:53], v[172:175], v[180:183], v[50:53]
	v_mfma_f32_16x16x32_bf16 v[38:41], v[164:167], v[188:191], v[38:41]
	v_mfma_f32_16x16x32_bf16 v[34:37], v[172:175], v[188:191], v[34:37]
	v_mfma_f32_16x16x32_bf16 v[22:25], v[164:167], v[196:199], v[22:25]
	v_mfma_f32_16x16x32_bf16 v[18:21], v[172:175], v[196:199], v[18:21]
	v_mfma_f32_16x16x32_bf16 v[6:9], v[164:167], v[204:207], v[6:9]
	v_mfma_f32_16x16x32_bf16 v[2:5], v[172:175], v[204:207], v[2:5]
	v_mfma_f32_16x16x32_bf16 v[54:57], v[168:171], v[184:187], v[54:57]
	v_mfma_f32_16x16x32_bf16 v[50:53], v[176:179], v[184:187], v[50:53]
	v_mfma_f32_16x16x32_bf16 v[38:41], v[168:171], v[192:195], v[38:41]
	v_mfma_f32_16x16x32_bf16 v[34:37], v[176:179], v[192:195], v[34:37]
	v_mfma_f32_16x16x32_bf16 v[22:25], v[168:171], v[200:203], v[22:25]
	v_mfma_f32_16x16x32_bf16 v[18:21], v[176:179], v[200:203], v[18:21]
	v_mfma_f32_16x16x32_bf16 v[6:9], v[168:171], v[208:211], v[6:9]
	v_mfma_f32_16x16x32_bf16 v[2:5], v[176:179], v[208:211], v[2:5]
	s_setprio 0
	s_barrier
	s_add_i32 s22, s22, 2
	s_add_u32 s2, s2, 0x100
	s_addc_u32 s3, s3, 0
	s_add_u32 s8, s8, 0x100
	s_addc_u32 s9, s9, 0
	s_cmp_gt_u32 s22, 13
	s_cbranch_scc0 .LBB0_1088

.LBB0_1473:
	s_add_u32 s16, s4, s14
	s_addc_u32 s17, s5, s15
	s_add_u32 s22, s16, 0x100
	s_addc_u32 s23, s17, 0
	s_and_b64 s[10:11], s[12:13], exec
	s_cselect_b32 s11, s5, s23
	s_cselect_b32 s10, s4, s22
	s_add_u32 s14, s6, s14
	s_addc_u32 s15, s7, s15
	s_add_u32 s14, s14, 0x100
	s_addc_u32 s15, s15, 0
	s_add_i32 s69, 0, 0x10000
	s_and_b64 s[12:13], s[12:13], exec
	s_cselect_b32 s13, s7, s15
	s_cselect_b32 s12, s6, s14
	s_add_i32 s15, 0, 0x14000
	s_add_u32 s46, s16, 0x80080
	s_addc_u32 s47, s17, 0
	s_add_i32 s71, s69, s41
	s_add_i32 m0, s42, 0xc000
	s_add_i32 s74, s42, 0xe000
	s_add_i32 s67, s71, 0x2000
	v_add_u32_e32 v0, s69, v136
	s_add_u32 s22, s12, 0x40000
	ds_read_b128 v[138:141], v0
	ds_read_b128 v[142:145], v0 offset:1024
	ds_read_b128 v[146:149], v0 offset:2048
	ds_read_b128 v[150:153], v0 offset:3072
	s_addc_u32 s23, s13, 0
	s_add_i32 s68, s15, s41
	ds_read_b128 v[154:157], v0 offset:16384
	ds_read_b128 v[158:161], v0 offset:17408
	ds_read_b128 v[162:165], v0 offset:18432
	ds_read_b128 v[166:169], v0 offset:19456
	s_add_i32 s66, s68, 0x2000
	s_add_i32 s65, 0, 0x18000
	s_add_i32 s64, 0, 0x1c000
	s_add_u32 s16, s10, 0x80000
	s_addc_u32 s17, s11, 0
	s_add_i32 s61, s65, s41
	s_add_i32 s60, s61, 0x2000
	s_add_u32 s14, s12, 0x40080
	s_addc_u32 s15, s13, 0
	s_add_i32 s70, s64, s41
	s_add_i32 s69, s70, 0x2000
	ds_read_b128 v[170:173], v137
	ds_read_b128 v[174:177], v137 offset:1024
	ds_read_b128 v[178:181], v137 offset:2048
	ds_read_b128 v[182:185], v137 offset:3072
	ds_read_b128 v[186:189], v137 offset:4096
	ds_read_b128 v[190:193], v137 offset:5120
	ds_read_b128 v[194:197], v137 offset:6144
	ds_read_b128 v[198:201], v137 offset:7168
	s_nop 0
	global_load_lds_dwordx4 v130, s[46:47]
	s_mov_b32 m0, s74
	s_nop 0
	global_load_lds_dwordx4 v132, s[46:47]
	s_waitcnt vmcnt(8)
	s_waitcnt lgkmcnt(0)
	s_barrier
	s_setprio 1
	s_waitcnt lgkmcnt(0)
	v_mfma_f32_16x16x32_bf16 v[126:129], v[138:141], v[170:173], v[126:129]
	v_mfma_f32_16x16x32_bf16 v[122:125], v[146:149], v[170:173], v[122:125]
	v_mfma_f32_16x16x32_bf16 v[118:121], v[138:141], v[178:181], v[118:121]
	v_mfma_f32_16x16x32_bf16 v[110:113], v[146:149], v[178:181], v[110:113]
	v_mfma_f32_16x16x32_bf16 v[102:105], v[138:141], v[186:189], v[102:105]
	v_mfma_f32_16x16x32_bf16 v[94:97], v[146:149], v[186:189], v[94:97]
	v_mfma_f32_16x16x32_bf16 v[86:89], v[138:141], v[194:197], v[86:89]
	v_mfma_f32_16x16x32_bf16 v[78:81], v[146:149], v[194:197], v[78:81]
	v_mfma_f32_16x16x32_bf16 v[126:129], v[142:145], v[174:177], v[126:129]
	v_mfma_f32_16x16x32_bf16 v[122:125], v[150:153], v[174:177], v[122:125]
	v_mfma_f32_16x16x32_bf16 v[118:121], v[142:145], v[182:185], v[118:121]
	v_mfma_f32_16x16x32_bf16 v[110:113], v[150:153], v[182:185], v[110:113]
	v_mfma_f32_16x16x32_bf16 v[102:105], v[142:145], v[190:193], v[102:105]
	v_mfma_f32_16x16x32_bf16 v[94:97], v[150:153], v[190:193], v[94:97]
	v_mfma_f32_16x16x32_bf16 v[86:89], v[142:145], v[198:201], v[86:89]
	v_mfma_f32_16x16x32_bf16 v[78:81], v[150:153], v[198:201], v[78:81]
	s_setprio 0
	s_setprio 1
	v_mfma_f32_16x16x32_bf16 v[114:117], v[154:157], v[170:173], v[114:117]
	v_mfma_f32_16x16x32_bf16 v[106:109], v[162:165], v[170:173], v[106:109]
	v_mfma_f32_16x16x32_bf16 v[98:101], v[154:157], v[178:181], v[98:101]
	v_mfma_f32_16x16x32_bf16 v[90:93], v[162:165], v[178:181], v[90:93]
	v_mfma_f32_16x16x32_bf16 v[82:85], v[154:157], v[186:189], v[82:85]
	v_mfma_f32_16x16x32_bf16 v[74:77], v[162:165], v[186:189], v[74:77]
	v_mfma_f32_16x16x32_bf16 v[70:73], v[154:157], v[194:197], v[70:73]
	v_mfma_f32_16x16x32_bf16 v[62:65], v[162:165], v[194:197], v[62:65]
	v_mfma_f32_16x16x32_bf16 v[114:117], v[158:161], v[174:177], v[114:117]
	v_mfma_f32_16x16x32_bf16 v[106:109], v[166:169], v[174:177], v[106:109]
	v_mfma_f32_16x16x32_bf16 v[98:101], v[158:161], v[182:185], v[98:101]
	v_mfma_f32_16x16x32_bf16 v[90:93], v[166:169], v[182:185], v[90:93]
	v_mfma_f32_16x16x32_bf16 v[82:85], v[158:161], v[190:193], v[82:85]
	v_mfma_f32_16x16x32_bf16 v[74:77], v[166:169], v[190:193], v[74:77]
	v_mfma_f32_16x16x32_bf16 v[70:73], v[158:161], v[198:201], v[70:73]
	v_mfma_f32_16x16x32_bf16 v[62:65], v[166:169], v[198:201], v[62:65]
	s_setprio 0
	s_barrier
	s_mov_b32 m0, s71
	ds_read_b128 v[170:173], v137 offset:16384
	ds_read_b128 v[174:177], v137 offset:17408
	ds_read_b128 v[178:181], v137 offset:18432
	ds_read_b128 v[182:185], v137 offset:19456
	ds_read_b128 v[186:189], v137 offset:20480
	ds_read_b128 v[190:193], v137 offset:21504
	ds_read_b128 v[194:197], v137 offset:22528
	ds_read_b128 v[198:201], v137 offset:23552
	s_nop 0
	global_load_lds_dwordx4 v131, s[12:13]
	s_mov_b32 m0, s67
	s_nop 0
	global_load_lds_dwordx4 v133, s[12:13]
	s_mov_b32 m0, s68
	s_nop 0
	global_load_lds_dwordx4 v131, s[22:23]
	s_mov_b32 m0, s66
	s_nop 0
	global_load_lds_dwordx4 v133, s[22:23]
	s_mov_b32 m0, s42
	s_nop 0
	global_load_lds_dwordx4 v130, s[10:11]
	s_mov_b32 m0, s43
	s_nop 0
	global_load_lds_dwordx4 v132, s[10:11]
	s_waitcnt vmcnt(8)
	s_waitcnt lgkmcnt(0)
	s_barrier
	s_setprio 1
	s_waitcnt lgkmcnt(0)
	v_mfma_f32_16x16x32_bf16 v[66:69], v[138:141], v[170:173], v[66:69]
	v_mfma_f32_16x16x32_bf16 v[58:61], v[146:149], v[170:173], v[58:61]
	v_mfma_f32_16x16x32_bf16 v[54:57], v[138:141], v[178:181], v[54:57]
	v_mfma_f32_16x16x32_bf16 v[46:49], v[146:149], v[178:181], v[46:49]
	v_mfma_f32_16x16x32_bf16 v[38:41], v[138:141], v[186:189], v[38:41]
	v_mfma_f32_16x16x32_bf16 v[30:33], v[146:149], v[186:189], v[30:33]
	v_mfma_f32_16x16x32_bf16 v[22:25], v[138:141], v[194:197], v[22:25]
	v_mfma_f32_16x16x32_bf16 v[14:17], v[146:149], v[194:197], v[14:17]
	v_mfma_f32_16x16x32_bf16 v[66:69], v[142:145], v[174:177], v[66:69]
	v_mfma_f32_16x16x32_bf16 v[58:61], v[150:153], v[174:177], v[58:61]
	v_mfma_f32_16x16x32_bf16 v[54:57], v[142:145], v[182:185], v[54:57]
	v_mfma_f32_16x16x32_bf16 v[46:49], v[150:153], v[182:185], v[46:49]
	v_mfma_f32_16x16x32_bf16 v[38:41], v[142:145], v[190:193], v[38:41]
	v_mfma_f32_16x16x32_bf16 v[30:33], v[150:153], v[190:193], v[30:33]
	v_mfma_f32_16x16x32_bf16 v[22:25], v[142:145], v[198:201], v[22:25]
	v_mfma_f32_16x16x32_bf16 v[14:17], v[150:153], v[198:201], v[14:17]
	s_setprio 0
	s_setprio 1
	v_mfma_f32_16x16x32_bf16 v[50:53], v[154:157], v[170:173], v[50:53]
	v_mfma_f32_16x16x32_bf16 v[42:45], v[162:165], v[170:173], v[42:45]
	v_mfma_f32_16x16x32_bf16 v[34:37], v[154:157], v[178:181], v[34:37]
	v_mfma_f32_16x16x32_bf16 v[26:29], v[162:165], v[178:181], v[26:29]
	v_mfma_f32_16x16x32_bf16 v[18:21], v[154:157], v[186:189], v[18:21]
	v_mfma_f32_16x16x32_bf16 v[10:13], v[162:165], v[186:189], v[10:13]
	v_mfma_f32_16x16x32_bf16 v[6:9], v[154:157], v[194:197], v[6:9]
	v_mfma_f32_16x16x32_bf16 v[2:5], v[162:165], v[194:197], v[2:5]
	v_mfma_f32_16x16x32_bf16 v[50:53], v[158:161], v[174:177], v[50:53]
	v_mfma_f32_16x16x32_bf16 v[42:45], v[166:169], v[174:177], v[42:45]
	v_mfma_f32_16x16x32_bf16 v[34:37], v[158:161], v[182:185], v[34:37]
	v_mfma_f32_16x16x32_bf16 v[26:29], v[166:169], v[182:185], v[26:29]
	v_mfma_f32_16x16x32_bf16 v[18:21], v[158:161], v[190:193], v[18:21]
	v_mfma_f32_16x16x32_bf16 v[10:13], v[166:169], v[190:193], v[10:13]
	v_mfma_f32_16x16x32_bf16 v[6:9], v[158:161], v[198:201], v[6:9]
	v_mfma_f32_16x16x32_bf16 v[2:5], v[166:169], v[198:201], v[2:5]
	s_setprio 0
	s_barrier
	ds_read_b128 v[138:141], v0 offset:32768
	ds_read_b128 v[142:145], v0 offset:33792
	ds_read_b128 v[146:149], v0 offset:34816
	ds_read_b128 v[150:153], v0 offset:35840
	ds_read_b128 v[154:157], v0 offset:49152
	ds_read_b128 v[158:161], v0 offset:50176
	ds_read_b128 v[162:165], v0 offset:51200
	ds_read_b128 v[166:169], v0 offset:52224
	s_mov_b32 m0, s50
	ds_read_b128 v[170:173], v137 offset:32768
	ds_read_b128 v[174:177], v137 offset:33792
	ds_read_b128 v[178:181], v137 offset:34816
	ds_read_b128 v[182:185], v137 offset:35840
	ds_read_b128 v[186:189], v137 offset:36864
	ds_read_b128 v[190:193], v137 offset:37888
	ds_read_b128 v[194:197], v137 offset:38912
	ds_read_b128 v[198:201], v137 offset:39936
	s_nop 0
	global_load_lds_dwordx4 v130, s[16:17]
	s_mov_b32 m0, s51
	s_nop 0
	global_load_lds_dwordx4 v132, s[16:17]
	s_waitcnt vmcnt(8)
	s_waitcnt lgkmcnt(0)
	s_barrier
	s_setprio 1
	s_waitcnt lgkmcnt(0)
	v_mfma_f32_16x16x32_bf16 v[126:129], v[138:141], v[170:173], v[126:129]
	v_mfma_f32_16x16x32_bf16 v[122:125], v[146:149], v[170:173], v[122:125]
	v_mfma_f32_16x16x32_bf16 v[118:121], v[138:141], v[178:181], v[118:121]
	v_mfma_f32_16x16x32_bf16 v[110:113], v[146:149], v[178:181], v[110:113]
	v_mfma_f32_16x16x32_bf16 v[102:105], v[138:141], v[186:189], v[102:105]
	v_mfma_f32_16x16x32_bf16 v[94:97], v[146:149], v[186:189], v[94:97]
	v_mfma_f32_16x16x32_bf16 v[86:89], v[138:141], v[194:197], v[86:89]
	v_mfma_f32_16x16x32_bf16 v[78:81], v[146:149], v[194:197], v[78:81]
	v_mfma_f32_16x16x32_bf16 v[126:129], v[142:145], v[174:177], v[126:129]
	v_mfma_f32_16x16x32_bf16 v[122:125], v[150:153], v[174:177], v[122:125]
	v_mfma_f32_16x16x32_bf16 v[118:121], v[142:145], v[182:185], v[118:121]
	v_mfma_f32_16x16x32_bf16 v[110:113], v[150:153], v[182:185], v[110:113]
	v_mfma_f32_16x16x32_bf16 v[102:105], v[142:145], v[190:193], v[102:105]
	v_mfma_f32_16x16x32_bf16 v[94:97], v[150:153], v[190:193], v[94:97]
	v_mfma_f32_16x16x32_bf16 v[86:89], v[142:145], v[198:201], v[86:89]
	v_mfma_f32_16x16x32_bf16 v[78:81], v[150:153], v[198:201], v[78:81]
	s_setprio 0
	s_setprio 1
	v_mfma_f32_16x16x32_bf16 v[114:117], v[154:157], v[170:173], v[114:117]
	v_mfma_f32_16x16x32_bf16 v[106:109], v[162:165], v[170:173], v[106:109]
	v_mfma_f32_16x16x32_bf16 v[98:101], v[154:157], v[178:181], v[98:101]
	v_mfma_f32_16x16x32_bf16 v[90:93], v[162:165], v[178:181], v[90:93]
	v_mfma_f32_16x16x32_bf16 v[82:85], v[154:157], v[186:189], v[82:85]
	v_mfma_f32_16x16x32_bf16 v[74:77], v[162:165], v[186:189], v[74:77]
	v_mfma_f32_16x16x32_bf16 v[70:73], v[154:157], v[194:197], v[70:73]
	v_mfma_f32_16x16x32_bf16 v[62:65], v[162:165], v[194:197], v[62:65]
	v_mfma_f32_16x16x32_bf16 v[114:117], v[158:161], v[174:177], v[114:117]
	v_mfma_f32_16x16x32_bf16 v[106:109], v[166:169], v[174:177], v[106:109]
	v_mfma_f32_16x16x32_bf16 v[98:101], v[158:161], v[182:185], v[98:101]
	v_mfma_f32_16x16x32_bf16 v[90:93], v[166:169], v[182:185], v[90:93]
	v_mfma_f32_16x16x32_bf16 v[82:85], v[158:161], v[190:193], v[82:85]
	v_mfma_f32_16x16x32_bf16 v[74:77], v[166:169], v[190:193], v[74:77]
	v_mfma_f32_16x16x32_bf16 v[70:73], v[158:161], v[198:201], v[70:73]
	v_mfma_f32_16x16x32_bf16 v[62:65], v[166:169], v[198:201], v[62:65]
	s_setprio 0
	s_barrier
	ds_read_b128 v[170:173], v137 offset:49152
	ds_read_b128 v[174:177], v137 offset:50176
	ds_read_b128 v[178:181], v137 offset:51200
	ds_read_b128 v[182:185], v137 offset:52224
	ds_read_b128 v[186:189], v137 offset:53248
	ds_read_b128 v[190:193], v137 offset:54272
	ds_read_b128 v[194:197], v137 offset:55296
	ds_read_b128 v[198:201], v137 offset:56320
	s_mov_b32 m0, s61
	s_add_u32 s100, s12, s38
	s_addc_u32 s101, s13, s39
	global_load_lds_dwordx4 v131, s[100:101]
	s_mov_b32 m0, s60
	s_nop 0
	global_load_lds_dwordx4 v133, s[100:101]
	s_mov_b32 m0, s70
	s_nop 0
	global_load_lds_dwordx4 v131, s[14:15]
	s_mov_b32 m0, s69
	s_nop 0
	global_load_lds_dwordx4 v133, s[14:15]
	s_mov_b32 m0, s58
	s_add_u32 s100, s10, s38
	s_addc_u32 s101, s11, s39
	v_mov_b32_e32 v0, v132
	global_load_lds_dwordx4 v130, s[100:101]
	s_mov_b32 m0, s59
	s_nop 0
	global_load_lds_dwordx4 v132, s[100:101]
	s_waitcnt vmcnt(8)
	s_waitcnt lgkmcnt(0)
	s_barrier
	s_setprio 1
	s_waitcnt lgkmcnt(0)
	v_mfma_f32_16x16x32_bf16 v[66:69], v[138:141], v[170:173], v[66:69]
	v_mfma_f32_16x16x32_bf16 v[58:61], v[146:149], v[170:173], v[58:61]
	v_mfma_f32_16x16x32_bf16 v[54:57], v[138:141], v[178:181], v[54:57]
	v_mfma_f32_16x16x32_bf16 v[46:49], v[146:149], v[178:181], v[46:49]
	v_mfma_f32_16x16x32_bf16 v[38:41], v[138:141], v[186:189], v[38:41]
	v_mfma_f32_16x16x32_bf16 v[30:33], v[146:149], v[186:189], v[30:33]
	v_mfma_f32_16x16x32_bf16 v[22:25], v[138:141], v[194:197], v[22:25]
	v_mfma_f32_16x16x32_bf16 v[14:17], v[146:149], v[194:197], v[14:17]
	v_mfma_f32_16x16x32_bf16 v[66:69], v[142:145], v[174:177], v[66:69]
	v_mfma_f32_16x16x32_bf16 v[58:61], v[150:153], v[174:177], v[58:61]
	v_mfma_f32_16x16x32_bf16 v[54:57], v[142:145], v[182:185], v[54:57]
	v_mfma_f32_16x16x32_bf16 v[46:49], v[150:153], v[182:185], v[46:49]
	v_mfma_f32_16x16x32_bf16 v[38:41], v[142:145], v[190:193], v[38:41]
	v_mfma_f32_16x16x32_bf16 v[30:33], v[150:153], v[190:193], v[30:33]
	v_mfma_f32_16x16x32_bf16 v[22:25], v[142:145], v[198:201], v[22:25]
	v_mfma_f32_16x16x32_bf16 v[14:17], v[150:153], v[198:201], v[14:17]
	s_setprio 0
	s_setprio 1
	v_mfma_f32_16x16x32_bf16 v[50:53], v[154:157], v[170:173], v[50:53]
	v_mfma_f32_16x16x32_bf16 v[42:45], v[162:165], v[170:173], v[42:45]
	v_mfma_f32_16x16x32_bf16 v[34:37], v[154:157], v[178:181], v[34:37]
	v_mfma_f32_16x16x32_bf16 v[26:29], v[162:165], v[178:181], v[26:29]
	v_mfma_f32_16x16x32_bf16 v[18:21], v[154:157], v[186:189], v[18:21]
	v_mfma_f32_16x16x32_bf16 v[10:13], v[162:165], v[186:189], v[10:13]
	v_mfma_f32_16x16x32_bf16 v[6:9], v[154:157], v[194:197], v[6:9]
	v_mfma_f32_16x16x32_bf16 v[2:5], v[162:165], v[194:197], v[2:5]
	v_mfma_f32_16x16x32_bf16 v[50:53], v[158:161], v[174:177], v[50:53]
	v_mfma_f32_16x16x32_bf16 v[42:45], v[166:169], v[174:177], v[42:45]
	v_mfma_f32_16x16x32_bf16 v[34:37], v[158:161], v[182:185], v[34:37]
	v_mfma_f32_16x16x32_bf16 v[26:29], v[166:169], v[182:185], v[26:29]
	v_mfma_f32_16x16x32_bf16 v[18:21], v[158:161], v[190:193], v[18:21]
	v_mfma_f32_16x16x32_bf16 v[10:13], v[166:169], v[190:193], v[10:13]
	v_mfma_f32_16x16x32_bf16 v[6:9], v[158:161], v[198:201], v[6:9]
	v_mfma_f32_16x16x32_bf16 v[2:5], v[166:169], v[198:201], v[2:5]
	s_setprio 0
	s_barrier
	s_andn2_b64 vcc, exec, s[8:9]
	s_mov_b64 s[12:13], -1
	s_mov_b64 s[8:9], 0
	s_mov_b64 s[14:15], 0x100
	s_cbranch_vccz .LBB0_1473
	s_cmpk_lt_u32 s24, 0x100
	s_cbranch_scc0 .LBB0_1476
	s_barrier

.LBB0_1481:
	s_add_u32 s16, s4, s14
	s_addc_u32 s17, s5, s15
	s_add_u32 s22, s16, 0x100
	s_addc_u32 s23, s17, 0
	s_and_b64 s[10:11], s[12:13], exec
	s_cselect_b32 s11, s5, s23
	s_cselect_b32 s10, s4, s22
	s_add_u32 s14, s6, s14
	s_addc_u32 s15, s7, s15
	s_add_u32 s14, s14, 0x900
	s_addc_u32 s15, s15, 0
	s_add_i32 s70, 0, 0x10000
	s_and_b64 s[12:13], s[12:13], exec
	s_cselect_b32 s13, s58, s15
	s_cselect_b32 s12, s51, s14
	s_add_i32 s15, 0, 0x14000
	s_add_u32 s46, s16, 0x40080
	s_addc_u32 s47, s17, 0
	s_add_i32 s74, s70, s40
	s_add_i32 m0, s41, 0xc000
	s_add_i32 s75, s41, 0xe000
	s_add_i32 s68, s74, 0x2000
	v_add_u32_e32 v0, s70, v136
	s_add_u32 s22, s12, 0x80000
	ds_read_b128 v[138:141], v0
	ds_read_b128 v[142:145], v0 offset:1024
	ds_read_b128 v[146:149], v0 offset:2048
	ds_read_b128 v[150:153], v0 offset:3072
	s_addc_u32 s23, s13, 0
	s_add_i32 s69, s15, s40
	ds_read_b128 v[154:157], v0 offset:16384
	ds_read_b128 v[158:161], v0 offset:17408
	ds_read_b128 v[162:165], v0 offset:18432
	ds_read_b128 v[166:169], v0 offset:19456
	s_add_i32 s67, s69, 0x2000
	s_add_i32 s66, 0, 0x18000
	s_add_i32 s65, 0, 0x1c000
	s_add_u32 s16, s10, 0x40000
	s_addc_u32 s17, s11, 0
	s_add_i32 s64, s66, s40
	s_add_i32 s61, s64, 0x2000
	s_add_u32 s14, s12, 0x80080
	s_addc_u32 s15, s13, 0
	s_add_i32 s71, s65, s40
	s_add_i32 s70, s71, 0x2000
	ds_read_b128 v[170:173], v137
	ds_read_b128 v[174:177], v137 offset:1024
	ds_read_b128 v[178:181], v137 offset:2048
	ds_read_b128 v[182:185], v137 offset:3072
	ds_read_b128 v[186:189], v137 offset:4096
	ds_read_b128 v[190:193], v137 offset:5120
	ds_read_b128 v[194:197], v137 offset:6144
	ds_read_b128 v[198:201], v137 offset:7168
	s_nop 0
	global_load_lds_dwordx4 v130, s[46:47]
	s_mov_b32 m0, s75
	s_nop 0
	global_load_lds_dwordx4 v132, s[46:47]
	s_waitcnt vmcnt(8)
	s_waitcnt lgkmcnt(0)
	s_barrier
	s_setprio 1
	s_waitcnt lgkmcnt(0)
	v_mfma_f32_16x16x32_bf16 v[126:129], v[138:141], v[170:173], v[126:129]
	v_mfma_f32_16x16x32_bf16 v[122:125], v[146:149], v[170:173], v[122:125]
	v_mfma_f32_16x16x32_bf16 v[118:121], v[138:141], v[178:181], v[118:121]
	v_mfma_f32_16x16x32_bf16 v[110:113], v[146:149], v[178:181], v[110:113]
	v_mfma_f32_16x16x32_bf16 v[102:105], v[138:141], v[186:189], v[102:105]
	v_mfma_f32_16x16x32_bf16 v[94:97], v[146:149], v[186:189], v[94:97]
	v_mfma_f32_16x16x32_bf16 v[86:89], v[138:141], v[194:197], v[86:89]
	v_mfma_f32_16x16x32_bf16 v[78:81], v[146:149], v[194:197], v[78:81]
	v_mfma_f32_16x16x32_bf16 v[126:129], v[142:145], v[174:177], v[126:129]
	v_mfma_f32_16x16x32_bf16 v[122:125], v[150:153], v[174:177], v[122:125]
	v_mfma_f32_16x16x32_bf16 v[118:121], v[142:145], v[182:185], v[118:121]
	v_mfma_f32_16x16x32_bf16 v[110:113], v[150:153], v[182:185], v[110:113]
	v_mfma_f32_16x16x32_bf16 v[102:105], v[142:145], v[190:193], v[102:105]
	v_mfma_f32_16x16x32_bf16 v[94:97], v[150:153], v[190:193], v[94:97]
	v_mfma_f32_16x16x32_bf16 v[86:89], v[142:145], v[198:201], v[86:89]
	v_mfma_f32_16x16x32_bf16 v[78:81], v[150:153], v[198:201], v[78:81]
	s_setprio 0
	s_setprio 1
	v_mfma_f32_16x16x32_bf16 v[114:117], v[154:157], v[170:173], v[114:117]
	v_mfma_f32_16x16x32_bf16 v[106:109], v[162:165], v[170:173], v[106:109]
	v_mfma_f32_16x16x32_bf16 v[98:101], v[154:157], v[178:181], v[98:101]
	v_mfma_f32_16x16x32_bf16 v[90:93], v[162:165], v[178:181], v[90:93]
	v_mfma_f32_16x16x32_bf16 v[82:85], v[154:157], v[186:189], v[82:85]
	v_mfma_f32_16x16x32_bf16 v[74:77], v[162:165], v[186:189], v[74:77]
	v_mfma_f32_16x16x32_bf16 v[70:73], v[154:157], v[194:197], v[70:73]
	v_mfma_f32_16x16x32_bf16 v[62:65], v[162:165], v[194:197], v[62:65]
	v_mfma_f32_16x16x32_bf16 v[114:117], v[158:161], v[174:177], v[114:117]
	v_mfma_f32_16x16x32_bf16 v[106:109], v[166:169], v[174:177], v[106:109]
	v_mfma_f32_16x16x32_bf16 v[98:101], v[158:161], v[182:185], v[98:101]
	v_mfma_f32_16x16x32_bf16 v[90:93], v[166:169], v[182:185], v[90:93]
	v_mfma_f32_16x16x32_bf16 v[82:85], v[158:161], v[190:193], v[82:85]
	v_mfma_f32_16x16x32_bf16 v[74:77], v[166:169], v[190:193], v[74:77]
	v_mfma_f32_16x16x32_bf16 v[70:73], v[158:161], v[198:201], v[70:73]
	v_mfma_f32_16x16x32_bf16 v[62:65], v[166:169], v[198:201], v[62:65]
	s_setprio 0
	s_barrier
	s_mov_b32 m0, s74
	ds_read_b128 v[170:173], v137 offset:16384
	ds_read_b128 v[174:177], v137 offset:17408
	ds_read_b128 v[178:181], v137 offset:18432
	ds_read_b128 v[182:185], v137 offset:19456
	ds_read_b128 v[186:189], v137 offset:20480
	ds_read_b128 v[190:193], v137 offset:21504
	ds_read_b128 v[194:197], v137 offset:22528
	ds_read_b128 v[198:201], v137 offset:23552
	s_nop 0
	global_load_lds_dwordx4 v131, s[12:13]
	s_mov_b32 m0, s68
	s_nop 0
	global_load_lds_dwordx4 v133, s[12:13]
	s_mov_b32 m0, s69
	s_nop 0
	global_load_lds_dwordx4 v131, s[22:23]
	s_mov_b32 m0, s67
	s_nop 0
	global_load_lds_dwordx4 v133, s[22:23]
	s_mov_b32 m0, s41
	s_nop 0
	global_load_lds_dwordx4 v130, s[10:11]
	s_mov_b32 m0, s42
	s_nop 0
	global_load_lds_dwordx4 v132, s[10:11]
	s_waitcnt vmcnt(8)
	s_waitcnt lgkmcnt(0)
	s_barrier
	s_setprio 1
	s_waitcnt lgkmcnt(0)
	v_mfma_f32_16x16x32_bf16 v[66:69], v[138:141], v[170:173], v[66:69]
	v_mfma_f32_16x16x32_bf16 v[58:61], v[146:149], v[170:173], v[58:61]
	v_mfma_f32_16x16x32_bf16 v[54:57], v[138:141], v[178:181], v[54:57]
	v_mfma_f32_16x16x32_bf16 v[46:49], v[146:149], v[178:181], v[46:49]
	v_mfma_f32_16x16x32_bf16 v[38:41], v[138:141], v[186:189], v[38:41]
	v_mfma_f32_16x16x32_bf16 v[30:33], v[146:149], v[186:189], v[30:33]
	v_mfma_f32_16x16x32_bf16 v[22:25], v[138:141], v[194:197], v[22:25]
	v_mfma_f32_16x16x32_bf16 v[14:17], v[146:149], v[194:197], v[14:17]
	v_mfma_f32_16x16x32_bf16 v[66:69], v[142:145], v[174:177], v[66:69]
	v_mfma_f32_16x16x32_bf16 v[58:61], v[150:153], v[174:177], v[58:61]
	v_mfma_f32_16x16x32_bf16 v[54:57], v[142:145], v[182:185], v[54:57]
	v_mfma_f32_16x16x32_bf16 v[46:49], v[150:153], v[182:185], v[46:49]
	v_mfma_f32_16x16x32_bf16 v[38:41], v[142:145], v[190:193], v[38:41]
	v_mfma_f32_16x16x32_bf16 v[30:33], v[150:153], v[190:193], v[30:33]
	v_mfma_f32_16x16x32_bf16 v[22:25], v[142:145], v[198:201], v[22:25]
	v_mfma_f32_16x16x32_bf16 v[14:17], v[150:153], v[198:201], v[14:17]
	s_setprio 0
	s_setprio 1
	v_mfma_f32_16x16x32_bf16 v[50:53], v[154:157], v[170:173], v[50:53]
	v_mfma_f32_16x16x32_bf16 v[42:45], v[162:165], v[170:173], v[42:45]
	v_mfma_f32_16x16x32_bf16 v[34:37], v[154:157], v[178:181], v[34:37]
	v_mfma_f32_16x16x32_bf16 v[26:29], v[162:165], v[178:181], v[26:29]
	v_mfma_f32_16x16x32_bf16 v[18:21], v[154:157], v[186:189], v[18:21]
	v_mfma_f32_16x16x32_bf16 v[10:13], v[162:165], v[186:189], v[10:13]
	v_mfma_f32_16x16x32_bf16 v[6:9], v[154:157], v[194:197], v[6:9]
	v_mfma_f32_16x16x32_bf16 v[2:5], v[162:165], v[194:197], v[2:5]
	v_mfma_f32_16x16x32_bf16 v[50:53], v[158:161], v[174:177], v[50:53]
	v_mfma_f32_16x16x32_bf16 v[42:45], v[166:169], v[174:177], v[42:45]
	v_mfma_f32_16x16x32_bf16 v[34:37], v[158:161], v[182:185], v[34:37]
	v_mfma_f32_16x16x32_bf16 v[26:29], v[166:169], v[182:185], v[26:29]
	v_mfma_f32_16x16x32_bf16 v[18:21], v[158:161], v[190:193], v[18:21]
	v_mfma_f32_16x16x32_bf16 v[10:13], v[166:169], v[190:193], v[10:13]
	v_mfma_f32_16x16x32_bf16 v[6:9], v[158:161], v[198:201], v[6:9]
	v_mfma_f32_16x16x32_bf16 v[2:5], v[166:169], v[198:201], v[2:5]
	s_setprio 0
	s_barrier
	ds_read_b128 v[138:141], v0 offset:32768
	ds_read_b128 v[142:145], v0 offset:33792
	ds_read_b128 v[146:149], v0 offset:34816
	ds_read_b128 v[150:153], v0 offset:35840
	ds_read_b128 v[154:157], v0 offset:49152
	ds_read_b128 v[158:161], v0 offset:50176
	ds_read_b128 v[162:165], v0 offset:51200
	ds_read_b128 v[166:169], v0 offset:52224
	s_mov_b32 m0, s43
	ds_read_b128 v[170:173], v137 offset:32768
	ds_read_b128 v[174:177], v137 offset:33792
	ds_read_b128 v[178:181], v137 offset:34816
	ds_read_b128 v[182:185], v137 offset:35840
	ds_read_b128 v[186:189], v137 offset:36864
	ds_read_b128 v[190:193], v137 offset:37888
	ds_read_b128 v[194:197], v137 offset:38912
	ds_read_b128 v[198:201], v137 offset:39936
	s_nop 0
	global_load_lds_dwordx4 v130, s[16:17]
	s_mov_b32 m0, s50
	s_nop 0
	global_load_lds_dwordx4 v132, s[16:17]
	s_waitcnt vmcnt(8)
	s_waitcnt lgkmcnt(0)
	s_barrier
	s_setprio 1
	s_waitcnt lgkmcnt(0)
	v_mfma_f32_16x16x32_bf16 v[126:129], v[138:141], v[170:173], v[126:129]
	v_mfma_f32_16x16x32_bf16 v[122:125], v[146:149], v[170:173], v[122:125]
	v_mfma_f32_16x16x32_bf16 v[118:121], v[138:141], v[178:181], v[118:121]
	v_mfma_f32_16x16x32_bf16 v[110:113], v[146:149], v[178:181], v[110:113]
	v_mfma_f32_16x16x32_bf16 v[102:105], v[138:141], v[186:189], v[102:105]
	v_mfma_f32_16x16x32_bf16 v[94:97], v[146:149], v[186:189], v[94:97]
	v_mfma_f32_16x16x32_bf16 v[86:89], v[138:141], v[194:197], v[86:89]
	v_mfma_f32_16x16x32_bf16 v[78:81], v[146:149], v[194:197], v[78:81]
	v_mfma_f32_16x16x32_bf16 v[126:129], v[142:145], v[174:177], v[126:129]
	v_mfma_f32_16x16x32_bf16 v[122:125], v[150:153], v[174:177], v[122:125]
	v_mfma_f32_16x16x32_bf16 v[118:121], v[142:145], v[182:185], v[118:121]
	v_mfma_f32_16x16x32_bf16 v[110:113], v[150:153], v[182:185], v[110:113]
	v_mfma_f32_16x16x32_bf16 v[102:105], v[142:145], v[190:193], v[102:105]
	v_mfma_f32_16x16x32_bf16 v[94:97], v[150:153], v[190:193], v[94:97]
	v_mfma_f32_16x16x32_bf16 v[86:89], v[142:145], v[198:201], v[86:89]
	v_mfma_f32_16x16x32_bf16 v[78:81], v[150:153], v[198:201], v[78:81]
	s_setprio 0
	s_setprio 1
	v_mfma_f32_16x16x32_bf16 v[114:117], v[154:157], v[170:173], v[114:117]
	v_mfma_f32_16x16x32_bf16 v[106:109], v[162:165], v[170:173], v[106:109]
	v_mfma_f32_16x16x32_bf16 v[98:101], v[154:157], v[178:181], v[98:101]
	v_mfma_f32_16x16x32_bf16 v[90:93], v[162:165], v[178:181], v[90:93]
	v_mfma_f32_16x16x32_bf16 v[82:85], v[154:157], v[186:189], v[82:85]
	v_mfma_f32_16x16x32_bf16 v[74:77], v[162:165], v[186:189], v[74:77]
	v_mfma_f32_16x16x32_bf16 v[70:73], v[154:157], v[194:197], v[70:73]
	v_mfma_f32_16x16x32_bf16 v[62:65], v[162:165], v[194:197], v[62:65]
	v_mfma_f32_16x16x32_bf16 v[114:117], v[158:161], v[174:177], v[114:117]
	v_mfma_f32_16x16x32_bf16 v[106:109], v[166:169], v[174:177], v[106:109]
	v_mfma_f32_16x16x32_bf16 v[98:101], v[158:161], v[182:185], v[98:101]
	v_mfma_f32_16x16x32_bf16 v[90:93], v[166:169], v[182:185], v[90:93]
	v_mfma_f32_16x16x32_bf16 v[82:85], v[158:161], v[190:193], v[82:85]
	v_mfma_f32_16x16x32_bf16 v[74:77], v[166:169], v[190:193], v[74:77]
	v_mfma_f32_16x16x32_bf16 v[70:73], v[158:161], v[198:201], v[70:73]
	v_mfma_f32_16x16x32_bf16 v[62:65], v[166:169], v[198:201], v[62:65]
	s_setprio 0
	s_barrier
	ds_read_b128 v[170:173], v137 offset:49152
	ds_read_b128 v[174:177], v137 offset:50176
	ds_read_b128 v[178:181], v137 offset:51200
	ds_read_b128 v[182:185], v137 offset:52224
	ds_read_b128 v[186:189], v137 offset:53248
	ds_read_b128 v[190:193], v137 offset:54272
	ds_read_b128 v[194:197], v137 offset:55296
	ds_read_b128 v[198:201], v137 offset:56320
	s_mov_b32 m0, s64
	s_add_u32 s100, s12, s38
	s_addc_u32 s101, s13, s39
	global_load_lds_dwordx4 v131, s[100:101]
	s_mov_b32 m0, s61
	s_nop 0
	global_load_lds_dwordx4 v133, s[100:101]
	s_mov_b32 m0, s71
	s_nop 0
	global_load_lds_dwordx4 v131, s[14:15]
	s_mov_b32 m0, s70
	s_nop 0
	global_load_lds_dwordx4 v133, s[14:15]
	s_mov_b32 m0, s59
	s_add_u32 s100, s10, s38
	s_addc_u32 s101, s11, s39
	v_mov_b32_e32 v0, v132
	global_load_lds_dwordx4 v130, s[100:101]
	s_mov_b32 m0, s60
	s_nop 0
	global_load_lds_dwordx4 v132, s[100:101]
	s_waitcnt vmcnt(8)
	s_waitcnt lgkmcnt(0)
	s_barrier
	s_setprio 1
	s_waitcnt lgkmcnt(0)
	v_mfma_f32_16x16x32_bf16 v[66:69], v[138:141], v[170:173], v[66:69]
	v_mfma_f32_16x16x32_bf16 v[58:61], v[146:149], v[170:173], v[58:61]
	v_mfma_f32_16x16x32_bf16 v[54:57], v[138:141], v[178:181], v[54:57]
	v_mfma_f32_16x16x32_bf16 v[46:49], v[146:149], v[178:181], v[46:49]
	v_mfma_f32_16x16x32_bf16 v[38:41], v[138:141], v[186:189], v[38:41]
	v_mfma_f32_16x16x32_bf16 v[30:33], v[146:149], v[186:189], v[30:33]
	v_mfma_f32_16x16x32_bf16 v[22:25], v[138:141], v[194:197], v[22:25]
	v_mfma_f32_16x16x32_bf16 v[14:17], v[146:149], v[194:197], v[14:17]
	v_mfma_f32_16x16x32_bf16 v[66:69], v[142:145], v[174:177], v[66:69]
	v_mfma_f32_16x16x32_bf16 v[58:61], v[150:153], v[174:177], v[58:61]
	v_mfma_f32_16x16x32_bf16 v[54:57], v[142:145], v[182:185], v[54:57]
	v_mfma_f32_16x16x32_bf16 v[46:49], v[150:153], v[182:185], v[46:49]
	v_mfma_f32_16x16x32_bf16 v[38:41], v[142:145], v[190:193], v[38:41]
	v_mfma_f32_16x16x32_bf16 v[30:33], v[150:153], v[190:193], v[30:33]
	v_mfma_f32_16x16x32_bf16 v[22:25], v[142:145], v[198:201], v[22:25]
	v_mfma_f32_16x16x32_bf16 v[14:17], v[150:153], v[198:201], v[14:17]
	s_setprio 0
	s_setprio 1
	v_mfma_f32_16x16x32_bf16 v[50:53], v[154:157], v[170:173], v[50:53]
	v_mfma_f32_16x16x32_bf16 v[42:45], v[162:165], v[170:173], v[42:45]
	v_mfma_f32_16x16x32_bf16 v[34:37], v[154:157], v[178:181], v[34:37]
	v_mfma_f32_16x16x32_bf16 v[26:29], v[162:165], v[178:181], v[26:29]
	v_mfma_f32_16x16x32_bf16 v[18:21], v[154:157], v[186:189], v[18:21]
	v_mfma_f32_16x16x32_bf16 v[10:13], v[162:165], v[186:189], v[10:13]
	v_mfma_f32_16x16x32_bf16 v[6:9], v[154:157], v[194:197], v[6:9]
	v_mfma_f32_16x16x32_bf16 v[2:5], v[162:165], v[194:197], v[2:5]
	v_mfma_f32_16x16x32_bf16 v[50:53], v[158:161], v[174:177], v[50:53]
	v_mfma_f32_16x16x32_bf16 v[42:45], v[166:169], v[174:177], v[42:45]
	v_mfma_f32_16x16x32_bf16 v[34:37], v[158:161], v[182:185], v[34:37]
	v_mfma_f32_16x16x32_bf16 v[26:29], v[166:169], v[182:185], v[26:29]
	v_mfma_f32_16x16x32_bf16 v[18:21], v[158:161], v[190:193], v[18:21]
	v_mfma_f32_16x16x32_bf16 v[10:13], v[166:169], v[190:193], v[10:13]
	v_mfma_f32_16x16x32_bf16 v[6:9], v[158:161], v[198:201], v[6:9]
	v_mfma_f32_16x16x32_bf16 v[2:5], v[166:169], v[198:201], v[2:5]
	s_setprio 0
	s_barrier
	s_andn2_b64 vcc, exec, s[8:9]
	s_mov_b64 s[12:13], -1
	s_mov_b64 s[8:9], 0
	s_mov_b64 s[14:15], 0x100
	s_cbranch_vccz .LBB0_1481
	s_cmpk_lt_u32 s24, 0x100
	s_cbranch_scc0 .LBB0_1484
	s_barrier

.LBB0_1570:
	s_add_u32 s48, s41, s6
	s_addc_u32 s49, s42, s7
	s_add_u32 s8, s48, 0x9800100
	s_addc_u32 s9, s49, 0
	s_add_u32 s10, s43, s6
	s_addc_u32 s11, s46, s7
	s_cmpk_eq_i32 s6, 0x700
	s_cselect_b32 s9, s3, s9
	s_cselect_b32 s8, s2, s8
	s_cselect_b32 s11, s26, s11
	s_cselect_b32 s10, s25, s10
	s_add_i32 s50, 0, 0x10000
	v_add_u32_e32 v0, s50, v169
	s_add_i32 s51, 0, 0x14000
	ds_read_b128 v[172:175], v0
	ds_read_b128 v[176:179], v0 offset:1024
	ds_read_b128 v[180:183], v0 offset:2048
	ds_read_b128 v[184:187], v0 offset:3072
	ds_read_b128 v[188:191], v0 offset:16384
	ds_read_b128 v[192:195], v0 offset:17408
	ds_read_b128 v[196:199], v0 offset:18432
	ds_read_b128 v[200:203], v0 offset:19456
	ds_read_b128 v[204:207], v170
	ds_read_b128 v[208:211], v170 offset:1024
	ds_read_b128 v[212:215], v170 offset:2048
	ds_read_b128 v[216:219], v170 offset:3072
	ds_read_b128 v[220:223], v170 offset:4096
	ds_read_b128 v[224:227], v170 offset:5120
	ds_read_b128 v[232:235], v170 offset:6144
	ds_read_b128 v[242:245], v170 offset:7168
	s_mov_b64 s[58:59], 0x9840080
	s_add_u32 s100, s48, s58
	s_addc_u32 s101, s49, s59
	s_add_i32 m0, s17, 0xc000
	s_nop 0
	global_load_lds_dwordx4 v164, s[100:101]
	s_add_i32 m0, s17, 0xe000
	s_nop 0
	global_load_lds_dwordx4 v166, s[100:101]
	s_waitcnt vmcnt(8)
	s_waitcnt lgkmcnt(0)
	s_barrier
	s_setprio 1
	s_waitcnt lgkmcnt(0)
	v_mfma_f32_16x16x32_bf16 v[160:163], v[172:175], v[204:207], v[160:163]
	v_mfma_f32_16x16x32_bf16 v[156:159], v[180:183], v[204:207], v[156:159]
	v_mfma_f32_16x16x32_bf16 v[112:115], v[172:175], v[212:215], v[112:115]
	v_mfma_f32_16x16x32_bf16 v[108:111], v[180:183], v[212:215], v[108:111]
	v_mfma_f32_16x16x32_bf16 v[96:99], v[172:175], v[220:223], v[96:99]
	v_mfma_f32_16x16x32_bf16 v[92:95], v[180:183], v[220:223], v[92:95]
	v_mfma_f32_16x16x32_bf16 v[80:83], v[172:175], v[232:235], v[80:83]
	v_mfma_f32_16x16x32_bf16 v[76:79], v[180:183], v[232:235], v[76:79]
	v_mfma_f32_16x16x32_bf16 v[160:163], v[176:179], v[208:211], v[160:163]
	v_mfma_f32_16x16x32_bf16 v[156:159], v[184:187], v[208:211], v[156:159]
	v_mfma_f32_16x16x32_bf16 v[112:115], v[176:179], v[216:219], v[112:115]
	v_mfma_f32_16x16x32_bf16 v[108:111], v[184:187], v[216:219], v[108:111]
	v_mfma_f32_16x16x32_bf16 v[96:99], v[176:179], v[224:227], v[96:99]
	v_mfma_f32_16x16x32_bf16 v[92:95], v[184:187], v[224:227], v[92:95]
	v_mfma_f32_16x16x32_bf16 v[80:83], v[176:179], v[242:245], v[80:83]
	v_mfma_f32_16x16x32_bf16 v[76:79], v[184:187], v[242:245], v[76:79]
	s_setprio 0
	s_setprio 1
	v_mfma_f32_16x16x32_bf16 v[128:131], v[188:191], v[204:207], v[128:131]
	v_mfma_f32_16x16x32_bf16 v[120:123], v[196:199], v[204:207], v[120:123]
	v_mfma_f32_16x16x32_bf16 v[104:107], v[188:191], v[212:215], v[104:107]
	v_mfma_f32_16x16x32_bf16 v[100:103], v[196:199], v[212:215], v[100:103]
	v_mfma_f32_16x16x32_bf16 v[88:91], v[188:191], v[220:223], v[88:91]
	v_mfma_f32_16x16x32_bf16 v[84:87], v[196:199], v[220:223], v[84:87]
	v_mfma_f32_16x16x32_bf16 v[72:75], v[188:191], v[232:235], v[72:75]
	v_mfma_f32_16x16x32_bf16 v[68:71], v[196:199], v[232:235], v[68:71]
	v_mfma_f32_16x16x32_bf16 v[128:131], v[192:195], v[208:211], v[128:131]
	v_mfma_f32_16x16x32_bf16 v[120:123], v[200:203], v[208:211], v[120:123]
	v_mfma_f32_16x16x32_bf16 v[104:107], v[192:195], v[216:219], v[104:107]
	v_mfma_f32_16x16x32_bf16 v[100:103], v[200:203], v[216:219], v[100:103]
	v_mfma_f32_16x16x32_bf16 v[88:91], v[192:195], v[224:227], v[88:91]
	v_mfma_f32_16x16x32_bf16 v[84:87], v[200:203], v[224:227], v[84:87]
	v_mfma_f32_16x16x32_bf16 v[72:75], v[192:195], v[242:245], v[72:75]
	v_mfma_f32_16x16x32_bf16 v[68:71], v[200:203], v[242:245], v[68:71]
	s_setprio 0
	s_barrier
	s_add_i32 s48, s50, s16
	ds_read_b128 v[204:207], v170 offset:16384
	ds_read_b128 v[208:211], v170 offset:17408
	ds_read_b128 v[212:215], v170 offset:18432
	ds_read_b128 v[216:219], v170 offset:19456
	ds_read_b128 v[220:223], v170 offset:20480
	ds_read_b128 v[224:227], v170 offset:21504
	ds_read_b128 v[232:235], v170 offset:22528
	ds_read_b128 v[242:245], v170 offset:23552
	s_mov_b32 m0, s48
	s_nop 0
	global_load_lds_dwordx4 v167, s[10:11]
	s_add_i32 m0, s48, 0x2000
	s_add_u32 s48, s10, 0x40000
	global_load_lds_dwordx4 v168, s[10:11]
	s_addc_u32 s49, s11, 0
	s_add_i32 s50, s51, s16
	s_mov_b32 m0, s50
	s_nop 0
	global_load_lds_dwordx4 v167, s[48:49]
	s_add_i32 m0, s50, 0x2000
	s_nop 0
	global_load_lds_dwordx4 v168, s[48:49]
	s_mov_b32 m0, s17
	s_nop 0
	global_load_lds_dwordx4 v164, s[8:9]
	s_mov_b32 m0, s22
	s_nop 0
	global_load_lds_dwordx4 v166, s[8:9]
	s_waitcnt vmcnt(8)
	s_waitcnt lgkmcnt(0)
	s_barrier
	s_setprio 1
	s_waitcnt lgkmcnt(0)
	v_mfma_f32_16x16x32_bf16 v[64:67], v[172:175], v[204:207], v[64:67]
	v_mfma_f32_16x16x32_bf16 v[60:63], v[180:183], v[204:207], v[60:63]
	v_mfma_f32_16x16x32_bf16 v[48:51], v[172:175], v[212:215], v[48:51]
	v_mfma_f32_16x16x32_bf16 v[44:47], v[180:183], v[212:215], v[44:47]
	v_mfma_f32_16x16x32_bf16 v[32:35], v[172:175], v[220:223], v[32:35]
	v_mfma_f32_16x16x32_bf16 v[28:31], v[180:183], v[220:223], v[28:31]
	v_mfma_f32_16x16x32_bf16 v[16:19], v[172:175], v[232:235], v[16:19]
	v_mfma_f32_16x16x32_bf16 v[12:15], v[180:183], v[232:235], v[12:15]
	v_mfma_f32_16x16x32_bf16 v[64:67], v[176:179], v[208:211], v[64:67]
	v_mfma_f32_16x16x32_bf16 v[60:63], v[184:187], v[208:211], v[60:63]
	v_mfma_f32_16x16x32_bf16 v[48:51], v[176:179], v[216:219], v[48:51]
	v_mfma_f32_16x16x32_bf16 v[44:47], v[184:187], v[216:219], v[44:47]
	v_mfma_f32_16x16x32_bf16 v[32:35], v[176:179], v[224:227], v[32:35]
	v_mfma_f32_16x16x32_bf16 v[28:31], v[184:187], v[224:227], v[28:31]
	v_mfma_f32_16x16x32_bf16 v[16:19], v[176:179], v[242:245], v[16:19]
	v_mfma_f32_16x16x32_bf16 v[12:15], v[184:187], v[242:245], v[12:15]
	s_setprio 0
	s_setprio 1
	v_mfma_f32_16x16x32_bf16 v[56:59], v[188:191], v[204:207], v[56:59]
	v_mfma_f32_16x16x32_bf16 v[52:55], v[196:199], v[204:207], v[52:55]
	v_mfma_f32_16x16x32_bf16 v[40:43], v[188:191], v[212:215], v[40:43]
	v_mfma_f32_16x16x32_bf16 v[36:39], v[196:199], v[212:215], v[36:39]
	v_mfma_f32_16x16x32_bf16 v[24:27], v[188:191], v[220:223], v[24:27]
	v_mfma_f32_16x16x32_bf16 v[20:23], v[196:199], v[220:223], v[20:23]
	v_mfma_f32_16x16x32_bf16 v[8:11], v[188:191], v[232:235], v[8:11]
	v_mfma_f32_16x16x32_bf16 v[2:5], v[196:199], v[232:235], v[4:7]
	v_mfma_f32_16x16x32_bf16 v[56:59], v[192:195], v[208:211], v[56:59]
	v_mfma_f32_16x16x32_bf16 v[52:55], v[200:203], v[208:211], v[52:55]
	v_mfma_f32_16x16x32_bf16 v[40:43], v[192:195], v[216:219], v[40:43]
	v_mfma_f32_16x16x32_bf16 v[36:39], v[200:203], v[216:219], v[36:39]
	v_mfma_f32_16x16x32_bf16 v[24:27], v[192:195], v[224:227], v[24:27]
	v_mfma_f32_16x16x32_bf16 v[20:23], v[200:203], v[224:227], v[20:23]
	v_mfma_f32_16x16x32_bf16 v[8:11], v[192:195], v[242:245], v[8:11]
	v_mfma_f32_16x16x32_bf16 v[2:5], v[200:203], v[242:245], v[2:5]
	s_setprio 0
	s_barrier
	s_add_i32 s50, 0, 0x18000
	s_add_i32 s51, 0, 0x1c000
	ds_read_b128 v[172:175], v0 offset:32768
	ds_read_b128 v[176:179], v0 offset:33792
	ds_read_b128 v[180:183], v0 offset:34816
	ds_read_b128 v[184:187], v0 offset:35840
	ds_read_b128 v[188:191], v0 offset:49152
	ds_read_b128 v[192:195], v0 offset:50176
	ds_read_b128 v[196:199], v0 offset:51200
	ds_read_b128 v[200:203], v0 offset:52224
	s_add_u32 s48, s8, 0x40000
	s_mov_b32 m0, s23
	ds_read_b128 v[204:207], v170 offset:32768
	ds_read_b128 v[208:211], v170 offset:33792
	ds_read_b128 v[212:215], v170 offset:34816
	ds_read_b128 v[216:219], v170 offset:35840
	ds_read_b128 v[220:223], v170 offset:36864
	ds_read_b128 v[224:227], v170 offset:37888
	ds_read_b128 v[232:235], v170 offset:38912
	ds_read_b128 v[242:245], v170 offset:39936
	s_addc_u32 s49, s9, 0
	s_nop 0
	global_load_lds_dwordx4 v164, s[48:49]
	s_mov_b32 m0, s24
	s_nop 0
	global_load_lds_dwordx4 v166, s[48:49]
	s_waitcnt vmcnt(8)
	s_waitcnt lgkmcnt(0)
	s_barrier
	s_setprio 1
	s_waitcnt lgkmcnt(0)
	v_mfma_f32_16x16x32_bf16 v[160:163], v[172:175], v[204:207], v[160:163]
	v_mfma_f32_16x16x32_bf16 v[156:159], v[180:183], v[204:207], v[156:159]
	v_mfma_f32_16x16x32_bf16 v[112:115], v[172:175], v[212:215], v[112:115]
	v_mfma_f32_16x16x32_bf16 v[108:111], v[180:183], v[212:215], v[108:111]
	v_mfma_f32_16x16x32_bf16 v[96:99], v[172:175], v[220:223], v[96:99]
	v_mfma_f32_16x16x32_bf16 v[92:95], v[180:183], v[220:223], v[92:95]
	v_mfma_f32_16x16x32_bf16 v[80:83], v[172:175], v[232:235], v[80:83]
	v_mfma_f32_16x16x32_bf16 v[76:79], v[180:183], v[232:235], v[76:79]
	v_mfma_f32_16x16x32_bf16 v[160:163], v[176:179], v[208:211], v[160:163]
	v_mfma_f32_16x16x32_bf16 v[156:159], v[184:187], v[208:211], v[156:159]
	v_mfma_f32_16x16x32_bf16 v[112:115], v[176:179], v[216:219], v[112:115]
	v_mfma_f32_16x16x32_bf16 v[108:111], v[184:187], v[216:219], v[108:111]
	v_mfma_f32_16x16x32_bf16 v[96:99], v[176:179], v[224:227], v[96:99]
	v_mfma_f32_16x16x32_bf16 v[92:95], v[184:187], v[224:227], v[92:95]
	v_mfma_f32_16x16x32_bf16 v[80:83], v[176:179], v[242:245], v[80:83]
	v_mfma_f32_16x16x32_bf16 v[76:79], v[184:187], v[242:245], v[76:79]
	s_setprio 0
	s_setprio 1
	v_mfma_f32_16x16x32_bf16 v[128:131], v[188:191], v[204:207], v[128:131]
	v_mfma_f32_16x16x32_bf16 v[120:123], v[196:199], v[204:207], v[120:123]
	v_mfma_f32_16x16x32_bf16 v[104:107], v[188:191], v[212:215], v[104:107]
	v_mfma_f32_16x16x32_bf16 v[100:103], v[196:199], v[212:215], v[100:103]
	v_mfma_f32_16x16x32_bf16 v[88:91], v[188:191], v[220:223], v[88:91]
	v_mfma_f32_16x16x32_bf16 v[84:87], v[196:199], v[220:223], v[84:87]
	v_mfma_f32_16x16x32_bf16 v[72:75], v[188:191], v[232:235], v[72:75]
	v_mfma_f32_16x16x32_bf16 v[68:71], v[196:199], v[232:235], v[68:71]
	v_mfma_f32_16x16x32_bf16 v[128:131], v[192:195], v[208:211], v[128:131]
	v_mfma_f32_16x16x32_bf16 v[120:123], v[200:203], v[208:211], v[120:123]
	v_mfma_f32_16x16x32_bf16 v[104:107], v[192:195], v[216:219], v[104:107]
	v_mfma_f32_16x16x32_bf16 v[100:103], v[200:203], v[216:219], v[100:103]
	v_mfma_f32_16x16x32_bf16 v[88:91], v[192:195], v[224:227], v[88:91]
	v_mfma_f32_16x16x32_bf16 v[84:87], v[200:203], v[224:227], v[84:87]
	v_mfma_f32_16x16x32_bf16 v[72:75], v[192:195], v[242:245], v[72:75]
	v_mfma_f32_16x16x32_bf16 v[68:71], v[200:203], v[242:245], v[68:71]
	s_setprio 0
	s_barrier
	ds_read_b128 v[204:207], v170 offset:49152
	ds_read_b128 v[208:211], v170 offset:50176
	ds_read_b128 v[212:215], v170 offset:51200
	ds_read_b128 v[216:219], v170 offset:52224
	ds_read_b128 v[220:223], v170 offset:53248
	ds_read_b128 v[224:227], v170 offset:54272
	ds_read_b128 v[232:235], v170 offset:55296
	ds_read_b128 v[242:245], v170 offset:56320
	s_add_i32 s48, s50, s16
	s_add_u32 s100, s10, s38
	s_addc_u32 s101, s11, s39
	s_mov_b32 m0, s48
	s_nop 0
	global_load_lds_dwordx4 v167, s[100:101]
	s_add_i32 m0, s48, 0x2000
	s_nop 0
	s_add_u32 s10, s10, 0x40080
	s_addc_u32 s11, s11, 0
	s_add_i32 s48, s51, s16
	global_load_lds_dwordx4 v168, s[100:101]
	s_mov_b32 m0, s48
	s_nop 0
	global_load_lds_dwordx4 v167, s[10:11]
	s_add_i32 m0, s48, 0x2000
	s_nop 0
	global_load_lds_dwordx4 v168, s[10:11]
	s_mov_b32 m0, s37
	s_add_u32 s100, s8, s38
	s_addc_u32 s101, s9, s39
	v_mov_b32_e32 v0, v166
	global_load_lds_dwordx4 v164, s[100:101]
	s_mov_b32 m0, s40
	s_nop 0
	global_load_lds_dwordx4 v166, s[100:101]
	s_waitcnt vmcnt(8)
	s_waitcnt lgkmcnt(0)
	s_barrier
	s_setprio 1
	s_waitcnt lgkmcnt(0)
	v_mfma_f32_16x16x32_bf16 v[64:67], v[172:175], v[204:207], v[64:67]
	v_mfma_f32_16x16x32_bf16 v[60:63], v[180:183], v[204:207], v[60:63]
	v_mfma_f32_16x16x32_bf16 v[48:51], v[172:175], v[212:215], v[48:51]
	v_mfma_f32_16x16x32_bf16 v[44:47], v[180:183], v[212:215], v[44:47]
	v_mfma_f32_16x16x32_bf16 v[32:35], v[172:175], v[220:223], v[32:35]
	v_mfma_f32_16x16x32_bf16 v[28:31], v[180:183], v[220:223], v[28:31]
	v_mfma_f32_16x16x32_bf16 v[16:19], v[172:175], v[232:235], v[16:19]
	v_mfma_f32_16x16x32_bf16 v[12:15], v[180:183], v[232:235], v[12:15]
	v_mfma_f32_16x16x32_bf16 v[64:67], v[176:179], v[208:211], v[64:67]
	v_mfma_f32_16x16x32_bf16 v[60:63], v[184:187], v[208:211], v[60:63]
	v_mfma_f32_16x16x32_bf16 v[48:51], v[176:179], v[216:219], v[48:51]
	v_mfma_f32_16x16x32_bf16 v[44:47], v[184:187], v[216:219], v[44:47]
	v_mfma_f32_16x16x32_bf16 v[32:35], v[176:179], v[224:227], v[32:35]
	v_mfma_f32_16x16x32_bf16 v[28:31], v[184:187], v[224:227], v[28:31]
	v_mfma_f32_16x16x32_bf16 v[16:19], v[176:179], v[242:245], v[16:19]
	v_mfma_f32_16x16x32_bf16 v[12:15], v[184:187], v[242:245], v[12:15]
	s_setprio 0
	s_setprio 1
	v_mfma_f32_16x16x32_bf16 v[56:59], v[188:191], v[204:207], v[56:59]
	v_mfma_f32_16x16x32_bf16 v[52:55], v[196:199], v[204:207], v[52:55]
	v_mfma_f32_16x16x32_bf16 v[40:43], v[188:191], v[212:215], v[40:43]
	v_mfma_f32_16x16x32_bf16 v[36:39], v[196:199], v[212:215], v[36:39]
	v_mfma_f32_16x16x32_bf16 v[24:27], v[188:191], v[220:223], v[24:27]
	v_mfma_f32_16x16x32_bf16 v[20:23], v[196:199], v[220:223], v[20:23]
	v_mfma_f32_16x16x32_bf16 v[6:9], v[188:191], v[232:235], v[8:11]
	v_mfma_f32_16x16x32_bf16 v[2:5], v[196:199], v[232:235], v[2:5]
	v_mfma_f32_16x16x32_bf16 v[56:59], v[192:195], v[208:211], v[56:59]
	v_mfma_f32_16x16x32_bf16 v[52:55], v[200:203], v[208:211], v[52:55]
	v_mfma_f32_16x16x32_bf16 v[40:43], v[192:195], v[216:219], v[40:43]
	v_mfma_f32_16x16x32_bf16 v[36:39], v[200:203], v[216:219], v[36:39]
	v_mfma_f32_16x16x32_bf16 v[24:27], v[192:195], v[224:227], v[24:27]
	v_mfma_f32_16x16x32_bf16 v[20:23], v[200:203], v[224:227], v[20:23]
	v_mfma_f32_16x16x32_bf16 v[8:11], v[192:195], v[242:245], v[6:9]
	v_mfma_f32_16x16x32_bf16 v[4:7], v[200:203], v[242:245], v[2:5]
	s_setprio 0
	s_barrier
	s_add_i32 s47, s47, 2
	s_add_u32 s6, s6, 0x100
	s_addc_u32 s7, s7, 0
	s_cmp_gt_u32 s47, 13
	s_cbranch_scc1 .LBB0_1573

.LBB0_1681:
	s_add_u32 s48, s6, s2
	s_addc_u32 s49, s7, s3
	s_add_u32 s10, s48, 0x100
	s_addc_u32 s11, s49, 0
	s_add_u32 s12, s37, s2
	s_addc_u32 s13, s40, s3
	s_add_i32 s47, 0, 0x10000
	s_cmp_eq_u32 s46, 12
	s_cselect_b32 s11, s7, s11
	s_cselect_b32 s10, s6, s10
	v_add_u32_e32 v0, s47, v136
	s_cselect_b32 s13, s9, s13
	s_cselect_b32 s12, s8, s12
	s_add_i32 s50, 0, 0x14000
	ds_read_b128 v[138:141], v0
	ds_read_b128 v[142:145], v0 offset:1024
	ds_read_b128 v[146:149], v0 offset:2048
	ds_read_b128 v[150:153], v0 offset:3072
	ds_read_b128 v[154:157], v0 offset:16384
	ds_read_b128 v[158:161], v0 offset:17408
	ds_read_b128 v[162:165], v0 offset:18432
	ds_read_b128 v[166:169], v0 offset:19456
	ds_read_b128 v[170:173], v137
	ds_read_b128 v[174:177], v137 offset:1024
	ds_read_b128 v[178:181], v137 offset:2048
	ds_read_b128 v[182:185], v137 offset:3072
	ds_read_b128 v[186:189], v137 offset:4096
	ds_read_b128 v[190:193], v137 offset:5120
	ds_read_b128 v[194:197], v137 offset:6144
	ds_read_b128 v[198:201], v137 offset:7168
	s_add_i32 m0, s23, 0xc000
	s_add_u32 s100, s48, s56
	s_addc_u32 s101, s49, s57
	global_load_lds_dwordx4 v130, s[100:101]
	s_add_i32 m0, s23, 0xe000
	s_nop 0
	global_load_lds_dwordx4 v132, s[100:101]
	s_waitcnt vmcnt(8)
	s_waitcnt lgkmcnt(0)
	s_barrier
	s_setprio 1
	s_waitcnt lgkmcnt(0)
	v_mfma_f32_16x16x32_bf16 v[126:129], v[138:141], v[170:173], v[126:129]
	v_mfma_f32_16x16x32_bf16 v[122:125], v[146:149], v[170:173], v[122:125]
	v_mfma_f32_16x16x32_bf16 v[110:113], v[138:141], v[178:181], v[110:113]
	v_mfma_f32_16x16x32_bf16 v[106:109], v[146:149], v[178:181], v[106:109]
	v_mfma_f32_16x16x32_bf16 v[94:97], v[138:141], v[186:189], v[94:97]
	v_mfma_f32_16x16x32_bf16 v[90:93], v[146:149], v[186:189], v[90:93]
	v_mfma_f32_16x16x32_bf16 v[78:81], v[138:141], v[194:197], v[78:81]
	v_mfma_f32_16x16x32_bf16 v[74:77], v[146:149], v[194:197], v[74:77]
	v_mfma_f32_16x16x32_bf16 v[126:129], v[142:145], v[174:177], v[126:129]
	v_mfma_f32_16x16x32_bf16 v[122:125], v[150:153], v[174:177], v[122:125]
	v_mfma_f32_16x16x32_bf16 v[110:113], v[142:145], v[182:185], v[110:113]
	v_mfma_f32_16x16x32_bf16 v[106:109], v[150:153], v[182:185], v[106:109]
	v_mfma_f32_16x16x32_bf16 v[94:97], v[142:145], v[190:193], v[94:97]
	v_mfma_f32_16x16x32_bf16 v[90:93], v[150:153], v[190:193], v[90:93]
	v_mfma_f32_16x16x32_bf16 v[78:81], v[142:145], v[198:201], v[78:81]
	v_mfma_f32_16x16x32_bf16 v[74:77], v[150:153], v[198:201], v[74:77]
	s_setprio 0
	s_setprio 1
	v_mfma_f32_16x16x32_bf16 v[118:121], v[154:157], v[170:173], v[118:121]
	v_mfma_f32_16x16x32_bf16 v[114:117], v[162:165], v[170:173], v[114:117]
	v_mfma_f32_16x16x32_bf16 v[102:105], v[154:157], v[178:181], v[102:105]
	v_mfma_f32_16x16x32_bf16 v[98:101], v[162:165], v[178:181], v[98:101]
	v_mfma_f32_16x16x32_bf16 v[86:89], v[154:157], v[186:189], v[86:89]
	v_mfma_f32_16x16x32_bf16 v[82:85], v[162:165], v[186:189], v[82:85]
	v_mfma_f32_16x16x32_bf16 v[70:73], v[154:157], v[194:197], v[70:73]
	v_mfma_f32_16x16x32_bf16 v[66:69], v[162:165], v[194:197], v[66:69]
	v_mfma_f32_16x16x32_bf16 v[118:121], v[158:161], v[174:177], v[118:121]
	v_mfma_f32_16x16x32_bf16 v[114:117], v[166:169], v[174:177], v[114:117]
	v_mfma_f32_16x16x32_bf16 v[102:105], v[158:161], v[182:185], v[102:105]
	v_mfma_f32_16x16x32_bf16 v[98:101], v[166:169], v[182:185], v[98:101]
	v_mfma_f32_16x16x32_bf16 v[86:89], v[158:161], v[190:193], v[86:89]
	v_mfma_f32_16x16x32_bf16 v[82:85], v[166:169], v[190:193], v[82:85]
	v_mfma_f32_16x16x32_bf16 v[70:73], v[158:161], v[198:201], v[70:73]
	v_mfma_f32_16x16x32_bf16 v[66:69], v[166:169], v[198:201], v[66:69]
	s_setprio 0
	s_barrier
	s_add_i32 s47, s47, s22
	ds_read_b128 v[170:173], v137 offset:16384
	ds_read_b128 v[174:177], v137 offset:17408
	ds_read_b128 v[178:181], v137 offset:18432
	ds_read_b128 v[182:185], v137 offset:19456
	ds_read_b128 v[186:189], v137 offset:20480
	ds_read_b128 v[190:193], v137 offset:21504
	ds_read_b128 v[194:197], v137 offset:22528
	ds_read_b128 v[198:201], v137 offset:23552
	s_mov_b32 m0, s47
	s_nop 0
	global_load_lds_dwordx4 v134, s[12:13]
	s_add_i32 m0, s47, 0x2000
	s_add_u32 s48, s12, 0x40000
	global_load_lds_dwordx4 v135, s[12:13]
	s_addc_u32 s49, s13, 0
	s_add_i32 s47, s50, s22
	s_mov_b32 m0, s47
	s_nop 0
	global_load_lds_dwordx4 v134, s[48:49]
	s_add_i32 m0, s47, 0x2000
	s_nop 0
	global_load_lds_dwordx4 v135, s[48:49]
	s_mov_b32 m0, s23
	s_nop 0
	global_load_lds_dwordx4 v130, s[10:11]
	s_mov_b32 m0, s24
	s_nop 0
	global_load_lds_dwordx4 v132, s[10:11]
	s_waitcnt vmcnt(8)
	s_waitcnt lgkmcnt(0)
	s_barrier
	s_setprio 1
	s_waitcnt lgkmcnt(0)
	v_mfma_f32_16x16x32_bf16 v[62:65], v[138:141], v[170:173], v[62:65]
	v_mfma_f32_16x16x32_bf16 v[58:61], v[146:149], v[170:173], v[58:61]
	v_mfma_f32_16x16x32_bf16 v[46:49], v[138:141], v[178:181], v[46:49]
	v_mfma_f32_16x16x32_bf16 v[42:45], v[146:149], v[178:181], v[42:45]
	v_mfma_f32_16x16x32_bf16 v[30:33], v[138:141], v[186:189], v[30:33]
	v_mfma_f32_16x16x32_bf16 v[26:29], v[146:149], v[186:189], v[26:29]
	v_mfma_f32_16x16x32_bf16 v[14:17], v[138:141], v[194:197], v[14:17]
	v_mfma_f32_16x16x32_bf16 v[10:13], v[146:149], v[194:197], v[10:13]
	v_mfma_f32_16x16x32_bf16 v[62:65], v[142:145], v[174:177], v[62:65]
	v_mfma_f32_16x16x32_bf16 v[58:61], v[150:153], v[174:177], v[58:61]
	v_mfma_f32_16x16x32_bf16 v[46:49], v[142:145], v[182:185], v[46:49]
	v_mfma_f32_16x16x32_bf16 v[42:45], v[150:153], v[182:185], v[42:45]
	v_mfma_f32_16x16x32_bf16 v[30:33], v[142:145], v[190:193], v[30:33]
	v_mfma_f32_16x16x32_bf16 v[26:29], v[150:153], v[190:193], v[26:29]
	v_mfma_f32_16x16x32_bf16 v[14:17], v[142:145], v[198:201], v[14:17]
	v_mfma_f32_16x16x32_bf16 v[10:13], v[150:153], v[198:201], v[10:13]
	s_setprio 0
	s_setprio 1
	v_mfma_f32_16x16x32_bf16 v[54:57], v[154:157], v[170:173], v[54:57]
	v_mfma_f32_16x16x32_bf16 v[50:53], v[162:165], v[170:173], v[50:53]
	v_mfma_f32_16x16x32_bf16 v[38:41], v[154:157], v[178:181], v[38:41]
	v_mfma_f32_16x16x32_bf16 v[34:37], v[162:165], v[178:181], v[34:37]
	v_mfma_f32_16x16x32_bf16 v[22:25], v[154:157], v[186:189], v[22:25]
	v_mfma_f32_16x16x32_bf16 v[18:21], v[162:165], v[186:189], v[18:21]
	v_mfma_f32_16x16x32_bf16 v[6:9], v[154:157], v[194:197], v[6:9]
	v_mfma_f32_16x16x32_bf16 v[2:5], v[162:165], v[194:197], v[2:5]
	v_mfma_f32_16x16x32_bf16 v[54:57], v[158:161], v[174:177], v[54:57]
	v_mfma_f32_16x16x32_bf16 v[50:53], v[166:169], v[174:177], v[50:53]
	v_mfma_f32_16x16x32_bf16 v[38:41], v[158:161], v[182:185], v[38:41]
	v_mfma_f32_16x16x32_bf16 v[34:37], v[166:169], v[182:185], v[34:37]
	v_mfma_f32_16x16x32_bf16 v[22:25], v[158:161], v[190:193], v[22:25]
	v_mfma_f32_16x16x32_bf16 v[18:21], v[166:169], v[190:193], v[18:21]
	v_mfma_f32_16x16x32_bf16 v[6:9], v[158:161], v[198:201], v[6:9]
	v_mfma_f32_16x16x32_bf16 v[2:5], v[166:169], v[198:201], v[2:5]
	s_setprio 0
	s_barrier
	s_add_i32 s47, 0, 0x18000
	s_add_i32 s50, 0, 0x1c000
	ds_read_b128 v[138:141], v0 offset:32768
	ds_read_b128 v[142:145], v0 offset:33792
	ds_read_b128 v[146:149], v0 offset:34816
	ds_read_b128 v[150:153], v0 offset:35840
	ds_read_b128 v[154:157], v0 offset:49152
	ds_read_b128 v[158:161], v0 offset:50176
	ds_read_b128 v[162:165], v0 offset:51200
	ds_read_b128 v[166:169], v0 offset:52224
	s_add_u32 s48, s10, 0x40000
	s_mov_b32 m0, s25
	ds_read_b128 v[170:173], v137 offset:32768
	ds_read_b128 v[174:177], v137 offset:33792
	ds_read_b128 v[178:181], v137 offset:34816
	ds_read_b128 v[182:185], v137 offset:35840
	ds_read_b128 v[186:189], v137 offset:36864
	ds_read_b128 v[190:193], v137 offset:37888
	ds_read_b128 v[194:197], v137 offset:38912
	ds_read_b128 v[198:201], v137 offset:39936
	s_addc_u32 s49, s11, 0
	s_nop 0
	global_load_lds_dwordx4 v130, s[48:49]
	s_mov_b32 m0, s26
	s_nop 0
	global_load_lds_dwordx4 v132, s[48:49]
	s_waitcnt vmcnt(8)
	s_waitcnt lgkmcnt(0)
	s_barrier
	s_setprio 1
	s_waitcnt lgkmcnt(0)
	v_mfma_f32_16x16x32_bf16 v[126:129], v[138:141], v[170:173], v[126:129]
	v_mfma_f32_16x16x32_bf16 v[122:125], v[146:149], v[170:173], v[122:125]
	v_mfma_f32_16x16x32_bf16 v[110:113], v[138:141], v[178:181], v[110:113]
	v_mfma_f32_16x16x32_bf16 v[106:109], v[146:149], v[178:181], v[106:109]
	v_mfma_f32_16x16x32_bf16 v[94:97], v[138:141], v[186:189], v[94:97]
	v_mfma_f32_16x16x32_bf16 v[90:93], v[146:149], v[186:189], v[90:93]
	v_mfma_f32_16x16x32_bf16 v[78:81], v[138:141], v[194:197], v[78:81]
	v_mfma_f32_16x16x32_bf16 v[74:77], v[146:149], v[194:197], v[74:77]
	v_mfma_f32_16x16x32_bf16 v[126:129], v[142:145], v[174:177], v[126:129]
	v_mfma_f32_16x16x32_bf16 v[122:125], v[150:153], v[174:177], v[122:125]
	v_mfma_f32_16x16x32_bf16 v[110:113], v[142:145], v[182:185], v[110:113]
	v_mfma_f32_16x16x32_bf16 v[106:109], v[150:153], v[182:185], v[106:109]
	v_mfma_f32_16x16x32_bf16 v[94:97], v[142:145], v[190:193], v[94:97]
	v_mfma_f32_16x16x32_bf16 v[90:93], v[150:153], v[190:193], v[90:93]
	v_mfma_f32_16x16x32_bf16 v[78:81], v[142:145], v[198:201], v[78:81]
	v_mfma_f32_16x16x32_bf16 v[74:77], v[150:153], v[198:201], v[74:77]
	s_setprio 0
	s_setprio 1
	v_mfma_f32_16x16x32_bf16 v[118:121], v[154:157], v[170:173], v[118:121]
	v_mfma_f32_16x16x32_bf16 v[114:117], v[162:165], v[170:173], v[114:117]
	v_mfma_f32_16x16x32_bf16 v[102:105], v[154:157], v[178:181], v[102:105]
	v_mfma_f32_16x16x32_bf16 v[98:101], v[162:165], v[178:181], v[98:101]
	v_mfma_f32_16x16x32_bf16 v[86:89], v[154:157], v[186:189], v[86:89]
	v_mfma_f32_16x16x32_bf16 v[82:85], v[162:165], v[186:189], v[82:85]
	v_mfma_f32_16x16x32_bf16 v[70:73], v[154:157], v[194:197], v[70:73]
	v_mfma_f32_16x16x32_bf16 v[66:69], v[162:165], v[194:197], v[66:69]
	v_mfma_f32_16x16x32_bf16 v[118:121], v[158:161], v[174:177], v[118:121]
	v_mfma_f32_16x16x32_bf16 v[114:117], v[166:169], v[174:177], v[114:117]
	v_mfma_f32_16x16x32_bf16 v[102:105], v[158:161], v[182:185], v[102:105]
	v_mfma_f32_16x16x32_bf16 v[98:101], v[166:169], v[182:185], v[98:101]
	v_mfma_f32_16x16x32_bf16 v[86:89], v[158:161], v[190:193], v[86:89]
	v_mfma_f32_16x16x32_bf16 v[82:85], v[166:169], v[190:193], v[82:85]
	v_mfma_f32_16x16x32_bf16 v[70:73], v[158:161], v[198:201], v[70:73]
	v_mfma_f32_16x16x32_bf16 v[66:69], v[166:169], v[198:201], v[66:69]
	s_setprio 0
	s_barrier
	ds_read_b128 v[170:173], v137 offset:49152
	ds_read_b128 v[174:177], v137 offset:50176
	ds_read_b128 v[178:181], v137 offset:51200
	ds_read_b128 v[182:185], v137 offset:52224
	ds_read_b128 v[186:189], v137 offset:53248
	ds_read_b128 v[190:193], v137 offset:54272
	ds_read_b128 v[194:197], v137 offset:55296
	ds_read_b128 v[198:201], v137 offset:56320
	s_add_i32 s47, s47, s22
	s_add_u32 s100, s12, s38
	s_addc_u32 s101, s13, s39
	s_mov_b32 m0, s47
	s_nop 0
	global_load_lds_dwordx4 v134, s[100:101]
	s_add_i32 m0, s47, 0x2000
	s_nop 0
	s_add_u32 s12, s12, 0x40080
	s_addc_u32 s13, s13, 0
	s_add_i32 s47, s50, s22
	global_load_lds_dwordx4 v135, s[100:101]
	s_mov_b32 m0, s47
	s_nop 0
	global_load_lds_dwordx4 v134, s[12:13]
	s_add_i32 m0, s47, 0x2000
	s_nop 0
	global_load_lds_dwordx4 v135, s[12:13]
	s_mov_b32 m0, s42
	s_add_u32 s100, s10, s38
	s_addc_u32 s101, s11, s39
	v_mov_b32_e32 v0, v132
	global_load_lds_dwordx4 v130, s[100:101]
	s_mov_b32 m0, s43
	s_nop 0
	global_load_lds_dwordx4 v132, s[100:101]
	s_waitcnt vmcnt(8)
	s_waitcnt lgkmcnt(0)
	s_barrier
	s_setprio 1
	s_waitcnt lgkmcnt(0)
	v_mfma_f32_16x16x32_bf16 v[62:65], v[138:141], v[170:173], v[62:65]
	v_mfma_f32_16x16x32_bf16 v[58:61], v[146:149], v[170:173], v[58:61]
	v_mfma_f32_16x16x32_bf16 v[46:49], v[138:141], v[178:181], v[46:49]
	v_mfma_f32_16x16x32_bf16 v[42:45], v[146:149], v[178:181], v[42:45]
	v_mfma_f32_16x16x32_bf16 v[30:33], v[138:141], v[186:189], v[30:33]
	v_mfma_f32_16x16x32_bf16 v[26:29], v[146:149], v[186:189], v[26:29]
	v_mfma_f32_16x16x32_bf16 v[14:17], v[138:141], v[194:197], v[14:17]
	v_mfma_f32_16x16x32_bf16 v[10:13], v[146:149], v[194:197], v[10:13]
	v_mfma_f32_16x16x32_bf16 v[62:65], v[142:145], v[174:177], v[62:65]
	v_mfma_f32_16x16x32_bf16 v[58:61], v[150:153], v[174:177], v[58:61]
	v_mfma_f32_16x16x32_bf16 v[46:49], v[142:145], v[182:185], v[46:49]
	v_mfma_f32_16x16x32_bf16 v[42:45], v[150:153], v[182:185], v[42:45]
	v_mfma_f32_16x16x32_bf16 v[30:33], v[142:145], v[190:193], v[30:33]
	v_mfma_f32_16x16x32_bf16 v[26:29], v[150:153], v[190:193], v[26:29]
	v_mfma_f32_16x16x32_bf16 v[14:17], v[142:145], v[198:201], v[14:17]
	v_mfma_f32_16x16x32_bf16 v[10:13], v[150:153], v[198:201], v[10:13]
	s_setprio 0
	s_setprio 1
	v_mfma_f32_16x16x32_bf16 v[54:57], v[154:157], v[170:173], v[54:57]
	v_mfma_f32_16x16x32_bf16 v[50:53], v[162:165], v[170:173], v[50:53]
	v_mfma_f32_16x16x32_bf16 v[38:41], v[154:157], v[178:181], v[38:41]
	v_mfma_f32_16x16x32_bf16 v[34:37], v[162:165], v[178:181], v[34:37]
	v_mfma_f32_16x16x32_bf16 v[22:25], v[154:157], v[186:189], v[22:25]
	v_mfma_f32_16x16x32_bf16 v[18:21], v[162:165], v[186:189], v[18:21]
	v_mfma_f32_16x16x32_bf16 v[6:9], v[154:157], v[194:197], v[6:9]
	v_mfma_f32_16x16x32_bf16 v[2:5], v[162:165], v[194:197], v[2:5]
	v_mfma_f32_16x16x32_bf16 v[54:57], v[158:161], v[174:177], v[54:57]
	v_mfma_f32_16x16x32_bf16 v[50:53], v[166:169], v[174:177], v[50:53]
	v_mfma_f32_16x16x32_bf16 v[38:41], v[158:161], v[182:185], v[38:41]
	v_mfma_f32_16x16x32_bf16 v[34:37], v[166:169], v[182:185], v[34:37]
	v_mfma_f32_16x16x32_bf16 v[22:25], v[158:161], v[190:193], v[22:25]
	v_mfma_f32_16x16x32_bf16 v[18:21], v[166:169], v[190:193], v[18:21]
	v_mfma_f32_16x16x32_bf16 v[6:9], v[158:161], v[198:201], v[6:9]
	v_mfma_f32_16x16x32_bf16 v[2:5], v[166:169], v[198:201], v[2:5]
	s_setprio 0
	s_barrier
	s_add_i32 s46, s46, 2
	s_add_u32 s2, s2, 0x100
	s_addc_u32 s3, s3, 0
	s_cmp_gt_u32 s46, 13
	s_cbranch_scc0 .LBB0_1681
	s_cmpk_lt_u32 s17, 0x100
	s_cbranch_scc0 .LBB0_1684
	s_barrier

.LBB0_1807:
	s_add_u32 s68, s4, s14
	s_addc_u32 s69, s5, s15
	s_add_u32 s16, s68, 0x100
	s_addc_u32 s17, s69, 0
	s_add_u32 s22, s50, s14
	s_addc_u32 s23, s51, s15
	s_add_i32 s67, 0, 0x10000
	s_cmp_eq_u32 s66, 12
	s_cselect_b32 s17, s5, s17
	s_cselect_b32 s16, s4, s16
	v_add_u32_e32 v0, s67, v126
	s_cselect_b32 s23, s13, s23
	s_cselect_b32 s22, s12, s22
	s_add_i32 s70, 0, 0x14000
	ds_read_b128 v[128:131], v0
	ds_read_b128 v[142:145], v0 offset:1024
	ds_read_b128 v[146:149], v0 offset:2048
	ds_read_b128 v[150:153], v0 offset:3072
	ds_read_b128 v[154:157], v0 offset:16384
	ds_read_b128 v[160:163], v0 offset:17408
	ds_read_b128 v[164:167], v0 offset:18432
	ds_read_b128 v[168:171], v0 offset:19456
	ds_read_b128 v[172:175], v127
	ds_read_b128 v[176:179], v127 offset:1024
	ds_read_b128 v[180:183], v127 offset:2048
	ds_read_b128 v[184:187], v127 offset:3072
	ds_read_b128 v[188:191], v127 offset:4096
	ds_read_b128 v[192:195], v127 offset:5120
	ds_read_b128 v[196:199], v127 offset:6144
	ds_read_b128 v[200:203], v127 offset:7168
	s_add_i32 m0, s43, 0xc000
	s_add_u32 s100, s68, s56
	s_addc_u32 s101, s69, s57
	global_load_lds_dwordx4 v122, s[100:101]
	s_add_i32 m0, s43, 0xe000
	s_nop 0
	global_load_lds_dwordx4 v123, s[100:101]
	s_waitcnt vmcnt(8)
	s_waitcnt lgkmcnt(0)
	s_barrier
	s_setprio 1
	s_waitcnt lgkmcnt(0)
	v_mfma_f32_16x16x32_bf16 v[138:141], v[128:131], v[172:175], v[138:141]
	v_mfma_f32_16x16x32_bf16 v[132:135], v[146:149], v[172:175], v[134:137]
	v_mfma_f32_16x16x32_bf16 v[110:113], v[128:131], v[180:183], v[110:113]
	v_mfma_f32_16x16x32_bf16 v[106:109], v[146:149], v[180:183], v[106:109]
	v_mfma_f32_16x16x32_bf16 v[94:97], v[128:131], v[188:191], v[94:97]
	v_mfma_f32_16x16x32_bf16 v[90:93], v[146:149], v[188:191], v[90:93]
	v_mfma_f32_16x16x32_bf16 v[78:81], v[128:131], v[196:199], v[78:81]
	v_mfma_f32_16x16x32_bf16 v[74:77], v[146:149], v[196:199], v[74:77]
	v_mfma_f32_16x16x32_bf16 v[138:141], v[142:145], v[176:179], v[138:141]
	v_mfma_f32_16x16x32_bf16 v[132:135], v[150:153], v[176:179], v[132:135]
	v_mfma_f32_16x16x32_bf16 v[110:113], v[142:145], v[184:187], v[110:113]
	v_mfma_f32_16x16x32_bf16 v[106:109], v[150:153], v[184:187], v[106:109]
	v_mfma_f32_16x16x32_bf16 v[94:97], v[142:145], v[192:195], v[94:97]
	v_mfma_f32_16x16x32_bf16 v[90:93], v[150:153], v[192:195], v[90:93]
	v_mfma_f32_16x16x32_bf16 v[78:81], v[142:145], v[200:203], v[78:81]
	v_mfma_f32_16x16x32_bf16 v[74:77], v[150:153], v[200:203], v[74:77]
	s_setprio 0
	s_setprio 1
	v_mfma_f32_16x16x32_bf16 v[118:121], v[154:157], v[172:175], v[118:121]
	v_mfma_f32_16x16x32_bf16 v[114:117], v[164:167], v[172:175], v[114:117]
	v_mfma_f32_16x16x32_bf16 v[102:105], v[154:157], v[180:183], v[102:105]
	v_mfma_f32_16x16x32_bf16 v[98:101], v[164:167], v[180:183], v[98:101]
	v_mfma_f32_16x16x32_bf16 v[86:89], v[154:157], v[188:191], v[86:89]
	v_mfma_f32_16x16x32_bf16 v[82:85], v[164:167], v[188:191], v[82:85]
	v_mfma_f32_16x16x32_bf16 v[70:73], v[154:157], v[196:199], v[70:73]
	v_mfma_f32_16x16x32_bf16 v[66:69], v[164:167], v[196:199], v[66:69]
	v_mfma_f32_16x16x32_bf16 v[118:121], v[160:163], v[176:179], v[118:121]
	v_mfma_f32_16x16x32_bf16 v[114:117], v[168:171], v[176:179], v[114:117]
	v_mfma_f32_16x16x32_bf16 v[102:105], v[160:163], v[184:187], v[102:105]
	v_mfma_f32_16x16x32_bf16 v[98:101], v[168:171], v[184:187], v[98:101]
	v_mfma_f32_16x16x32_bf16 v[86:89], v[160:163], v[192:195], v[86:89]
	v_mfma_f32_16x16x32_bf16 v[82:85], v[168:171], v[192:195], v[82:85]
	v_mfma_f32_16x16x32_bf16 v[70:73], v[160:163], v[200:203], v[70:73]
	v_mfma_f32_16x16x32_bf16 v[66:69], v[168:171], v[200:203], v[66:69]
	s_setprio 0
	s_barrier
	s_add_i32 s67, s67, s42
	ds_read_b128 v[172:175], v127 offset:16384
	ds_read_b128 v[176:179], v127 offset:17408
	ds_read_b128 v[180:183], v127 offset:18432
	ds_read_b128 v[184:187], v127 offset:19456
	ds_read_b128 v[188:191], v127 offset:20480
	ds_read_b128 v[192:195], v127 offset:21504
	ds_read_b128 v[196:199], v127 offset:22528
	ds_read_b128 v[200:203], v127 offset:23552
	s_mov_b32 m0, s67
	s_nop 0
	global_load_lds_dwordx4 v124, s[22:23]
	s_add_i32 m0, s67, 0x2000
	s_add_u32 s68, s22, 0x40000
	global_load_lds_dwordx4 v125, s[22:23]
	s_addc_u32 s69, s23, 0
	s_add_i32 s67, s70, s42
	s_mov_b32 m0, s67
	s_nop 0
	global_load_lds_dwordx4 v124, s[68:69]
	s_add_i32 m0, s67, 0x2000
	s_nop 0
	global_load_lds_dwordx4 v125, s[68:69]
	s_mov_b32 m0, s43
	s_nop 0
	global_load_lds_dwordx4 v122, s[16:17]
	s_mov_b32 m0, s46
	s_nop 0
	global_load_lds_dwordx4 v123, s[16:17]
	s_waitcnt vmcnt(8)
	s_waitcnt lgkmcnt(0)
	s_barrier
	s_setprio 1
	s_waitcnt lgkmcnt(0)
	v_mfma_f32_16x16x32_bf16 v[62:65], v[128:131], v[172:175], v[62:65]
	v_mfma_f32_16x16x32_bf16 v[58:61], v[146:149], v[172:175], v[58:61]
	v_mfma_f32_16x16x32_bf16 v[46:49], v[128:131], v[180:183], v[46:49]
	v_mfma_f32_16x16x32_bf16 v[42:45], v[146:149], v[180:183], v[42:45]
	v_mfma_f32_16x16x32_bf16 v[30:33], v[128:131], v[188:191], v[30:33]
	v_mfma_f32_16x16x32_bf16 v[26:29], v[146:149], v[188:191], v[26:29]
	v_mfma_f32_16x16x32_bf16 v[14:17], v[128:131], v[196:199], v[14:17]
	v_mfma_f32_16x16x32_bf16 v[10:13], v[146:149], v[196:199], v[10:13]
	v_mfma_f32_16x16x32_bf16 v[62:65], v[142:145], v[176:179], v[62:65]
	v_mfma_f32_16x16x32_bf16 v[58:61], v[150:153], v[176:179], v[58:61]
	v_mfma_f32_16x16x32_bf16 v[46:49], v[142:145], v[184:187], v[46:49]
	v_mfma_f32_16x16x32_bf16 v[42:45], v[150:153], v[184:187], v[42:45]
	v_mfma_f32_16x16x32_bf16 v[30:33], v[142:145], v[192:195], v[30:33]
	v_mfma_f32_16x16x32_bf16 v[26:29], v[150:153], v[192:195], v[26:29]
	v_mfma_f32_16x16x32_bf16 v[14:17], v[142:145], v[200:203], v[14:17]
	v_mfma_f32_16x16x32_bf16 v[10:13], v[150:153], v[200:203], v[10:13]
	s_setprio 0
	s_setprio 1
	v_mfma_f32_16x16x32_bf16 v[54:57], v[154:157], v[172:175], v[54:57]
	v_mfma_f32_16x16x32_bf16 v[50:53], v[164:167], v[172:175], v[50:53]
	v_mfma_f32_16x16x32_bf16 v[38:41], v[154:157], v[180:183], v[38:41]
	v_mfma_f32_16x16x32_bf16 v[34:37], v[164:167], v[180:183], v[34:37]
	v_mfma_f32_16x16x32_bf16 v[22:25], v[154:157], v[188:191], v[22:25]
	v_mfma_f32_16x16x32_bf16 v[18:21], v[164:167], v[188:191], v[18:21]
	v_mfma_f32_16x16x32_bf16 v[6:9], v[154:157], v[196:199], v[6:9]
	v_mfma_f32_16x16x32_bf16 v[2:5], v[164:167], v[196:199], v[2:5]
	v_mfma_f32_16x16x32_bf16 v[54:57], v[160:163], v[176:179], v[54:57]
	v_mfma_f32_16x16x32_bf16 v[50:53], v[168:171], v[176:179], v[50:53]
	v_mfma_f32_16x16x32_bf16 v[38:41], v[160:163], v[184:187], v[38:41]
	v_mfma_f32_16x16x32_bf16 v[34:37], v[168:171], v[184:187], v[34:37]
	v_mfma_f32_16x16x32_bf16 v[22:25], v[160:163], v[192:195], v[22:25]
	v_mfma_f32_16x16x32_bf16 v[18:21], v[168:171], v[192:195], v[18:21]
	v_mfma_f32_16x16x32_bf16 v[6:9], v[160:163], v[200:203], v[6:9]
	v_mfma_f32_16x16x32_bf16 v[2:5], v[168:171], v[200:203], v[2:5]
	s_setprio 0
	s_barrier
	s_add_i32 s67, 0, 0x18000
	s_add_i32 s70, 0, 0x1c000
	ds_read_b128 v[128:131], v0 offset:32768
	ds_read_b128 v[142:145], v0 offset:33792
	ds_read_b128 v[146:149], v0 offset:34816
	ds_read_b128 v[150:153], v0 offset:35840
	ds_read_b128 v[154:157], v0 offset:49152
	ds_read_b128 v[160:163], v0 offset:50176
	ds_read_b128 v[164:167], v0 offset:51200
	ds_read_b128 v[168:171], v0 offset:52224
	s_add_u32 s68, s16, 0x40000
	s_mov_b32 m0, s47
	ds_read_b128 v[172:175], v127 offset:32768
	ds_read_b128 v[176:179], v127 offset:33792
	ds_read_b128 v[180:183], v127 offset:34816
	ds_read_b128 v[184:187], v127 offset:35840
	ds_read_b128 v[188:191], v127 offset:36864
	ds_read_b128 v[192:195], v127 offset:37888
	ds_read_b128 v[196:199], v127 offset:38912
	ds_read_b128 v[200:203], v127 offset:39936
	s_addc_u32 s69, s17, 0
	s_nop 0
	global_load_lds_dwordx4 v122, s[68:69]
	s_mov_b32 m0, s48
	s_nop 0
	global_load_lds_dwordx4 v123, s[68:69]
	s_waitcnt vmcnt(8)
	s_waitcnt lgkmcnt(0)
	s_barrier
	s_setprio 1
	s_waitcnt lgkmcnt(0)
	v_mfma_f32_16x16x32_bf16 v[136:139], v[128:131], v[172:175], v[138:141]
	v_mfma_f32_16x16x32_bf16 v[132:135], v[146:149], v[172:175], v[132:135]
	v_mfma_f32_16x16x32_bf16 v[110:113], v[128:131], v[180:183], v[110:113]
	v_mfma_f32_16x16x32_bf16 v[106:109], v[146:149], v[180:183], v[106:109]
	v_mfma_f32_16x16x32_bf16 v[94:97], v[128:131], v[188:191], v[94:97]
	v_mfma_f32_16x16x32_bf16 v[90:93], v[146:149], v[188:191], v[90:93]
	v_mfma_f32_16x16x32_bf16 v[78:81], v[128:131], v[196:199], v[78:81]
	v_mfma_f32_16x16x32_bf16 v[74:77], v[146:149], v[196:199], v[74:77]
	v_mfma_f32_16x16x32_bf16 v[138:141], v[142:145], v[176:179], v[136:139]
	v_mfma_f32_16x16x32_bf16 v[134:137], v[150:153], v[176:179], v[132:135]
	v_mfma_f32_16x16x32_bf16 v[110:113], v[142:145], v[184:187], v[110:113]
	v_mfma_f32_16x16x32_bf16 v[106:109], v[150:153], v[184:187], v[106:109]
	v_mfma_f32_16x16x32_bf16 v[94:97], v[142:145], v[192:195], v[94:97]
	v_mfma_f32_16x16x32_bf16 v[90:93], v[150:153], v[192:195], v[90:93]
	v_mfma_f32_16x16x32_bf16 v[78:81], v[142:145], v[200:203], v[78:81]
	v_mfma_f32_16x16x32_bf16 v[74:77], v[150:153], v[200:203], v[74:77]
	s_setprio 0
	s_setprio 1
	v_mfma_f32_16x16x32_bf16 v[118:121], v[154:157], v[172:175], v[118:121]
	v_mfma_f32_16x16x32_bf16 v[114:117], v[164:167], v[172:175], v[114:117]
	v_mfma_f32_16x16x32_bf16 v[102:105], v[154:157], v[180:183], v[102:105]
	v_mfma_f32_16x16x32_bf16 v[98:101], v[164:167], v[180:183], v[98:101]
	v_mfma_f32_16x16x32_bf16 v[86:89], v[154:157], v[188:191], v[86:89]
	v_mfma_f32_16x16x32_bf16 v[82:85], v[164:167], v[188:191], v[82:85]
	v_mfma_f32_16x16x32_bf16 v[70:73], v[154:157], v[196:199], v[70:73]
	v_mfma_f32_16x16x32_bf16 v[66:69], v[164:167], v[196:199], v[66:69]
	v_mfma_f32_16x16x32_bf16 v[118:121], v[160:163], v[176:179], v[118:121]
	v_mfma_f32_16x16x32_bf16 v[114:117], v[168:171], v[176:179], v[114:117]
	v_mfma_f32_16x16x32_bf16 v[102:105], v[160:163], v[184:187], v[102:105]
	v_mfma_f32_16x16x32_bf16 v[98:101], v[168:171], v[184:187], v[98:101]
	v_mfma_f32_16x16x32_bf16 v[86:89], v[160:163], v[192:195], v[86:89]
	v_mfma_f32_16x16x32_bf16 v[82:85], v[168:171], v[192:195], v[82:85]
	v_mfma_f32_16x16x32_bf16 v[70:73], v[160:163], v[200:203], v[70:73]
	v_mfma_f32_16x16x32_bf16 v[66:69], v[168:171], v[200:203], v[66:69]
	s_setprio 0
	s_barrier
	ds_read_b128 v[172:175], v127 offset:49152
	ds_read_b128 v[176:179], v127 offset:50176
	ds_read_b128 v[180:183], v127 offset:51200
	ds_read_b128 v[184:187], v127 offset:52224
	ds_read_b128 v[188:191], v127 offset:53248
	ds_read_b128 v[192:195], v127 offset:54272
	ds_read_b128 v[196:199], v127 offset:55296
	ds_read_b128 v[200:203], v127 offset:56320
	s_add_i32 s67, s67, s42
	s_add_u32 s100, s22, s38
	s_addc_u32 s101, s23, s39
	s_mov_b32 m0, s67
	s_nop 0
	global_load_lds_dwordx4 v124, s[100:101]
	s_add_i32 m0, s67, 0x2000
	s_nop 0
	s_add_u32 s22, s22, 0x40080
	s_addc_u32 s23, s23, 0
	s_add_i32 s67, s70, s42
	global_load_lds_dwordx4 v125, s[100:101]
	s_mov_b32 m0, s67
	s_nop 0
	global_load_lds_dwordx4 v124, s[22:23]
	s_add_i32 m0, s67, 0x2000
	s_nop 0
	global_load_lds_dwordx4 v125, s[22:23]
	s_mov_b32 m0, s64
	s_add_u32 s100, s16, s38
	s_addc_u32 s101, s17, s39
	v_mov_b32_e32 v0, v123
	global_load_lds_dwordx4 v122, s[100:101]
	s_mov_b32 m0, s65
	s_nop 0
	global_load_lds_dwordx4 v123, s[100:101]
	s_waitcnt vmcnt(8)
	s_waitcnt lgkmcnt(0)
	s_barrier
	s_setprio 1
	s_waitcnt lgkmcnt(0)
	v_mfma_f32_16x16x32_bf16 v[62:65], v[128:131], v[172:175], v[62:65]
	v_mfma_f32_16x16x32_bf16 v[58:61], v[146:149], v[172:175], v[58:61]
	v_mfma_f32_16x16x32_bf16 v[46:49], v[128:131], v[180:183], v[46:49]
	v_mfma_f32_16x16x32_bf16 v[42:45], v[146:149], v[180:183], v[42:45]
	v_mfma_f32_16x16x32_bf16 v[30:33], v[128:131], v[188:191], v[30:33]
	v_mfma_f32_16x16x32_bf16 v[26:29], v[146:149], v[188:191], v[26:29]
	v_mfma_f32_16x16x32_bf16 v[14:17], v[128:131], v[196:199], v[14:17]
	v_mfma_f32_16x16x32_bf16 v[10:13], v[146:149], v[196:199], v[10:13]
	v_mfma_f32_16x16x32_bf16 v[62:65], v[142:145], v[176:179], v[62:65]
	v_mfma_f32_16x16x32_bf16 v[58:61], v[150:153], v[176:179], v[58:61]
	v_mfma_f32_16x16x32_bf16 v[46:49], v[142:145], v[184:187], v[46:49]
	v_mfma_f32_16x16x32_bf16 v[42:45], v[150:153], v[184:187], v[42:45]
	v_mfma_f32_16x16x32_bf16 v[30:33], v[142:145], v[192:195], v[30:33]
	v_mfma_f32_16x16x32_bf16 v[26:29], v[150:153], v[192:195], v[26:29]
	v_mfma_f32_16x16x32_bf16 v[14:17], v[142:145], v[200:203], v[14:17]
	v_mfma_f32_16x16x32_bf16 v[10:13], v[150:153], v[200:203], v[10:13]
	s_setprio 0
	s_setprio 1
	v_mfma_f32_16x16x32_bf16 v[54:57], v[154:157], v[172:175], v[54:57]
	v_mfma_f32_16x16x32_bf16 v[50:53], v[164:167], v[172:175], v[50:53]
	v_mfma_f32_16x16x32_bf16 v[38:41], v[154:157], v[180:183], v[38:41]
	v_mfma_f32_16x16x32_bf16 v[34:37], v[164:167], v[180:183], v[34:37]
	v_mfma_f32_16x16x32_bf16 v[22:25], v[154:157], v[188:191], v[22:25]
	v_mfma_f32_16x16x32_bf16 v[18:21], v[164:167], v[188:191], v[18:21]
	v_mfma_f32_16x16x32_bf16 v[6:9], v[154:157], v[196:199], v[6:9]
	v_mfma_f32_16x16x32_bf16 v[2:5], v[164:167], v[196:199], v[2:5]
	v_mfma_f32_16x16x32_bf16 v[54:57], v[160:163], v[176:179], v[54:57]
	v_mfma_f32_16x16x32_bf16 v[50:53], v[168:171], v[176:179], v[50:53]
	v_mfma_f32_16x16x32_bf16 v[38:41], v[160:163], v[184:187], v[38:41]
	v_mfma_f32_16x16x32_bf16 v[34:37], v[168:171], v[184:187], v[34:37]
	v_mfma_f32_16x16x32_bf16 v[22:25], v[160:163], v[192:195], v[22:25]
	v_mfma_f32_16x16x32_bf16 v[18:21], v[168:171], v[192:195], v[18:21]
	v_mfma_f32_16x16x32_bf16 v[6:9], v[160:163], v[200:203], v[6:9]
	v_mfma_f32_16x16x32_bf16 v[2:5], v[168:171], v[200:203], v[2:5]
	s_setprio 0
	s_barrier
	s_add_i32 s66, s66, 2
	s_add_u32 s14, s14, 0x100
	s_addc_u32 s15, s15, 0
	s_cmp_gt_u32 s66, 13
	s_cbranch_scc0 .LBB0_1807
	s_cmpk_lt_u32 s26, 0x100
	s_cbranch_scc0 .LBB0_1810
	s_barrier

.LBB0_1886:
	s_add_u32 s6, s4, 0xfffc0080
	s_addc_u32 s7, s5, -1
	s_add_i32 s47, 0, 0x10000
	s_cmp_eq_u32 s46, 12
	s_cselect_b32 s7, s3, s7
	s_cselect_b32 s6, s2, s6
	v_add_u32_e32 v0, s47, v127
	s_cselect_b32 s11, s40, s43
	s_cselect_b32 s10, s26, s37
	s_add_i32 s50, 0, 0x14000
	ds_read_b128 v[130:133], v0
	ds_read_b128 v[134:137], v0 offset:1024
	ds_read_b128 v[138:141], v0 offset:2048
	ds_read_b128 v[142:145], v0 offset:3072
	ds_read_b128 v[146:149], v0 offset:16384
	ds_read_b128 v[158:161], v0 offset:17408
	ds_read_b128 v[162:165], v0 offset:18432
	ds_read_b128 v[166:169], v0 offset:19456
	ds_read_b128 v[170:173], v128
	ds_read_b128 v[174:177], v128 offset:1024
	ds_read_b128 v[178:181], v128 offset:2048
	ds_read_b128 v[182:185], v128 offset:3072
	ds_read_b128 v[186:189], v128 offset:4096
	ds_read_b128 v[190:193], v128 offset:5120
	ds_read_b128 v[194:197], v128 offset:6144
	ds_read_b128 v[198:201], v128 offset:7168
	s_add_i32 m0, s17, 0xc000
	s_nop 0
	global_load_lds_dwordx4 v122, s[4:5]
	s_add_i32 m0, s17, 0xe000
	s_nop 0
	global_load_lds_dwordx4 v123, s[4:5]
	s_waitcnt vmcnt(8)
	s_waitcnt lgkmcnt(0)
	s_barrier
	s_setprio 1
	s_waitcnt lgkmcnt(0)
	v_mfma_f32_16x16x32_bf16 v[154:157], v[130:133], v[170:173], v[154:157]
	v_mfma_f32_16x16x32_bf16 v[150:153], v[138:141], v[170:173], v[150:153]
	v_mfma_f32_16x16x32_bf16 v[110:113], v[130:133], v[178:181], v[110:113]
	v_mfma_f32_16x16x32_bf16 v[106:109], v[138:141], v[178:181], v[106:109]
	v_mfma_f32_16x16x32_bf16 v[94:97], v[130:133], v[186:189], v[94:97]
	v_mfma_f32_16x16x32_bf16 v[90:93], v[138:141], v[186:189], v[90:93]
	v_mfma_f32_16x16x32_bf16 v[78:81], v[130:133], v[194:197], v[78:81]
	v_mfma_f32_16x16x32_bf16 v[74:77], v[138:141], v[194:197], v[74:77]
	v_mfma_f32_16x16x32_bf16 v[154:157], v[134:137], v[174:177], v[154:157]
	v_mfma_f32_16x16x32_bf16 v[150:153], v[142:145], v[174:177], v[150:153]
	v_mfma_f32_16x16x32_bf16 v[110:113], v[134:137], v[182:185], v[110:113]
	v_mfma_f32_16x16x32_bf16 v[106:109], v[142:145], v[182:185], v[106:109]
	v_mfma_f32_16x16x32_bf16 v[94:97], v[134:137], v[190:193], v[94:97]
	v_mfma_f32_16x16x32_bf16 v[90:93], v[142:145], v[190:193], v[90:93]
	v_mfma_f32_16x16x32_bf16 v[78:81], v[134:137], v[198:201], v[78:81]
	v_mfma_f32_16x16x32_bf16 v[74:77], v[142:145], v[198:201], v[74:77]
	s_setprio 0
	s_setprio 1
	v_mfma_f32_16x16x32_bf16 v[118:121], v[146:149], v[170:173], v[118:121]
	v_mfma_f32_16x16x32_bf16 v[114:117], v[162:165], v[170:173], v[114:117]
	v_mfma_f32_16x16x32_bf16 v[102:105], v[146:149], v[178:181], v[102:105]
	v_mfma_f32_16x16x32_bf16 v[98:101], v[162:165], v[178:181], v[98:101]
	v_mfma_f32_16x16x32_bf16 v[86:89], v[146:149], v[186:189], v[86:89]
	v_mfma_f32_16x16x32_bf16 v[82:85], v[162:165], v[186:189], v[82:85]
	v_mfma_f32_16x16x32_bf16 v[70:73], v[146:149], v[194:197], v[70:73]
	v_mfma_f32_16x16x32_bf16 v[66:69], v[162:165], v[194:197], v[66:69]
	v_mfma_f32_16x16x32_bf16 v[118:121], v[158:161], v[174:177], v[118:121]
	v_mfma_f32_16x16x32_bf16 v[114:117], v[166:169], v[174:177], v[114:117]
	v_mfma_f32_16x16x32_bf16 v[102:105], v[158:161], v[182:185], v[102:105]
	v_mfma_f32_16x16x32_bf16 v[98:101], v[166:169], v[182:185], v[98:101]
	v_mfma_f32_16x16x32_bf16 v[86:89], v[158:161], v[190:193], v[86:89]
	v_mfma_f32_16x16x32_bf16 v[82:85], v[166:169], v[190:193], v[82:85]
	v_mfma_f32_16x16x32_bf16 v[70:73], v[158:161], v[198:201], v[70:73]
	v_mfma_f32_16x16x32_bf16 v[66:69], v[166:169], v[198:201], v[66:69]
	s_setprio 0
	s_barrier
	s_add_i32 s47, s47, s16
	ds_read_b128 v[170:173], v128 offset:16384
	ds_read_b128 v[174:177], v128 offset:17408
	ds_read_b128 v[178:181], v128 offset:18432
	ds_read_b128 v[182:185], v128 offset:19456
	ds_read_b128 v[186:189], v128 offset:20480
	ds_read_b128 v[190:193], v128 offset:21504
	ds_read_b128 v[194:197], v128 offset:22528
	ds_read_b128 v[198:201], v128 offset:23552
	s_mov_b32 m0, s47
	s_nop 0
	global_load_lds_dwordx4 v125, s[10:11]
	s_add_i32 m0, s47, 0x2000
	s_add_u32 s48, s10, 0x40000
	global_load_lds_dwordx4 v126, s[10:11]
	s_addc_u32 s49, s11, 0
	s_add_i32 s47, s50, s16
	s_mov_b32 m0, s47
	s_nop 0
	global_load_lds_dwordx4 v125, s[48:49]
	s_add_i32 m0, s47, 0x2000
	s_nop 0
	global_load_lds_dwordx4 v126, s[48:49]
	s_mov_b32 m0, s17
	s_nop 0
	global_load_lds_dwordx4 v122, s[6:7]
	s_mov_b32 m0, s22
	s_nop 0
	global_load_lds_dwordx4 v123, s[6:7]
	s_waitcnt vmcnt(8)
	s_waitcnt lgkmcnt(0)
	s_barrier
	s_setprio 1
	s_waitcnt lgkmcnt(0)
	v_mfma_f32_16x16x32_bf16 v[62:65], v[130:133], v[170:173], v[62:65]
	v_mfma_f32_16x16x32_bf16 v[58:61], v[138:141], v[170:173], v[58:61]
	v_mfma_f32_16x16x32_bf16 v[46:49], v[130:133], v[178:181], v[46:49]
	v_mfma_f32_16x16x32_bf16 v[42:45], v[138:141], v[178:181], v[42:45]
	v_mfma_f32_16x16x32_bf16 v[30:33], v[130:133], v[186:189], v[30:33]
	v_mfma_f32_16x16x32_bf16 v[26:29], v[138:141], v[186:189], v[26:29]
	v_mfma_f32_16x16x32_bf16 v[14:17], v[130:133], v[194:197], v[14:17]
	v_mfma_f32_16x16x32_bf16 v[10:13], v[138:141], v[194:197], v[10:13]
	v_mfma_f32_16x16x32_bf16 v[62:65], v[134:137], v[174:177], v[62:65]
	v_mfma_f32_16x16x32_bf16 v[58:61], v[142:145], v[174:177], v[58:61]
	v_mfma_f32_16x16x32_bf16 v[46:49], v[134:137], v[182:185], v[46:49]
	v_mfma_f32_16x16x32_bf16 v[42:45], v[142:145], v[182:185], v[42:45]
	v_mfma_f32_16x16x32_bf16 v[30:33], v[134:137], v[190:193], v[30:33]
	v_mfma_f32_16x16x32_bf16 v[26:29], v[142:145], v[190:193], v[26:29]
	v_mfma_f32_16x16x32_bf16 v[14:17], v[134:137], v[198:201], v[14:17]
	v_mfma_f32_16x16x32_bf16 v[10:13], v[142:145], v[198:201], v[10:13]
	s_setprio 0
	s_setprio 1
	v_mfma_f32_16x16x32_bf16 v[54:57], v[146:149], v[170:173], v[54:57]
	v_mfma_f32_16x16x32_bf16 v[50:53], v[162:165], v[170:173], v[50:53]
	v_mfma_f32_16x16x32_bf16 v[38:41], v[146:149], v[178:181], v[38:41]
	v_mfma_f32_16x16x32_bf16 v[34:37], v[162:165], v[178:181], v[34:37]
	v_mfma_f32_16x16x32_bf16 v[22:25], v[146:149], v[186:189], v[22:25]
	v_mfma_f32_16x16x32_bf16 v[18:21], v[162:165], v[186:189], v[18:21]
	v_mfma_f32_16x16x32_bf16 v[6:9], v[146:149], v[194:197], v[6:9]
	v_mfma_f32_16x16x32_bf16 v[2:5], v[162:165], v[194:197], v[2:5]
	v_mfma_f32_16x16x32_bf16 v[54:57], v[158:161], v[174:177], v[54:57]
	v_mfma_f32_16x16x32_bf16 v[50:53], v[166:169], v[174:177], v[50:53]
	v_mfma_f32_16x16x32_bf16 v[38:41], v[158:161], v[182:185], v[38:41]
	v_mfma_f32_16x16x32_bf16 v[34:37], v[166:169], v[182:185], v[34:37]
	v_mfma_f32_16x16x32_bf16 v[22:25], v[158:161], v[190:193], v[22:25]
	v_mfma_f32_16x16x32_bf16 v[18:21], v[166:169], v[190:193], v[18:21]
	v_mfma_f32_16x16x32_bf16 v[6:9], v[158:161], v[198:201], v[6:9]
	v_mfma_f32_16x16x32_bf16 v[2:5], v[166:169], v[198:201], v[2:5]
	s_setprio 0
	s_barrier
	s_add_i32 s47, 0, 0x18000
	s_add_i32 s50, 0, 0x1c000
	ds_read_b128 v[130:133], v0 offset:32768
	ds_read_b128 v[134:137], v0 offset:33792
	ds_read_b128 v[138:141], v0 offset:34816
	ds_read_b128 v[142:145], v0 offset:35840
	ds_read_b128 v[146:149], v0 offset:49152
	ds_read_b128 v[158:161], v0 offset:50176
	ds_read_b128 v[162:165], v0 offset:51200
	ds_read_b128 v[166:169], v0 offset:52224
	s_add_u32 s48, s6, 0x40000
	s_mov_b32 m0, s23
	ds_read_b128 v[170:173], v128 offset:32768
	ds_read_b128 v[174:177], v128 offset:33792
	ds_read_b128 v[178:181], v128 offset:34816
	ds_read_b128 v[182:185], v128 offset:35840
	ds_read_b128 v[186:189], v128 offset:36864
	ds_read_b128 v[190:193], v128 offset:37888
	ds_read_b128 v[194:197], v128 offset:38912
	ds_read_b128 v[198:201], v128 offset:39936
	s_addc_u32 s49, s7, 0
	s_nop 0
	global_load_lds_dwordx4 v122, s[48:49]
	s_mov_b32 m0, s24
	s_nop 0
	global_load_lds_dwordx4 v123, s[48:49]
	s_waitcnt vmcnt(8)
	s_waitcnt lgkmcnt(0)
	s_barrier
	s_setprio 1
	s_waitcnt lgkmcnt(0)
	v_mfma_f32_16x16x32_bf16 v[154:157], v[130:133], v[170:173], v[154:157]
	v_mfma_f32_16x16x32_bf16 v[150:153], v[138:141], v[170:173], v[150:153]
	v_mfma_f32_16x16x32_bf16 v[110:113], v[130:133], v[178:181], v[110:113]
	v_mfma_f32_16x16x32_bf16 v[106:109], v[138:141], v[178:181], v[106:109]
	v_mfma_f32_16x16x32_bf16 v[94:97], v[130:133], v[186:189], v[94:97]
	v_mfma_f32_16x16x32_bf16 v[90:93], v[138:141], v[186:189], v[90:93]
	v_mfma_f32_16x16x32_bf16 v[78:81], v[130:133], v[194:197], v[78:81]
	v_mfma_f32_16x16x32_bf16 v[74:77], v[138:141], v[194:197], v[74:77]
	v_mfma_f32_16x16x32_bf16 v[154:157], v[134:137], v[174:177], v[154:157]
	v_mfma_f32_16x16x32_bf16 v[150:153], v[142:145], v[174:177], v[150:153]
	v_mfma_f32_16x16x32_bf16 v[110:113], v[134:137], v[182:185], v[110:113]
	v_mfma_f32_16x16x32_bf16 v[106:109], v[142:145], v[182:185], v[106:109]
	v_mfma_f32_16x16x32_bf16 v[94:97], v[134:137], v[190:193], v[94:97]
	v_mfma_f32_16x16x32_bf16 v[90:93], v[142:145], v[190:193], v[90:93]
	v_mfma_f32_16x16x32_bf16 v[78:81], v[134:137], v[198:201], v[78:81]
	v_mfma_f32_16x16x32_bf16 v[74:77], v[142:145], v[198:201], v[74:77]
	s_setprio 0
	s_setprio 1
	v_mfma_f32_16x16x32_bf16 v[118:121], v[146:149], v[170:173], v[118:121]
	v_mfma_f32_16x16x32_bf16 v[114:117], v[162:165], v[170:173], v[114:117]
	v_mfma_f32_16x16x32_bf16 v[102:105], v[146:149], v[178:181], v[102:105]
	v_mfma_f32_16x16x32_bf16 v[98:101], v[162:165], v[178:181], v[98:101]
	v_mfma_f32_16x16x32_bf16 v[86:89], v[146:149], v[186:189], v[86:89]
	v_mfma_f32_16x16x32_bf16 v[82:85], v[162:165], v[186:189], v[82:85]
	v_mfma_f32_16x16x32_bf16 v[70:73], v[146:149], v[194:197], v[70:73]
	v_mfma_f32_16x16x32_bf16 v[66:69], v[162:165], v[194:197], v[66:69]
	v_mfma_f32_16x16x32_bf16 v[118:121], v[158:161], v[174:177], v[118:121]
	v_mfma_f32_16x16x32_bf16 v[114:117], v[166:169], v[174:177], v[114:117]
	v_mfma_f32_16x16x32_bf16 v[102:105], v[158:161], v[182:185], v[102:105]
	v_mfma_f32_16x16x32_bf16 v[98:101], v[166:169], v[182:185], v[98:101]
	v_mfma_f32_16x16x32_bf16 v[86:89], v[158:161], v[190:193], v[86:89]
	v_mfma_f32_16x16x32_bf16 v[82:85], v[166:169], v[190:193], v[82:85]
	v_mfma_f32_16x16x32_bf16 v[70:73], v[158:161], v[198:201], v[70:73]
	v_mfma_f32_16x16x32_bf16 v[66:69], v[166:169], v[198:201], v[66:69]
	s_setprio 0
	s_barrier
	ds_read_b128 v[170:173], v128 offset:49152
	ds_read_b128 v[174:177], v128 offset:50176
	ds_read_b128 v[178:181], v128 offset:51200
	ds_read_b128 v[182:185], v128 offset:52224
	ds_read_b128 v[186:189], v128 offset:53248
	ds_read_b128 v[190:193], v128 offset:54272
	ds_read_b128 v[194:197], v128 offset:55296
	ds_read_b128 v[198:201], v128 offset:56320
	s_add_i32 s47, s47, s16
	s_add_u32 s100, s10, s38
	s_addc_u32 s101, s11, s39
	s_mov_b32 m0, s47
	s_nop 0
	global_load_lds_dwordx4 v125, s[100:101]
	s_add_i32 m0, s47, 0x2000
	s_nop 0
	s_add_u32 s10, s10, 0x40080
	s_addc_u32 s11, s11, 0
	s_add_i32 s47, s50, s16
	global_load_lds_dwordx4 v126, s[100:101]
	s_mov_b32 m0, s47
	s_nop 0
	global_load_lds_dwordx4 v125, s[10:11]
	s_add_i32 m0, s47, 0x2000
	s_nop 0
	global_load_lds_dwordx4 v126, s[10:11]
	s_mov_b32 m0, s41
	s_add_u32 s100, s6, s38
	s_addc_u32 s101, s7, s39
	v_mov_b32_e32 v0, v123
	global_load_lds_dwordx4 v122, s[100:101]
	s_mov_b32 m0, s42
	s_nop 0
	global_load_lds_dwordx4 v123, s[100:101]
	s_waitcnt vmcnt(8)
	s_waitcnt lgkmcnt(0)
	s_barrier
	s_setprio 1
	s_waitcnt lgkmcnt(0)
	v_mfma_f32_16x16x32_bf16 v[62:65], v[130:133], v[170:173], v[62:65]
	v_mfma_f32_16x16x32_bf16 v[58:61], v[138:141], v[170:173], v[58:61]
	v_mfma_f32_16x16x32_bf16 v[46:49], v[130:133], v[178:181], v[46:49]
	v_mfma_f32_16x16x32_bf16 v[42:45], v[138:141], v[178:181], v[42:45]
	v_mfma_f32_16x16x32_bf16 v[30:33], v[130:133], v[186:189], v[30:33]
	v_mfma_f32_16x16x32_bf16 v[26:29], v[138:141], v[186:189], v[26:29]
	v_mfma_f32_16x16x32_bf16 v[14:17], v[130:133], v[194:197], v[14:17]
	v_mfma_f32_16x16x32_bf16 v[10:13], v[138:141], v[194:197], v[10:13]
	v_mfma_f32_16x16x32_bf16 v[62:65], v[134:137], v[174:177], v[62:65]
	v_mfma_f32_16x16x32_bf16 v[58:61], v[142:145], v[174:177], v[58:61]
	v_mfma_f32_16x16x32_bf16 v[46:49], v[134:137], v[182:185], v[46:49]
	v_mfma_f32_16x16x32_bf16 v[42:45], v[142:145], v[182:185], v[42:45]
	v_mfma_f32_16x16x32_bf16 v[30:33], v[134:137], v[190:193], v[30:33]
	v_mfma_f32_16x16x32_bf16 v[26:29], v[142:145], v[190:193], v[26:29]
	v_mfma_f32_16x16x32_bf16 v[14:17], v[134:137], v[198:201], v[14:17]
	v_mfma_f32_16x16x32_bf16 v[10:13], v[142:145], v[198:201], v[10:13]
	s_setprio 0
	s_setprio 1
	v_mfma_f32_16x16x32_bf16 v[54:57], v[146:149], v[170:173], v[54:57]
	v_mfma_f32_16x16x32_bf16 v[50:53], v[162:165], v[170:173], v[50:53]
	v_mfma_f32_16x16x32_bf16 v[38:41], v[146:149], v[178:181], v[38:41]
	v_mfma_f32_16x16x32_bf16 v[34:37], v[162:165], v[178:181], v[34:37]
	v_mfma_f32_16x16x32_bf16 v[22:25], v[146:149], v[186:189], v[22:25]
	v_mfma_f32_16x16x32_bf16 v[18:21], v[162:165], v[186:189], v[18:21]
	v_mfma_f32_16x16x32_bf16 v[6:9], v[146:149], v[194:197], v[6:9]
	v_mfma_f32_16x16x32_bf16 v[2:5], v[162:165], v[194:197], v[2:5]
	v_mfma_f32_16x16x32_bf16 v[54:57], v[158:161], v[174:177], v[54:57]
	v_mfma_f32_16x16x32_bf16 v[50:53], v[166:169], v[174:177], v[50:53]
	v_mfma_f32_16x16x32_bf16 v[38:41], v[158:161], v[182:185], v[38:41]
	v_mfma_f32_16x16x32_bf16 v[34:37], v[166:169], v[182:185], v[34:37]
	v_mfma_f32_16x16x32_bf16 v[22:25], v[158:161], v[190:193], v[22:25]
	v_mfma_f32_16x16x32_bf16 v[18:21], v[166:169], v[190:193], v[18:21]
	v_mfma_f32_16x16x32_bf16 v[6:9], v[158:161], v[198:201], v[6:9]
	v_mfma_f32_16x16x32_bf16 v[2:5], v[166:169], v[198:201], v[2:5]
	s_setprio 0
	s_barrier
	s_add_i32 s46, s46, 2
	s_add_u32 s4, s4, 0x100
	s_addc_u32 s5, s5, 0
	s_add_u32 s37, s37, 0x100
	s_addc_u32 s43, s43, 0
	s_cmp_gt_u32 s46, 13
	s_cbranch_scc0 .LBB0_1886
	s_cmpk_lt_u32 s14, 0x100
	s_cbranch_scc0 .LBB0_1889
	s_barrier
